# v35 + P0 8-bit weight transposes rewritten WG-cooperative (1KB row reads, full-line stores)
# speedup vs baseline: 1.0031x; 1.0031x over previous
; #define LAS __attribute__((address_space(3)))
;     if (ldw == 0) ldw = N;
;     LAS float* scr = (LAS float*)(F.lds + F.wave * 16384); const int lane = F.lane;
;     const int nblk = N / 32, nitems = (K / 64) * nblk;
;     for (int item = F.gw; item < nitems; item += F.NGW) { const int kb = item / nblk, nb = item % nblk, k0 = 64 * kb, n0 = 32 * nb;
;         int dr0 = n0; if (MAP == 1) { if (n0 < DFF) dr0 = (n0 >> 7) * 256 + (n0 & 127); else { const int uo = n0 - DFF; dr0 = (uo >> 7) * 256 + 128 + (uo & 127); } }
; #pragma unroll 8
;         for (int i = 0; i < 32; ++i) { const int kk = 2 * i + (lane >> 5); scr[kk * 33 + (lane & 31)] = W[(size_t)(k0 + kk) * ldw + n0 + (lane & 31)]; }
; __device__ __forceinline__ void p0_prologue(Frame& F) {
;     ...
;     transpose_f8_matrix<1, true>(F, F.in[I_F1IN], D, NFF, F.ws + WS_WFI, I8_W);
.LBB0_11:
	s_or_b64 exec, exec, s[0:1]
	s_lshr_b32 s0, s86, 6
	s_lshl_b32 s79, s2, 3
	s_add_i32 s94, s0, s79
	s_lshl_b32 s92, s96, 3
	s_cmp_lt_i32 s94, 0xac00
	v_and_b32_e32 v178, 63, v0
	v_writelane_b32 v240, s0, 2
	s_cselect_b64 s[0:1], -1, 0
	v_writelane_b32 v240, s0, 3
	s_cmp_gt_i32 s94, 0xabff
	v_lshrrev_b32_e32 v162, 5, v178
	v_and_b32_e32 v164, 31, v0
	v_lshrrev_b32_e32 v163, 2, v178
	v_lshlrev_b32_e32 v167, 4, v0
	v_and_b32_e32 v165, 60, v178
	v_writelane_b32 v240, s1, 4
	s_cbranch_scc1 .LBB0_20
	s_barrier
	s_load_dwordx2 s[50:51], s[74:75], 0x38
	v_readlane_b32 s16, v240, 2
	v_lshlrev_b32_e32 v204, 4, v178
	v_mov_b32_e32 v208, 0x42fe0000
	s_mov_b32 s36, 0x44fe0000
	s_mov_b32 s37, 0
	s_mov_b32 s38, 0x4b400000
	s_mov_b32 s39, 0
	s_mov_b32 s40, 0xc2fe0000
	s_mov_b32 s41, 0x0c0c0400
	s_mov_b32 s42, 0x05040100
	s_lshl_b32 s17, s16, 5
	s_and_b32 s18, s16, 4
	s_lshl_b32 s18, s18, 5
	s_add_i32 s17, s17, s18
	v_mul_u32_u24_e32 v205, 0x240, v178
	s_lshl_b32 s18, s16, 4
	v_add_u32_e32 v205, s18, v205
	v_lshrrev_b32_e32 v196, 3, v178
	v_and_b32_e32 v197, 7, v178
	s_lshl_b32 s18, s16, 5
	v_add_u32_e32 v198, s18, v196
	v_mul_u32_u24_e32 v206, 0x90, v198
	v_lshl_add_u32 v206, v197, 4, v206
	v_mul_u32_u24_e32 v207, 0x1000, v196
	v_lshl_add_u32 v207, v197, 4, v207
	s_lshl_b32 s16, s16, 4
	s_waitcnt lgkmcnt(0)
	s_add_u32 s56, s90, 0x8300000
	s_addc_u32 s57, s91, 0
	s_mov_b32 s19, s2
	s_cmp_lt_u32 s19, 0xac0
	s_cbranch_scc0 .Lf8t_f1in0_end
	s_mul_hi_u32 s20, s19, 0x2fa0be9
	s_mul_i32 s21, s20, 86
	s_sub_i32 s21, s19, s21
	s_lshl_b32 s60, s20, 7
	s_lshl_b32 s61, s21, 8
	s_add_i32 s24, s60, s16
	s_mul_i32 s24, s24, 0x15800
	s_lshl_b32 s25, s61, 2
	s_add_u32 s24, s24, s25
	s_add_u32 s52, s50, s24
	s_addc_u32 s53, s51, 0
	global_load_dwordx4 v[80:83], v204, s[52:53]
	s_add_u32 s52, s52, 0x15800
	s_addc_u32 s53, s53, 0
	global_load_dwordx4 v[84:87], v204, s[52:53]
	s_add_u32 s52, s52, 0x15800
	s_addc_u32 s53, s53, 0
	global_load_dwordx4 v[88:91], v204, s[52:53]
	s_add_u32 s52, s52, 0x15800
	s_addc_u32 s53, s53, 0
	global_load_dwordx4 v[92:95], v204, s[52:53]
	s_add_u32 s52, s52, 0x15800
	s_addc_u32 s53, s53, 0
	global_load_dwordx4 v[96:99], v204, s[52:53]
	s_add_u32 s52, s52, 0x15800
	s_addc_u32 s53, s53, 0
	global_load_dwordx4 v[100:103], v204, s[52:53]
	s_add_u32 s52, s52, 0x15800
	s_addc_u32 s53, s53, 0
	global_load_dwordx4 v[104:107], v204, s[52:53]
	s_add_u32 s52, s52, 0x15800
	s_addc_u32 s53, s53, 0
	global_load_dwordx4 v[108:111], v204, s[52:53]
	s_add_u32 s52, s52, 0x15800
	s_addc_u32 s53, s53, 0
	global_load_dwordx4 v[112:115], v204, s[52:53]
	s_add_u32 s52, s52, 0x15800
	s_addc_u32 s53, s53, 0
	global_load_dwordx4 v[116:119], v204, s[52:53]
	s_add_u32 s52, s52, 0x15800
	s_addc_u32 s53, s53, 0
	global_load_dwordx4 v[120:123], v204, s[52:53]
	s_add_u32 s52, s52, 0x15800
	s_addc_u32 s53, s53, 0
	global_load_dwordx4 v[124:127], v204, s[52:53]
	s_add_u32 s52, s52, 0x15800
	s_addc_u32 s53, s53, 0
	global_load_dwordx4 v[128:131], v204, s[52:53]
	s_add_u32 s52, s52, 0x15800
	s_addc_u32 s53, s53, 0
	global_load_dwordx4 v[132:135], v204, s[52:53]
	s_add_u32 s52, s52, 0x15800
	s_addc_u32 s53, s53, 0
	global_load_dwordx4 v[136:139], v204, s[52:53]
	s_add_u32 s52, s52, 0x15800
	s_addc_u32 s53, s53, 0
	global_load_dwordx4 v[140:143], v204, s[52:53]
	s_mov_b32 s58, 1
.Lf8t_f1in0_loop:
	s_add_i32 s64, s19, s96
	s_cmp_lt_u32 s64, 0xac0
	s_cbranch_scc0 .Lf8t_f1in0_a_nonext
	s_mul_hi_u32 s20, s64, 0x2fa0be9
	s_mul_i32 s21, s20, 86
	s_sub_i32 s21, s64, s21
	s_lshl_b32 s62, s20, 7
	s_lshl_b32 s63, s21, 8
	s_add_i32 s24, s62, s16
	s_mul_i32 s24, s24, 0x15800
	s_lshl_b32 s25, s63, 2
	s_add_u32 s24, s24, s25
	s_add_u32 s52, s50, s24
	s_addc_u32 s53, s51, 0
	global_load_dwordx4 v[16:19], v204, s[52:53]
	s_add_u32 s52, s52, 0x15800
	s_addc_u32 s53, s53, 0
	global_load_dwordx4 v[20:23], v204, s[52:53]
	s_add_u32 s52, s52, 0x15800
	s_addc_u32 s53, s53, 0
	global_load_dwordx4 v[24:27], v204, s[52:53]
	s_add_u32 s52, s52, 0x15800
	s_addc_u32 s53, s53, 0
	global_load_dwordx4 v[28:31], v204, s[52:53]
	s_add_u32 s52, s52, 0x15800
	s_addc_u32 s53, s53, 0
	global_load_dwordx4 v[32:35], v204, s[52:53]
	s_add_u32 s52, s52, 0x15800
	s_addc_u32 s53, s53, 0
	global_load_dwordx4 v[36:39], v204, s[52:53]
	s_add_u32 s52, s52, 0x15800
	s_addc_u32 s53, s53, 0
	global_load_dwordx4 v[40:43], v204, s[52:53]
	s_add_u32 s52, s52, 0x15800
	s_addc_u32 s53, s53, 0
	global_load_dwordx4 v[44:47], v204, s[52:53]
	s_add_u32 s52, s52, 0x15800
	s_addc_u32 s53, s53, 0
	global_load_dwordx4 v[48:51], v204, s[52:53]
	s_add_u32 s52, s52, 0x15800
	s_addc_u32 s53, s53, 0
	global_load_dwordx4 v[52:55], v204, s[52:53]
	s_add_u32 s52, s52, 0x15800
	s_addc_u32 s53, s53, 0
	global_load_dwordx4 v[56:59], v204, s[52:53]
	s_add_u32 s52, s52, 0x15800
	s_addc_u32 s53, s53, 0
	global_load_dwordx4 v[60:63], v204, s[52:53]
	s_add_u32 s52, s52, 0x15800
	s_addc_u32 s53, s53, 0
	global_load_dwordx4 v[64:67], v204, s[52:53]
	s_add_u32 s52, s52, 0x15800
	s_addc_u32 s53, s53, 0
	global_load_dwordx4 v[68:71], v204, s[52:53]
	s_add_u32 s52, s52, 0x15800
	s_addc_u32 s53, s53, 0
	global_load_dwordx4 v[144:147], v204, s[52:53]
	s_add_u32 s52, s52, 0x15800
	s_addc_u32 s53, s53, 0
	global_load_dwordx4 v[148:151], v204, s[52:53]
	s_cmp_eq_u32 s58, 1
	s_cbranch_scc1 .Lf8t_f1in0_a_first
	s_waitcnt vmcnt(20)
	s_branch .Lf8t_f1in0_a_go
.Lf8t_f1in0_a_first:
	s_waitcnt vmcnt(16)
	s_branch .Lf8t_f1in0_a_go

; #define LAS __attribute__((address_space(3)))
; __device__ __forceinline__ unsigned pk4_i8(float a, float b, float c, float d, float s) {
;     const unsigned ua = __float_as_uint(__builtin_amdgcn_fmed3f(a * s, -127.f, 127.f) + 12582912.f), ub = __float_as_uint(__builtin_amdgcn_fmed3f(b * s, -127.f, 127.f) + 12582912.f);
;     const unsigned uc = __float_as_uint(__builtin_amdgcn_fmed3f(c * s, -127.f, 127.f) + 12582912.f), ud = __float_as_uint(__builtin_amdgcn_fmed3f(d * s, -127.f, 127.f) + 12582912.f);
;     return (ua & 0xffu) | ((ub & 0xffu) << 8) | ((uc & 0xffu) << 16) | (ud << 24);
; }
;     ...
;         const int c = lane & 3;
; #pragma unroll
;         for (int j = 0; j < 2; ++j) { const int n = (lane >> 2) + 16 * j; const LAS float* sp = scr + (16 * c) * 33 + n;
;             u32x4 o;
;             if (QI8) { o.x = pk4_i8(sp[0 * 33], sp[1 * 33], sp[2 * 33], sp[3 * 33], scl); o.y = pk4_i8(sp[4 * 33], sp[5 * 33], sp[6 * 33], sp[7 * 33], scl);
;                 o.z = pk4_i8(sp[8 * 33], sp[9 * 33], sp[10 * 33], sp[11 * 33], scl); o.w = pk4_i8(sp[12 * 33], sp[13 * 33], sp[14 * 33], sp[15 * 33], scl); }
.Lf8t_f1in0_a_go:
	s_mov_b32 s58, 0
	v_pk_mul_f32 v[80:81], v[80:81], s[36:37] op_sel_hi:[1,0]
	v_pk_mul_f32 v[82:83], v[82:83], s[36:37] op_sel_hi:[1,0]
	v_pk_mul_f32 v[84:85], v[84:85], s[36:37] op_sel_hi:[1,0]
	v_pk_mul_f32 v[86:87], v[86:87], s[36:37] op_sel_hi:[1,0]
	v_pk_mul_f32 v[88:89], v[88:89], s[36:37] op_sel_hi:[1,0]
	v_pk_mul_f32 v[90:91], v[90:91], s[36:37] op_sel_hi:[1,0]
	v_pk_mul_f32 v[92:93], v[92:93], s[36:37] op_sel_hi:[1,0]
	v_pk_mul_f32 v[94:95], v[94:95], s[36:37] op_sel_hi:[1,0]
	v_pk_mul_f32 v[96:97], v[96:97], s[36:37] op_sel_hi:[1,0]
	v_pk_mul_f32 v[98:99], v[98:99], s[36:37] op_sel_hi:[1,0]
	v_pk_mul_f32 v[100:101], v[100:101], s[36:37] op_sel_hi:[1,0]
	v_pk_mul_f32 v[102:103], v[102:103], s[36:37] op_sel_hi:[1,0]
	v_pk_mul_f32 v[104:105], v[104:105], s[36:37] op_sel_hi:[1,0]
	v_pk_mul_f32 v[106:107], v[106:107], s[36:37] op_sel_hi:[1,0]
	v_pk_mul_f32 v[108:109], v[108:109], s[36:37] op_sel_hi:[1,0]
	v_pk_mul_f32 v[110:111], v[110:111], s[36:37] op_sel_hi:[1,0]
	v_pk_mul_f32 v[112:113], v[112:113], s[36:37] op_sel_hi:[1,0]
	v_pk_mul_f32 v[114:115], v[114:115], s[36:37] op_sel_hi:[1,0]
	v_pk_mul_f32 v[116:117], v[116:117], s[36:37] op_sel_hi:[1,0]
	v_pk_mul_f32 v[118:119], v[118:119], s[36:37] op_sel_hi:[1,0]
	v_pk_mul_f32 v[120:121], v[120:121], s[36:37] op_sel_hi:[1,0]
	v_pk_mul_f32 v[122:123], v[122:123], s[36:37] op_sel_hi:[1,0]
	v_pk_mul_f32 v[124:125], v[124:125], s[36:37] op_sel_hi:[1,0]
	v_pk_mul_f32 v[126:127], v[126:127], s[36:37] op_sel_hi:[1,0]
	v_pk_mul_f32 v[128:129], v[128:129], s[36:37] op_sel_hi:[1,0]
	v_pk_mul_f32 v[130:131], v[130:131], s[36:37] op_sel_hi:[1,0]
	v_pk_mul_f32 v[132:133], v[132:133], s[36:37] op_sel_hi:[1,0]
	v_pk_mul_f32 v[134:135], v[134:135], s[36:37] op_sel_hi:[1,0]
	v_pk_mul_f32 v[136:137], v[136:137], s[36:37] op_sel_hi:[1,0]
	v_pk_mul_f32 v[138:139], v[138:139], s[36:37] op_sel_hi:[1,0]
	v_pk_mul_f32 v[140:141], v[140:141], s[36:37] op_sel_hi:[1,0]
	v_pk_mul_f32 v[142:143], v[142:143], s[36:37] op_sel_hi:[1,0]
	v_med3_f32 v80, v80, s40, v208
	v_med3_f32 v81, v81, s40, v208
	v_med3_f32 v82, v82, s40, v208
	v_med3_f32 v83, v83, s40, v208
	v_med3_f32 v84, v84, s40, v208
	v_med3_f32 v85, v85, s40, v208
	v_med3_f32 v86, v86, s40, v208
	v_med3_f32 v87, v87, s40, v208
	v_med3_f32 v88, v88, s40, v208
	v_med3_f32 v89, v89, s40, v208
	v_med3_f32 v90, v90, s40, v208
	v_med3_f32 v91, v91, s40, v208
	v_med3_f32 v92, v92, s40, v208
	v_med3_f32 v93, v93, s40, v208
	v_med3_f32 v94, v94, s40, v208
	v_med3_f32 v95, v95, s40, v208
	v_med3_f32 v96, v96, s40, v208
	v_med3_f32 v97, v97, s40, v208
	v_med3_f32 v98, v98, s40, v208
	v_med3_f32 v99, v99, s40, v208
	v_med3_f32 v100, v100, s40, v208
	v_med3_f32 v101, v101, s40, v208
	v_med3_f32 v102, v102, s40, v208
	v_med3_f32 v103, v103, s40, v208
	v_med3_f32 v104, v104, s40, v208
	v_med3_f32 v105, v105, s40, v208
	v_med3_f32 v106, v106, s40, v208
	v_med3_f32 v107, v107, s40, v208
	v_med3_f32 v108, v108, s40, v208
	v_med3_f32 v109, v109, s40, v208
	v_med3_f32 v110, v110, s40, v208
	v_med3_f32 v111, v111, s40, v208
	v_med3_f32 v112, v112, s40, v208
	v_med3_f32 v113, v113, s40, v208
	v_med3_f32 v114, v114, s40, v208
	v_med3_f32 v115, v115, s40, v208
	v_med3_f32 v116, v116, s40, v208
	v_med3_f32 v117, v117, s40, v208
	v_med3_f32 v118, v118, s40, v208
	v_med3_f32 v119, v119, s40, v208
	v_med3_f32 v120, v120, s40, v208
	v_med3_f32 v121, v121, s40, v208
	v_med3_f32 v122, v122, s40, v208
	v_med3_f32 v123, v123, s40, v208
	v_med3_f32 v124, v124, s40, v208
	v_med3_f32 v125, v125, s40, v208
	v_med3_f32 v126, v126, s40, v208
	v_med3_f32 v127, v127, s40, v208
	v_med3_f32 v128, v128, s40, v208
	v_med3_f32 v129, v129, s40, v208
	v_med3_f32 v130, v130, s40, v208
	v_med3_f32 v131, v131, s40, v208
	v_med3_f32 v132, v132, s40, v208
	v_med3_f32 v133, v133, s40, v208
	v_med3_f32 v134, v134, s40, v208
	v_med3_f32 v135, v135, s40, v208
	v_med3_f32 v136, v136, s40, v208
	v_med3_f32 v137, v137, s40, v208
	v_med3_f32 v138, v138, s40, v208
	v_med3_f32 v139, v139, s40, v208
	v_med3_f32 v140, v140, s40, v208
	v_med3_f32 v141, v141, s40, v208
	v_med3_f32 v142, v142, s40, v208
	v_med3_f32 v143, v143, s40, v208
	v_pk_add_f32 v[80:81], v[80:81], s[38:39] op_sel_hi:[1,0]
	v_pk_add_f32 v[82:83], v[82:83], s[38:39] op_sel_hi:[1,0]
	v_pk_add_f32 v[84:85], v[84:85], s[38:39] op_sel_hi:[1,0]
	v_pk_add_f32 v[86:87], v[86:87], s[38:39] op_sel_hi:[1,0]
	v_pk_add_f32 v[88:89], v[88:89], s[38:39] op_sel_hi:[1,0]
	v_pk_add_f32 v[90:91], v[90:91], s[38:39] op_sel_hi:[1,0]
	v_pk_add_f32 v[92:93], v[92:93], s[38:39] op_sel_hi:[1,0]
	v_pk_add_f32 v[94:95], v[94:95], s[38:39] op_sel_hi:[1,0]
	v_pk_add_f32 v[96:97], v[96:97], s[38:39] op_sel_hi:[1,0]
	v_pk_add_f32 v[98:99], v[98:99], s[38:39] op_sel_hi:[1,0]
	v_pk_add_f32 v[100:101], v[100:101], s[38:39] op_sel_hi:[1,0]
	v_pk_add_f32 v[102:103], v[102:103], s[38:39] op_sel_hi:[1,0]
	v_pk_add_f32 v[104:105], v[104:105], s[38:39] op_sel_hi:[1,0]
	v_pk_add_f32 v[106:107], v[106:107], s[38:39] op_sel_hi:[1,0]
	v_pk_add_f32 v[108:109], v[108:109], s[38:39] op_sel_hi:[1,0]
	v_pk_add_f32 v[110:111], v[110:111], s[38:39] op_sel_hi:[1,0]
	v_pk_add_f32 v[112:113], v[112:113], s[38:39] op_sel_hi:[1,0]
	v_pk_add_f32 v[114:115], v[114:115], s[38:39] op_sel_hi:[1,0]
	v_pk_add_f32 v[116:117], v[116:117], s[38:39] op_sel_hi:[1,0]
	v_pk_add_f32 v[118:119], v[118:119], s[38:39] op_sel_hi:[1,0]
	v_pk_add_f32 v[120:121], v[120:121], s[38:39] op_sel_hi:[1,0]
; #define LAS __attribute__((address_space(3)))
; __device__ __forceinline__ unsigned pk4_f8(float a, float b, float c, float d) { int w = __builtin_amdgcn_cvt_pk_fp8_f32(a, b, 0, false); w = __builtin_amdgcn_cvt_pk_fp8_f32(c, d, w, true); return (unsigned)w; }
; #define LDS_WAIT() asm volatile("s_waitcnt lgkmcnt(0)" ::: "memory")
; __device__ __forceinline__ unsigned pk4_i8(float a, float b, float c, float d, float s) {
;     const unsigned ua = __float_as_uint(__builtin_amdgcn_fmed3f(a * s, -127.f, 127.f) + 12582912.f), ub = __float_as_uint(__builtin_amdgcn_fmed3f(b * s, -127.f, 127.f) + 12582912.f);
;     const unsigned uc = __float_as_uint(__builtin_amdgcn_fmed3f(c * s, -127.f, 127.f) + 12582912.f), ud = __float_as_uint(__builtin_amdgcn_fmed3f(d * s, -127.f, 127.f) + 12582912.f);
;     return (ua & 0xffu) | ((ub & 0xffu) << 8) | ((uc & 0xffu) << 16) | (ud << 24);
; }
;     ...
;         const int c = lane & 3;
; #pragma unroll
;         for (int j = 0; j < 2; ++j) { const int n = (lane >> 2) + 16 * j; const LAS float* sp = scr + (16 * c) * 33 + n;
;             u32x4 o;
;             if (QI8) { o.x = pk4_i8(sp[0 * 33], sp[1 * 33], sp[2 * 33], sp[3 * 33], scl); o.y = pk4_i8(sp[4 * 33], sp[5 * 33], sp[6 * 33], sp[7 * 33], scl);
;                 o.z = pk4_i8(sp[8 * 33], sp[9 * 33], sp[10 * 33], sp[11 * 33], scl); o.w = pk4_i8(sp[12 * 33], sp[13 * 33], sp[14 * 33], sp[15 * 33], scl); }
;             else {
;             o.x = pk4_f8(sp[0 * 33] * scl, sp[1 * 33] * scl, sp[2 * 33] * scl, sp[3 * 33] * scl); o.y = pk4_f8(sp[4 * 33] * scl, sp[5 * 33] * scl, sp[6 * 33] * scl, sp[7 * 33] * scl);
;             o.z = pk4_f8(sp[8 * 33] * scl, sp[9 * 33] * scl, sp[10 * 33] * scl, sp[11 * 33] * scl); o.w = pk4_f8(sp[12 * 33] * scl, sp[13 * 33] * scl, sp[14 * 33] * scl, sp[15 * 33] * scl); }
;             *(u32x4*)(WT + (size_t)(dr0 + n) * K + k0 + 16 * c) = o; }
;         LDS_WAIT(); asm volatile("" ::: "memory"); }
	v_pk_add_f32 v[122:123], v[122:123], s[38:39] op_sel_hi:[1,0]
	v_pk_add_f32 v[124:125], v[124:125], s[38:39] op_sel_hi:[1,0]
	v_pk_add_f32 v[126:127], v[126:127], s[38:39] op_sel_hi:[1,0]
	v_pk_add_f32 v[128:129], v[128:129], s[38:39] op_sel_hi:[1,0]
	v_pk_add_f32 v[130:131], v[130:131], s[38:39] op_sel_hi:[1,0]
	v_pk_add_f32 v[132:133], v[132:133], s[38:39] op_sel_hi:[1,0]
	v_pk_add_f32 v[134:135], v[134:135], s[38:39] op_sel_hi:[1,0]
	v_pk_add_f32 v[136:137], v[136:137], s[38:39] op_sel_hi:[1,0]
	v_pk_add_f32 v[138:139], v[138:139], s[38:39] op_sel_hi:[1,0]
	v_pk_add_f32 v[140:141], v[140:141], s[38:39] op_sel_hi:[1,0]
	v_pk_add_f32 v[142:143], v[142:143], s[38:39] op_sel_hi:[1,0]
	v_perm_b32 v196, v84, v80, s41
	v_perm_b32 v197, v92, v88, s41
	v_perm_b32 v180, v197, v196, s42
	v_perm_b32 v196, v100, v96, s41
	v_perm_b32 v197, v108, v104, s41
	v_perm_b32 v181, v197, v196, s42
	v_perm_b32 v196, v116, v112, s41
	v_perm_b32 v197, v124, v120, s41
	v_perm_b32 v182, v197, v196, s42
	v_perm_b32 v196, v132, v128, s41
	v_perm_b32 v197, v140, v136, s41
	v_perm_b32 v183, v197, v196, s42
	v_perm_b32 v196, v85, v81, s41
	v_perm_b32 v197, v93, v89, s41
	v_perm_b32 v184, v197, v196, s42
	v_perm_b32 v196, v101, v97, s41
	v_perm_b32 v197, v109, v105, s41
	v_perm_b32 v185, v197, v196, s42
	v_perm_b32 v196, v117, v113, s41
	v_perm_b32 v197, v125, v121, s41
	v_perm_b32 v186, v197, v196, s42
	v_perm_b32 v196, v133, v129, s41
	v_perm_b32 v197, v141, v137, s41
	v_perm_b32 v187, v197, v196, s42
	v_perm_b32 v196, v86, v82, s41
	v_perm_b32 v197, v94, v90, s41
	v_perm_b32 v188, v197, v196, s42
	v_perm_b32 v196, v102, v98, s41
	v_perm_b32 v197, v110, v106, s41
	v_perm_b32 v189, v197, v196, s42
	v_perm_b32 v196, v118, v114, s41
	v_perm_b32 v197, v126, v122, s41
	v_perm_b32 v190, v197, v196, s42
	v_perm_b32 v196, v134, v130, s41
	v_perm_b32 v197, v142, v138, s41
	v_perm_b32 v191, v197, v196, s42
	v_perm_b32 v196, v87, v83, s41
	v_perm_b32 v197, v95, v91, s41
	v_perm_b32 v192, v197, v196, s42
	v_perm_b32 v196, v103, v99, s41
	v_perm_b32 v197, v111, v107, s41
	v_perm_b32 v193, v197, v196, s42
	v_perm_b32 v196, v119, v115, s41
	v_perm_b32 v197, v127, v123, s41
	v_perm_b32 v194, v197, v196, s42
	v_perm_b32 v196, v135, v131, s41
	v_perm_b32 v197, v143, v139, s41
	v_perm_b32 v195, v197, v196, s42
	ds_write_b128 v205, v[180:183] offset:0
	ds_write_b128 v205, v[184:187] offset:144
	ds_write_b128 v205, v[188:191] offset:288
	ds_write_b128 v205, v[192:195] offset:432
	s_lshl_b32 s26, s61, 1
	s_add_i32 s27, s26, 0xffffaa80
	s_cmp_lt_u32 s61, 0x2b00
	s_cselect_b32 s26, s26, s27
	s_add_i32 s26, s26, s17
	s_mul_i32 s26, s26, 0x1000
	s_add_u32 s26, s26, s60
	s_add_u32 s54, s56, s26
	s_addc_u32 s55, s57, 0
	s_waitcnt lgkmcnt(0)
	s_barrier
	ds_read_b128 v[180:183], v206 offset:0
	ds_read_b128 v[184:187], v206 offset:1152
	ds_read_b128 v[188:191], v206 offset:2304
	ds_read_b128 v[192:195], v206 offset:3456
	s_waitcnt lgkmcnt(3)
	global_store_dwordx4 v207, v[180:183], s[54:55]
	s_add_u32 s54, s54, 0x8000
	s_addc_u32 s55, s55, 0
	s_waitcnt lgkmcnt(2)
	global_store_dwordx4 v207, v[184:187], s[54:55]
	s_add_u32 s54, s54, 0x8000
	s_addc_u32 s55, s55, 0
	s_waitcnt lgkmcnt(1)
	global_store_dwordx4 v207, v[188:191], s[54:55]
	s_add_u32 s54, s54, 0x8000
	s_addc_u32 s55, s55, 0
	s_waitcnt lgkmcnt(0)
	global_store_dwordx4 v207, v[192:195], s[54:55]
	s_mov_b32 s19, s64
	s_cmp_lt_u32 s19, 0xac0
	s_cbranch_scc0 .Lf8t_f1in0_end
	s_add_i32 s64, s19, s96
	s_cmp_lt_u32 s64, 0xac0
	s_cbranch_scc0 .Lf8t_f1in0_b_nonext
	s_mul_hi_u32 s20, s64, 0x2fa0be9
	s_mul_i32 s21, s20, 86
	s_sub_i32 s21, s64, s21
	s_lshl_b32 s60, s20, 7
	s_lshl_b32 s61, s21, 8
	s_add_i32 s24, s60, s16
	s_mul_i32 s24, s24, 0x15800
	s_lshl_b32 s25, s61, 2
	s_add_u32 s24, s24, s25
	s_add_u32 s52, s50, s24
	s_addc_u32 s53, s51, 0
	global_load_dwordx4 v[80:83], v204, s[52:53]
	s_add_u32 s52, s52, 0x15800
	s_addc_u32 s53, s53, 0
	global_load_dwordx4 v[84:87], v204, s[52:53]
	s_add_u32 s52, s52, 0x15800
	s_addc_u32 s53, s53, 0
	global_load_dwordx4 v[88:91], v204, s[52:53]
	s_add_u32 s52, s52, 0x15800
	s_addc_u32 s53, s53, 0
	global_load_dwordx4 v[92:95], v204, s[52:53]
	s_add_u32 s52, s52, 0x15800
	s_addc_u32 s53, s53, 0
	global_load_dwordx4 v[96:99], v204, s[52:53]
	s_add_u32 s52, s52, 0x15800
	s_addc_u32 s53, s53, 0
	global_load_dwordx4 v[100:103], v204, s[52:53]
	s_add_u32 s52, s52, 0x15800
	s_addc_u32 s53, s53, 0
	global_load_dwordx4 v[104:107], v204, s[52:53]
	s_add_u32 s52, s52, 0x15800
	s_addc_u32 s53, s53, 0
	global_load_dwordx4 v[108:111], v204, s[52:53]
	s_add_u32 s52, s52, 0x15800
	s_addc_u32 s53, s53, 0
	global_load_dwordx4 v[112:115], v204, s[52:53]
	s_add_u32 s52, s52, 0x15800
	s_addc_u32 s53, s53, 0
	global_load_dwordx4 v[116:119], v204, s[52:53]
	s_add_u32 s52, s52, 0x15800
	s_addc_u32 s53, s53, 0
	global_load_dwordx4 v[120:123], v204, s[52:53]
	s_add_u32 s52, s52, 0x15800
	s_addc_u32 s53, s53, 0
	global_load_dwordx4 v[124:127], v204, s[52:53]
	s_add_u32 s52, s52, 0x15800
	s_addc_u32 s53, s53, 0
	global_load_dwordx4 v[128:131], v204, s[52:53]
	s_add_u32 s52, s52, 0x15800
	s_addc_u32 s53, s53, 0
	global_load_dwordx4 v[132:135], v204, s[52:53]
	s_add_u32 s52, s52, 0x15800
	s_addc_u32 s53, s53, 0
	global_load_dwordx4 v[136:139], v204, s[52:53]
	s_add_u32 s52, s52, 0x15800
	s_addc_u32 s53, s53, 0
	global_load_dwordx4 v[140:143], v204, s[52:53]
	s_waitcnt vmcnt(20)
	s_branch .Lf8t_f1in0_b_go

; __device__ __forceinline__ unsigned pk4_i8(float a, float b, float c, float d, float s) {
;     const unsigned ua = __float_as_uint(__builtin_amdgcn_fmed3f(a * s, -127.f, 127.f) + 12582912.f), ub = __float_as_uint(__builtin_amdgcn_fmed3f(b * s, -127.f, 127.f) + 12582912.f);
;     const unsigned uc = __float_as_uint(__builtin_amdgcn_fmed3f(c * s, -127.f, 127.f) + 12582912.f), ud = __float_as_uint(__builtin_amdgcn_fmed3f(d * s, -127.f, 127.f) + 12582912.f);
;     return (ua & 0xffu) | ((ub & 0xffu) << 8) | ((uc & 0xffu) << 16) | (ud << 24);
;     ...
;             if (QI8) { o.x = pk4_i8(sp[0 * 33], sp[1 * 33], sp[2 * 33], sp[3 * 33], scl); o.y = pk4_i8(sp[4 * 33], sp[5 * 33], sp[6 * 33], sp[7 * 33], scl);
;                 o.z = pk4_i8(sp[8 * 33], sp[9 * 33], sp[10 * 33], sp[11 * 33], scl); o.w = pk4_i8(sp[12 * 33], sp[13 * 33], sp[14 * 33], sp[15 * 33], scl); }
.Lf8t_f1in0_b_go:
	v_pk_mul_f32 v[16:17], v[16:17], s[36:37] op_sel_hi:[1,0]
	v_pk_mul_f32 v[18:19], v[18:19], s[36:37] op_sel_hi:[1,0]
	v_pk_mul_f32 v[20:21], v[20:21], s[36:37] op_sel_hi:[1,0]
	v_pk_mul_f32 v[22:23], v[22:23], s[36:37] op_sel_hi:[1,0]
	v_pk_mul_f32 v[24:25], v[24:25], s[36:37] op_sel_hi:[1,0]
	v_pk_mul_f32 v[26:27], v[26:27], s[36:37] op_sel_hi:[1,0]
	v_pk_mul_f32 v[28:29], v[28:29], s[36:37] op_sel_hi:[1,0]
	v_pk_mul_f32 v[30:31], v[30:31], s[36:37] op_sel_hi:[1,0]
	v_pk_mul_f32 v[32:33], v[32:33], s[36:37] op_sel_hi:[1,0]
	v_pk_mul_f32 v[34:35], v[34:35], s[36:37] op_sel_hi:[1,0]
	v_pk_mul_f32 v[36:37], v[36:37], s[36:37] op_sel_hi:[1,0]
	v_pk_mul_f32 v[38:39], v[38:39], s[36:37] op_sel_hi:[1,0]
	v_pk_mul_f32 v[40:41], v[40:41], s[36:37] op_sel_hi:[1,0]
	v_pk_mul_f32 v[42:43], v[42:43], s[36:37] op_sel_hi:[1,0]
	v_pk_mul_f32 v[44:45], v[44:45], s[36:37] op_sel_hi:[1,0]
	v_pk_mul_f32 v[46:47], v[46:47], s[36:37] op_sel_hi:[1,0]
	v_pk_mul_f32 v[48:49], v[48:49], s[36:37] op_sel_hi:[1,0]
	v_pk_mul_f32 v[50:51], v[50:51], s[36:37] op_sel_hi:[1,0]
	v_pk_mul_f32 v[52:53], v[52:53], s[36:37] op_sel_hi:[1,0]
	v_pk_mul_f32 v[54:55], v[54:55], s[36:37] op_sel_hi:[1,0]
	v_pk_mul_f32 v[56:57], v[56:57], s[36:37] op_sel_hi:[1,0]
	v_pk_mul_f32 v[58:59], v[58:59], s[36:37] op_sel_hi:[1,0]
	v_pk_mul_f32 v[60:61], v[60:61], s[36:37] op_sel_hi:[1,0]
	v_pk_mul_f32 v[62:63], v[62:63], s[36:37] op_sel_hi:[1,0]
	v_pk_mul_f32 v[64:65], v[64:65], s[36:37] op_sel_hi:[1,0]
	v_pk_mul_f32 v[66:67], v[66:67], s[36:37] op_sel_hi:[1,0]
	v_pk_mul_f32 v[68:69], v[68:69], s[36:37] op_sel_hi:[1,0]
	v_pk_mul_f32 v[70:71], v[70:71], s[36:37] op_sel_hi:[1,0]
	v_pk_mul_f32 v[144:145], v[144:145], s[36:37] op_sel_hi:[1,0]
	v_pk_mul_f32 v[146:147], v[146:147], s[36:37] op_sel_hi:[1,0]
	v_pk_mul_f32 v[148:149], v[148:149], s[36:37] op_sel_hi:[1,0]
	v_pk_mul_f32 v[150:151], v[150:151], s[36:37] op_sel_hi:[1,0]
	v_med3_f32 v16, v16, s40, v208
	v_med3_f32 v17, v17, s40, v208
	v_med3_f32 v18, v18, s40, v208
	v_med3_f32 v19, v19, s40, v208
	v_med3_f32 v20, v20, s40, v208
	v_med3_f32 v21, v21, s40, v208
	v_med3_f32 v22, v22, s40, v208
	v_med3_f32 v23, v23, s40, v208
	v_med3_f32 v24, v24, s40, v208
	v_med3_f32 v25, v25, s40, v208
	v_med3_f32 v26, v26, s40, v208
	v_med3_f32 v27, v27, s40, v208
	v_med3_f32 v28, v28, s40, v208
	v_med3_f32 v29, v29, s40, v208
	v_med3_f32 v30, v30, s40, v208
	v_med3_f32 v31, v31, s40, v208
	v_med3_f32 v32, v32, s40, v208
	v_med3_f32 v33, v33, s40, v208
	v_med3_f32 v34, v34, s40, v208
	v_med3_f32 v35, v35, s40, v208
	v_med3_f32 v36, v36, s40, v208
	v_med3_f32 v37, v37, s40, v208
	v_med3_f32 v38, v38, s40, v208
	v_med3_f32 v39, v39, s40, v208
	v_med3_f32 v40, v40, s40, v208
	v_med3_f32 v41, v41, s40, v208
	v_med3_f32 v42, v42, s40, v208
	v_med3_f32 v43, v43, s40, v208
	v_med3_f32 v44, v44, s40, v208
	v_med3_f32 v45, v45, s40, v208
	v_med3_f32 v46, v46, s40, v208
	v_med3_f32 v47, v47, s40, v208
	v_med3_f32 v48, v48, s40, v208
	v_med3_f32 v49, v49, s40, v208
	v_med3_f32 v50, v50, s40, v208
	v_med3_f32 v51, v51, s40, v208
	v_med3_f32 v52, v52, s40, v208
	v_med3_f32 v53, v53, s40, v208
	v_med3_f32 v54, v54, s40, v208
	v_med3_f32 v55, v55, s40, v208
	v_med3_f32 v56, v56, s40, v208
	v_med3_f32 v57, v57, s40, v208
	v_med3_f32 v58, v58, s40, v208
	v_med3_f32 v59, v59, s40, v208
	v_med3_f32 v60, v60, s40, v208
	v_med3_f32 v61, v61, s40, v208
	v_med3_f32 v62, v62, s40, v208
	v_med3_f32 v63, v63, s40, v208
	v_med3_f32 v64, v64, s40, v208
	v_med3_f32 v65, v65, s40, v208
	v_med3_f32 v66, v66, s40, v208
	v_med3_f32 v67, v67, s40, v208
	v_med3_f32 v68, v68, s40, v208
	v_med3_f32 v69, v69, s40, v208
	v_med3_f32 v70, v70, s40, v208
	v_med3_f32 v71, v71, s40, v208
	v_med3_f32 v144, v144, s40, v208
	v_med3_f32 v145, v145, s40, v208
	v_med3_f32 v146, v146, s40, v208
	v_med3_f32 v147, v147, s40, v208
	v_med3_f32 v148, v148, s40, v208
	v_med3_f32 v149, v149, s40, v208
	v_med3_f32 v150, v150, s40, v208
	v_med3_f32 v151, v151, s40, v208
	v_pk_add_f32 v[16:17], v[16:17], s[38:39] op_sel_hi:[1,0]
	v_pk_add_f32 v[18:19], v[18:19], s[38:39] op_sel_hi:[1,0]
	v_pk_add_f32 v[20:21], v[20:21], s[38:39] op_sel_hi:[1,0]
	v_pk_add_f32 v[22:23], v[22:23], s[38:39] op_sel_hi:[1,0]
	v_pk_add_f32 v[24:25], v[24:25], s[38:39] op_sel_hi:[1,0]
	v_pk_add_f32 v[26:27], v[26:27], s[38:39] op_sel_hi:[1,0]
; #define LAS __attribute__((address_space(3)))
; __device__ __forceinline__ unsigned pk4_f8(float a, float b, float c, float d) { int w = __builtin_amdgcn_cvt_pk_fp8_f32(a, b, 0, false); w = __builtin_amdgcn_cvt_pk_fp8_f32(c, d, w, true); return (unsigned)w; }
; #define LDS_WAIT() asm volatile("s_waitcnt lgkmcnt(0)" ::: "memory")
;     ...
;         const int c = lane & 3;
; #pragma unroll
;         for (int j = 0; j < 2; ++j) { const int n = (lane >> 2) + 16 * j; const LAS float* sp = scr + (16 * c) * 33 + n;
;             u32x4 o;
;             if (QI8) { o.x = pk4_i8(sp[0 * 33], sp[1 * 33], sp[2 * 33], sp[3 * 33], scl); o.y = pk4_i8(sp[4 * 33], sp[5 * 33], sp[6 * 33], sp[7 * 33], scl);
;                 o.z = pk4_i8(sp[8 * 33], sp[9 * 33], sp[10 * 33], sp[11 * 33], scl); o.w = pk4_i8(sp[12 * 33], sp[13 * 33], sp[14 * 33], sp[15 * 33], scl); }
;             else {
;             o.x = pk4_f8(sp[0 * 33] * scl, sp[1 * 33] * scl, sp[2 * 33] * scl, sp[3 * 33] * scl); o.y = pk4_f8(sp[4 * 33] * scl, sp[5 * 33] * scl, sp[6 * 33] * scl, sp[7 * 33] * scl);
;             o.z = pk4_f8(sp[8 * 33] * scl, sp[9 * 33] * scl, sp[10 * 33] * scl, sp[11 * 33] * scl); o.w = pk4_f8(sp[12 * 33] * scl, sp[13 * 33] * scl, sp[14 * 33] * scl, sp[15 * 33] * scl); }
;             *(u32x4*)(WT + (size_t)(dr0 + n) * K + k0 + 16 * c) = o; }
;         LDS_WAIT(); asm volatile("" ::: "memory"); }
	v_pk_add_f32 v[28:29], v[28:29], s[38:39] op_sel_hi:[1,0]
	v_pk_add_f32 v[30:31], v[30:31], s[38:39] op_sel_hi:[1,0]
	v_pk_add_f32 v[32:33], v[32:33], s[38:39] op_sel_hi:[1,0]
	v_pk_add_f32 v[34:35], v[34:35], s[38:39] op_sel_hi:[1,0]
	v_pk_add_f32 v[36:37], v[36:37], s[38:39] op_sel_hi:[1,0]
	v_pk_add_f32 v[38:39], v[38:39], s[38:39] op_sel_hi:[1,0]
	v_pk_add_f32 v[40:41], v[40:41], s[38:39] op_sel_hi:[1,0]
	v_pk_add_f32 v[42:43], v[42:43], s[38:39] op_sel_hi:[1,0]
	v_pk_add_f32 v[44:45], v[44:45], s[38:39] op_sel_hi:[1,0]
	v_pk_add_f32 v[46:47], v[46:47], s[38:39] op_sel_hi:[1,0]
	v_pk_add_f32 v[48:49], v[48:49], s[38:39] op_sel_hi:[1,0]
	v_pk_add_f32 v[50:51], v[50:51], s[38:39] op_sel_hi:[1,0]
	v_pk_add_f32 v[52:53], v[52:53], s[38:39] op_sel_hi:[1,0]
	v_pk_add_f32 v[54:55], v[54:55], s[38:39] op_sel_hi:[1,0]
	v_pk_add_f32 v[56:57], v[56:57], s[38:39] op_sel_hi:[1,0]
	v_pk_add_f32 v[58:59], v[58:59], s[38:39] op_sel_hi:[1,0]
	v_pk_add_f32 v[60:61], v[60:61], s[38:39] op_sel_hi:[1,0]
	v_pk_add_f32 v[62:63], v[62:63], s[38:39] op_sel_hi:[1,0]
	v_pk_add_f32 v[64:65], v[64:65], s[38:39] op_sel_hi:[1,0]
	v_pk_add_f32 v[66:67], v[66:67], s[38:39] op_sel_hi:[1,0]
	v_pk_add_f32 v[68:69], v[68:69], s[38:39] op_sel_hi:[1,0]
	v_pk_add_f32 v[70:71], v[70:71], s[38:39] op_sel_hi:[1,0]
	v_pk_add_f32 v[144:145], v[144:145], s[38:39] op_sel_hi:[1,0]
	v_pk_add_f32 v[146:147], v[146:147], s[38:39] op_sel_hi:[1,0]
	v_pk_add_f32 v[148:149], v[148:149], s[38:39] op_sel_hi:[1,0]
	v_pk_add_f32 v[150:151], v[150:151], s[38:39] op_sel_hi:[1,0]
	v_perm_b32 v196, v20, v16, s41
	v_perm_b32 v197, v28, v24, s41
	v_perm_b32 v180, v197, v196, s42
	v_perm_b32 v196, v36, v32, s41
	v_perm_b32 v197, v44, v40, s41
	v_perm_b32 v181, v197, v196, s42
	v_perm_b32 v196, v52, v48, s41
	v_perm_b32 v197, v60, v56, s41
	v_perm_b32 v182, v197, v196, s42
	v_perm_b32 v196, v68, v64, s41
	v_perm_b32 v197, v148, v144, s41
	v_perm_b32 v183, v197, v196, s42
	v_perm_b32 v196, v21, v17, s41
	v_perm_b32 v197, v29, v25, s41
	v_perm_b32 v184, v197, v196, s42
	v_perm_b32 v196, v37, v33, s41
	v_perm_b32 v197, v45, v41, s41
	v_perm_b32 v185, v197, v196, s42
	v_perm_b32 v196, v53, v49, s41
	v_perm_b32 v197, v61, v57, s41
	v_perm_b32 v186, v197, v196, s42
	v_perm_b32 v196, v69, v65, s41
	v_perm_b32 v197, v149, v145, s41
	v_perm_b32 v187, v197, v196, s42
	v_perm_b32 v196, v22, v18, s41
	v_perm_b32 v197, v30, v26, s41
	v_perm_b32 v188, v197, v196, s42
	v_perm_b32 v196, v38, v34, s41
	v_perm_b32 v197, v46, v42, s41
	v_perm_b32 v189, v197, v196, s42
	v_perm_b32 v196, v54, v50, s41
	v_perm_b32 v197, v62, v58, s41
	v_perm_b32 v190, v197, v196, s42
	v_perm_b32 v196, v70, v66, s41
	v_perm_b32 v197, v150, v146, s41
	v_perm_b32 v191, v197, v196, s42
	v_perm_b32 v196, v23, v19, s41
	v_perm_b32 v197, v31, v27, s41
	v_perm_b32 v192, v197, v196, s42
	v_perm_b32 v196, v39, v35, s41
	v_perm_b32 v197, v47, v43, s41
	v_perm_b32 v193, v197, v196, s42
	v_perm_b32 v196, v55, v51, s41
	v_perm_b32 v197, v63, v59, s41
	v_perm_b32 v194, v197, v196, s42
	v_perm_b32 v196, v71, v67, s41
	v_perm_b32 v197, v151, v147, s41
	v_perm_b32 v195, v197, v196, s42
	ds_write_b128 v205, v[180:183] offset:36864
	ds_write_b128 v205, v[184:187] offset:37008
	ds_write_b128 v205, v[188:191] offset:37152
	ds_write_b128 v205, v[192:195] offset:37296
	s_lshl_b32 s26, s63, 1
	s_add_i32 s27, s26, 0xffffaa80
	s_cmp_lt_u32 s63, 0x2b00
	s_cselect_b32 s26, s26, s27
	s_add_i32 s26, s26, s17
	s_mul_i32 s26, s26, 0x1000
	s_add_u32 s26, s26, s62
	s_add_u32 s54, s56, s26
	s_addc_u32 s55, s57, 0
	s_waitcnt lgkmcnt(0)
	s_barrier
	ds_read_b128 v[180:183], v206 offset:36864
	ds_read_b128 v[184:187], v206 offset:38016
	ds_read_b128 v[188:191], v206 offset:39168
	ds_read_b128 v[192:195], v206 offset:40320
	s_waitcnt lgkmcnt(3)
	global_store_dwordx4 v207, v[180:183], s[54:55]
	s_add_u32 s54, s54, 0x8000
	s_addc_u32 s55, s55, 0
	s_waitcnt lgkmcnt(2)
	global_store_dwordx4 v207, v[184:187], s[54:55]
	s_add_u32 s54, s54, 0x8000
	s_addc_u32 s55, s55, 0
	s_waitcnt lgkmcnt(1)
	global_store_dwordx4 v207, v[188:191], s[54:55]
	s_add_u32 s54, s54, 0x8000
	s_addc_u32 s55, s55, 0
	s_waitcnt lgkmcnt(0)
	global_store_dwordx4 v207, v[192:195], s[54:55]
	s_mov_b32 s19, s64
	s_cmp_lt_u32 s19, 0xac0
	s_cbranch_scc1 .Lf8t_f1in0_loop
.Lf8t_f1in0_end:
	s_waitcnt vmcnt(0) lgkmcnt(0)
	s_barrier

; #define LAS __attribute__((address_space(3)))
;     if (ldw == 0) ldw = N;
;     LAS float* scr = (LAS float*)(F.lds + F.wave * 16384); const int lane = F.lane;
;     const int nblk = N / 32, nitems = (K / 64) * nblk;
;     for (int item = F.gw; item < nitems; item += F.NGW) { const int kb = item / nblk, nb = item % nblk, k0 = 64 * kb, n0 = 32 * nb;
;         int dr0 = n0; if (MAP == 1) { if (n0 < DFF) dr0 = (n0 >> 7) * 256 + (n0 & 127); else { const int uo = n0 - DFF; dr0 = (uo >> 7) * 256 + 128 + (uo & 127); } }
; #pragma unroll 8
;         for (int i = 0; i < 32; ++i) { const int kk = 2 * i + (lane >> 5); scr[kk * 33 + (lane & 31)] = W[(size_t)(k0 + kk) * ldw + n0 + (lane & 31)]; }
; __device__ __forceinline__ void p0_prologue(Frame& F) {
;     ...
;     transpose_f8_matrix<0>(F, F.in[I_F1DN], DFF, D, F.ws + WS_WFD, pg8::W8SCALE_DN);
.LBB0_22:
.LBB0_23:
	s_barrier
	s_load_dwordx2 s[50:51], s[74:75], 0x40
	v_readlane_b32 s16, v240, 2
	v_lshlrev_b32_e32 v204, 4, v178
	v_mov_b32_e32 v208, 0x42fe0000
	s_mov_b32 s36, 0x43000000
	s_mov_b32 s37, 0
	s_mov_b32 s38, 0x4b400000
	s_mov_b32 s39, 0
	s_mov_b32 s40, 0xc2fe0000
	s_mov_b32 s41, 0x0c0c0400
	s_mov_b32 s42, 0x05040100
	s_lshl_b32 s17, s16, 5
	v_mul_u32_u24_e32 v205, 0x240, v178
	s_lshl_b32 s18, s16, 4
	v_add_u32_e32 v205, s18, v205
	v_lshrrev_b32_e32 v196, 3, v178
	v_and_b32_e32 v197, 7, v178
	s_lshl_b32 s18, s16, 5
	v_add_u32_e32 v198, s18, v196
	v_mul_u32_u24_e32 v206, 0x90, v198
	v_lshl_add_u32 v206, v197, 4, v206
	v_mul_u32_u24_e32 v207, 0x2b00, v196
	v_lshl_add_u32 v207, v197, 4, v207
	s_lshl_b32 s16, s16, 4
	s_waitcnt lgkmcnt(0)
	s_add_u32 s56, s90, 0x12f00000
	s_addc_u32 s57, s91, 0
	s_mov_b32 s19, s2
	s_cmp_lt_u32 s19, 0x560
	s_cbranch_scc0 .Lf8t_f1dn0_end
	s_mul_hi_u32 s20, s19, 0x10000000
	s_mul_i32 s21, s20, 16
	s_sub_i32 s21, s19, s21
	s_lshl_b32 s60, s20, 7
	s_lshl_b32 s61, s21, 8
	s_add_i32 s24, s60, s16
	s_mul_i32 s24, s24, 0x4000
	s_lshl_b32 s25, s61, 2
	s_add_u32 s24, s24, s25
	s_add_u32 s52, s50, s24
	s_addc_u32 s53, s51, 0
	global_load_dwordx4 v[80:83], v204, s[52:53]
	s_add_u32 s52, s52, 0x4000
	s_addc_u32 s53, s53, 0
	global_load_dwordx4 v[84:87], v204, s[52:53]
	s_add_u32 s52, s52, 0x4000
	s_addc_u32 s53, s53, 0
	global_load_dwordx4 v[88:91], v204, s[52:53]
	s_add_u32 s52, s52, 0x4000
	s_addc_u32 s53, s53, 0
	global_load_dwordx4 v[92:95], v204, s[52:53]
	s_add_u32 s52, s52, 0x4000
	s_addc_u32 s53, s53, 0
	global_load_dwordx4 v[96:99], v204, s[52:53]
	s_add_u32 s52, s52, 0x4000
	s_addc_u32 s53, s53, 0
	global_load_dwordx4 v[100:103], v204, s[52:53]
	s_add_u32 s52, s52, 0x4000
	s_addc_u32 s53, s53, 0
	global_load_dwordx4 v[104:107], v204, s[52:53]
	s_add_u32 s52, s52, 0x4000
	s_addc_u32 s53, s53, 0
	global_load_dwordx4 v[108:111], v204, s[52:53]
	s_add_u32 s52, s52, 0x4000
	s_addc_u32 s53, s53, 0
	global_load_dwordx4 v[112:115], v204, s[52:53]
	s_add_u32 s52, s52, 0x4000
	s_addc_u32 s53, s53, 0
	global_load_dwordx4 v[116:119], v204, s[52:53]
	s_add_u32 s52, s52, 0x4000
	s_addc_u32 s53, s53, 0
	global_load_dwordx4 v[120:123], v204, s[52:53]
	s_add_u32 s52, s52, 0x4000
	s_addc_u32 s53, s53, 0
	global_load_dwordx4 v[124:127], v204, s[52:53]
	s_add_u32 s52, s52, 0x4000
	s_addc_u32 s53, s53, 0
	global_load_dwordx4 v[128:131], v204, s[52:53]
	s_add_u32 s52, s52, 0x4000
	s_addc_u32 s53, s53, 0
	global_load_dwordx4 v[132:135], v204, s[52:53]
	s_add_u32 s52, s52, 0x4000
	s_addc_u32 s53, s53, 0
	global_load_dwordx4 v[136:139], v204, s[52:53]
	s_add_u32 s52, s52, 0x4000
	s_addc_u32 s53, s53, 0
	global_load_dwordx4 v[140:143], v204, s[52:53]
	s_mov_b32 s58, 1
.Lf8t_f1dn0_loop:
	s_add_i32 s64, s19, s96
	s_cmp_lt_u32 s64, 0x560
	s_cbranch_scc0 .Lf8t_f1dn0_a_nonext
	s_mul_hi_u32 s20, s64, 0x10000000
	s_mul_i32 s21, s20, 16
	s_sub_i32 s21, s64, s21
	s_lshl_b32 s62, s20, 7
	s_lshl_b32 s63, s21, 8
	s_add_i32 s24, s62, s16
	s_mul_i32 s24, s24, 0x4000
	s_lshl_b32 s25, s63, 2
	s_add_u32 s24, s24, s25
	s_add_u32 s52, s50, s24
	s_addc_u32 s53, s51, 0
	global_load_dwordx4 v[16:19], v204, s[52:53]
	s_add_u32 s52, s52, 0x4000
	s_addc_u32 s53, s53, 0
	global_load_dwordx4 v[20:23], v204, s[52:53]
	s_add_u32 s52, s52, 0x4000
	s_addc_u32 s53, s53, 0
	global_load_dwordx4 v[24:27], v204, s[52:53]
	s_add_u32 s52, s52, 0x4000
	s_addc_u32 s53, s53, 0
	global_load_dwordx4 v[28:31], v204, s[52:53]
	s_add_u32 s52, s52, 0x4000
	s_addc_u32 s53, s53, 0
	global_load_dwordx4 v[32:35], v204, s[52:53]
	s_add_u32 s52, s52, 0x4000
	s_addc_u32 s53, s53, 0
	global_load_dwordx4 v[36:39], v204, s[52:53]
	s_add_u32 s52, s52, 0x4000
	s_addc_u32 s53, s53, 0
	global_load_dwordx4 v[40:43], v204, s[52:53]
	s_add_u32 s52, s52, 0x4000
	s_addc_u32 s53, s53, 0
	global_load_dwordx4 v[44:47], v204, s[52:53]
	s_add_u32 s52, s52, 0x4000
	s_addc_u32 s53, s53, 0
	global_load_dwordx4 v[48:51], v204, s[52:53]
	s_add_u32 s52, s52, 0x4000
	s_addc_u32 s53, s53, 0
	global_load_dwordx4 v[52:55], v204, s[52:53]
	s_add_u32 s52, s52, 0x4000
	s_addc_u32 s53, s53, 0
	global_load_dwordx4 v[56:59], v204, s[52:53]
	s_add_u32 s52, s52, 0x4000
	s_addc_u32 s53, s53, 0
	global_load_dwordx4 v[60:63], v204, s[52:53]
	s_add_u32 s52, s52, 0x4000
	s_addc_u32 s53, s53, 0
	global_load_dwordx4 v[64:67], v204, s[52:53]
	s_add_u32 s52, s52, 0x4000
	s_addc_u32 s53, s53, 0
	global_load_dwordx4 v[68:71], v204, s[52:53]
	s_add_u32 s52, s52, 0x4000
	s_addc_u32 s53, s53, 0
	global_load_dwordx4 v[144:147], v204, s[52:53]
	s_add_u32 s52, s52, 0x4000
	s_addc_u32 s53, s53, 0
	global_load_dwordx4 v[148:151], v204, s[52:53]
	s_cmp_eq_u32 s58, 1
	s_cbranch_scc1 .Lf8t_f1dn0_a_first
	s_waitcnt vmcnt(20)
	s_branch .Lf8t_f1dn0_a_go

; #define LAS __attribute__((address_space(3)))
; __device__ __forceinline__ unsigned pk4_f8(float a, float b, float c, float d) { int w = __builtin_amdgcn_cvt_pk_fp8_f32(a, b, 0, false); w = __builtin_amdgcn_cvt_pk_fp8_f32(c, d, w, true); return (unsigned)w; }
;     ...
;         const int c = lane & 3;
; #pragma unroll
;         for (int j = 0; j < 2; ++j) { const int n = (lane >> 2) + 16 * j; const LAS float* sp = scr + (16 * c) * 33 + n;
;             u32x4 o;
;             if (QI8) { o.x = pk4_i8(sp[0 * 33], sp[1 * 33], sp[2 * 33], sp[3 * 33], scl); o.y = pk4_i8(sp[4 * 33], sp[5 * 33], sp[6 * 33], sp[7 * 33], scl);
;                 o.z = pk4_i8(sp[8 * 33], sp[9 * 33], sp[10 * 33], sp[11 * 33], scl); o.w = pk4_i8(sp[12 * 33], sp[13 * 33], sp[14 * 33], sp[15 * 33], scl); }
;             else {
;             o.x = pk4_f8(sp[0 * 33] * scl, sp[1 * 33] * scl, sp[2 * 33] * scl, sp[3 * 33] * scl); o.y = pk4_f8(sp[4 * 33] * scl, sp[5 * 33] * scl, sp[6 * 33] * scl, sp[7 * 33] * scl);
;             o.z = pk4_f8(sp[8 * 33] * scl, sp[9 * 33] * scl, sp[10 * 33] * scl, sp[11 * 33] * scl); o.w = pk4_f8(sp[12 * 33] * scl, sp[13 * 33] * scl, sp[14 * 33] * scl, sp[15 * 33] * scl); }
;             *(u32x4*)(WT + (size_t)(dr0 + n) * K + k0 + 16 * c) = o; }
.Lf8t_f1dn0_a_go:
	s_mov_b32 s58, 0
	v_pk_mul_f32 v[80:81], v[80:81], s[36:37] op_sel_hi:[1,0]
	v_pk_mul_f32 v[82:83], v[82:83], s[36:37] op_sel_hi:[1,0]
	v_pk_mul_f32 v[84:85], v[84:85], s[36:37] op_sel_hi:[1,0]
	v_pk_mul_f32 v[86:87], v[86:87], s[36:37] op_sel_hi:[1,0]
	v_pk_mul_f32 v[88:89], v[88:89], s[36:37] op_sel_hi:[1,0]
	v_pk_mul_f32 v[90:91], v[90:91], s[36:37] op_sel_hi:[1,0]
	v_pk_mul_f32 v[92:93], v[92:93], s[36:37] op_sel_hi:[1,0]
	v_pk_mul_f32 v[94:95], v[94:95], s[36:37] op_sel_hi:[1,0]
	v_pk_mul_f32 v[96:97], v[96:97], s[36:37] op_sel_hi:[1,0]
	v_pk_mul_f32 v[98:99], v[98:99], s[36:37] op_sel_hi:[1,0]
	v_pk_mul_f32 v[100:101], v[100:101], s[36:37] op_sel_hi:[1,0]
	v_pk_mul_f32 v[102:103], v[102:103], s[36:37] op_sel_hi:[1,0]
	v_pk_mul_f32 v[104:105], v[104:105], s[36:37] op_sel_hi:[1,0]
	v_pk_mul_f32 v[106:107], v[106:107], s[36:37] op_sel_hi:[1,0]
	v_pk_mul_f32 v[108:109], v[108:109], s[36:37] op_sel_hi:[1,0]
	v_pk_mul_f32 v[110:111], v[110:111], s[36:37] op_sel_hi:[1,0]
	v_pk_mul_f32 v[112:113], v[112:113], s[36:37] op_sel_hi:[1,0]
	v_pk_mul_f32 v[114:115], v[114:115], s[36:37] op_sel_hi:[1,0]
	v_pk_mul_f32 v[116:117], v[116:117], s[36:37] op_sel_hi:[1,0]
	v_pk_mul_f32 v[118:119], v[118:119], s[36:37] op_sel_hi:[1,0]
	v_pk_mul_f32 v[120:121], v[120:121], s[36:37] op_sel_hi:[1,0]
	v_pk_mul_f32 v[122:123], v[122:123], s[36:37] op_sel_hi:[1,0]
	v_pk_mul_f32 v[124:125], v[124:125], s[36:37] op_sel_hi:[1,0]
	v_pk_mul_f32 v[126:127], v[126:127], s[36:37] op_sel_hi:[1,0]
	v_pk_mul_f32 v[128:129], v[128:129], s[36:37] op_sel_hi:[1,0]
	v_pk_mul_f32 v[130:131], v[130:131], s[36:37] op_sel_hi:[1,0]
	v_pk_mul_f32 v[132:133], v[132:133], s[36:37] op_sel_hi:[1,0]
	v_pk_mul_f32 v[134:135], v[134:135], s[36:37] op_sel_hi:[1,0]
	v_pk_mul_f32 v[136:137], v[136:137], s[36:37] op_sel_hi:[1,0]
	v_pk_mul_f32 v[138:139], v[138:139], s[36:37] op_sel_hi:[1,0]
	v_pk_mul_f32 v[140:141], v[140:141], s[36:37] op_sel_hi:[1,0]
	v_pk_mul_f32 v[142:143], v[142:143], s[36:37] op_sel_hi:[1,0]
	v_cvt_pk_fp8_f32 v180, v80, v84
	v_cvt_pk_fp8_f32 v180, v88, v92 op_sel:[0,0,1]
	v_cvt_pk_fp8_f32 v181, v96, v100
	v_cvt_pk_fp8_f32 v181, v104, v108 op_sel:[0,0,1]
	v_cvt_pk_fp8_f32 v182, v112, v116
	v_cvt_pk_fp8_f32 v182, v120, v124 op_sel:[0,0,1]
	v_cvt_pk_fp8_f32 v183, v128, v132
	v_cvt_pk_fp8_f32 v183, v136, v140 op_sel:[0,0,1]
	v_cvt_pk_fp8_f32 v184, v81, v85
	v_cvt_pk_fp8_f32 v184, v89, v93 op_sel:[0,0,1]
	v_cvt_pk_fp8_f32 v185, v97, v101
	v_cvt_pk_fp8_f32 v185, v105, v109 op_sel:[0,0,1]
	v_cvt_pk_fp8_f32 v186, v113, v117
	v_cvt_pk_fp8_f32 v186, v121, v125 op_sel:[0,0,1]
	v_cvt_pk_fp8_f32 v187, v129, v133
	v_cvt_pk_fp8_f32 v187, v137, v141 op_sel:[0,0,1]
	v_cvt_pk_fp8_f32 v188, v82, v86
	v_cvt_pk_fp8_f32 v188, v90, v94 op_sel:[0,0,1]
	v_cvt_pk_fp8_f32 v189, v98, v102
	v_cvt_pk_fp8_f32 v189, v106, v110 op_sel:[0,0,1]
	v_cvt_pk_fp8_f32 v190, v114, v118
	v_cvt_pk_fp8_f32 v190, v122, v126 op_sel:[0,0,1]
	v_cvt_pk_fp8_f32 v191, v130, v134
	v_cvt_pk_fp8_f32 v191, v138, v142 op_sel:[0,0,1]
	v_cvt_pk_fp8_f32 v192, v83, v87
	v_cvt_pk_fp8_f32 v192, v91, v95 op_sel:[0,0,1]
	v_cvt_pk_fp8_f32 v193, v99, v103
	v_cvt_pk_fp8_f32 v193, v107, v111 op_sel:[0,0,1]
	v_cvt_pk_fp8_f32 v194, v115, v119
	v_cvt_pk_fp8_f32 v194, v123, v127 op_sel:[0,0,1]
	v_cvt_pk_fp8_f32 v195, v131, v135
	v_cvt_pk_fp8_f32 v195, v139, v143 op_sel:[0,0,1]
	ds_write_b128 v205, v[180:183] offset:0
	ds_write_b128 v205, v[184:187] offset:144
	ds_write_b128 v205, v[188:191] offset:288
	ds_write_b128 v205, v[192:195] offset:432
	s_mov_b32 s26, s61
	s_add_i32 s26, s26, s17
	s_mul_i32 s26, s26, 0x2b00
	s_add_u32 s26, s26, s60
	s_add_u32 s54, s56, s26
	s_addc_u32 s55, s57, 0
	s_waitcnt lgkmcnt(0)
	s_barrier
	ds_read_b128 v[180:183], v206 offset:0
	ds_read_b128 v[184:187], v206 offset:1152
	ds_read_b128 v[188:191], v206 offset:2304
	ds_read_b128 v[192:195], v206 offset:3456
	s_waitcnt lgkmcnt(3)
	global_store_dwordx4 v207, v[180:183], s[54:55]
	s_add_u32 s54, s54, 0x15800
	s_addc_u32 s55, s55, 0
	s_waitcnt lgkmcnt(2)
	global_store_dwordx4 v207, v[184:187], s[54:55]
	s_add_u32 s54, s54, 0x15800
	s_addc_u32 s55, s55, 0
	s_waitcnt lgkmcnt(1)
	global_store_dwordx4 v207, v[188:191], s[54:55]
	s_add_u32 s54, s54, 0x15800
	s_addc_u32 s55, s55, 0
	s_waitcnt lgkmcnt(0)
	global_store_dwordx4 v207, v[192:195], s[54:55]
	s_mov_b32 s19, s64
	s_cmp_lt_u32 s19, 0x560
	s_cbranch_scc0 .Lf8t_f1dn0_end
	s_add_i32 s64, s19, s96
	s_cmp_lt_u32 s64, 0x560
	s_cbranch_scc0 .Lf8t_f1dn0_b_nonext
	s_mul_hi_u32 s20, s64, 0x10000000
	s_mul_i32 s21, s20, 16
	s_sub_i32 s21, s64, s21
	s_lshl_b32 s60, s20, 7
	s_lshl_b32 s61, s21, 8
	s_add_i32 s24, s60, s16
	s_mul_i32 s24, s24, 0x4000
	s_lshl_b32 s25, s61, 2
	s_add_u32 s24, s24, s25
	s_add_u32 s52, s50, s24
	s_addc_u32 s53, s51, 0
	global_load_dwordx4 v[80:83], v204, s[52:53]
	s_add_u32 s52, s52, 0x4000
	s_addc_u32 s53, s53, 0
	global_load_dwordx4 v[84:87], v204, s[52:53]
	s_add_u32 s52, s52, 0x4000
	s_addc_u32 s53, s53, 0
	global_load_dwordx4 v[88:91], v204, s[52:53]
	s_add_u32 s52, s52, 0x4000
	s_addc_u32 s53, s53, 0
	global_load_dwordx4 v[92:95], v204, s[52:53]
	s_add_u32 s52, s52, 0x4000
	s_addc_u32 s53, s53, 0
	global_load_dwordx4 v[96:99], v204, s[52:53]
	s_add_u32 s52, s52, 0x4000
	s_addc_u32 s53, s53, 0
	global_load_dwordx4 v[100:103], v204, s[52:53]
	s_add_u32 s52, s52, 0x4000
	s_addc_u32 s53, s53, 0
	global_load_dwordx4 v[104:107], v204, s[52:53]
	s_add_u32 s52, s52, 0x4000
	s_addc_u32 s53, s53, 0
	global_load_dwordx4 v[108:111], v204, s[52:53]
	s_add_u32 s52, s52, 0x4000
	s_addc_u32 s53, s53, 0
	global_load_dwordx4 v[112:115], v204, s[52:53]
	s_add_u32 s52, s52, 0x4000
	s_addc_u32 s53, s53, 0
	global_load_dwordx4 v[116:119], v204, s[52:53]
	s_add_u32 s52, s52, 0x4000
	s_addc_u32 s53, s53, 0
	global_load_dwordx4 v[120:123], v204, s[52:53]
	s_add_u32 s52, s52, 0x4000
	s_addc_u32 s53, s53, 0
	global_load_dwordx4 v[124:127], v204, s[52:53]
	s_add_u32 s52, s52, 0x4000
	s_addc_u32 s53, s53, 0
	global_load_dwordx4 v[128:131], v204, s[52:53]
	s_add_u32 s52, s52, 0x4000
	s_addc_u32 s53, s53, 0
	global_load_dwordx4 v[132:135], v204, s[52:53]
	s_add_u32 s52, s52, 0x4000
	s_addc_u32 s53, s53, 0
	global_load_dwordx4 v[136:139], v204, s[52:53]
	s_add_u32 s52, s52, 0x4000
	s_addc_u32 s53, s53, 0
	global_load_dwordx4 v[140:143], v204, s[52:53]
	s_waitcnt vmcnt(20)
	s_branch .Lf8t_f1dn0_b_go

; #define LAS __attribute__((address_space(3)))
; __device__ __forceinline__ unsigned pk4_f8(float a, float b, float c, float d) { int w = __builtin_amdgcn_cvt_pk_fp8_f32(a, b, 0, false); w = __builtin_amdgcn_cvt_pk_fp8_f32(c, d, w, true); return (unsigned)w; }
; #define LDS_WAIT() asm volatile("s_waitcnt lgkmcnt(0)" ::: "memory")
;     ...
;         for (int j = 0; j < 2; ++j) { const int n = (lane >> 2) + 16 * j; const LAS float* sp = scr + (16 * c) * 33 + n;
;             u32x4 o;
;             if (QI8) { o.x = pk4_i8(sp[0 * 33], sp[1 * 33], sp[2 * 33], sp[3 * 33], scl); o.y = pk4_i8(sp[4 * 33], sp[5 * 33], sp[6 * 33], sp[7 * 33], scl);
;                 o.z = pk4_i8(sp[8 * 33], sp[9 * 33], sp[10 * 33], sp[11 * 33], scl); o.w = pk4_i8(sp[12 * 33], sp[13 * 33], sp[14 * 33], sp[15 * 33], scl); }
;             else {
;             o.x = pk4_f8(sp[0 * 33] * scl, sp[1 * 33] * scl, sp[2 * 33] * scl, sp[3 * 33] * scl); o.y = pk4_f8(sp[4 * 33] * scl, sp[5 * 33] * scl, sp[6 * 33] * scl, sp[7 * 33] * scl);
;             o.z = pk4_f8(sp[8 * 33] * scl, sp[9 * 33] * scl, sp[10 * 33] * scl, sp[11 * 33] * scl); o.w = pk4_f8(sp[12 * 33] * scl, sp[13 * 33] * scl, sp[14 * 33] * scl, sp[15 * 33] * scl); }
;             *(u32x4*)(WT + (size_t)(dr0 + n) * K + k0 + 16 * c) = o; }
;         LDS_WAIT(); asm volatile("" ::: "memory"); }
.Lf8t_f1dn0_b_go:
	v_pk_mul_f32 v[16:17], v[16:17], s[36:37] op_sel_hi:[1,0]
	v_pk_mul_f32 v[18:19], v[18:19], s[36:37] op_sel_hi:[1,0]
	v_pk_mul_f32 v[20:21], v[20:21], s[36:37] op_sel_hi:[1,0]
	v_pk_mul_f32 v[22:23], v[22:23], s[36:37] op_sel_hi:[1,0]
	v_pk_mul_f32 v[24:25], v[24:25], s[36:37] op_sel_hi:[1,0]
	v_pk_mul_f32 v[26:27], v[26:27], s[36:37] op_sel_hi:[1,0]
	v_pk_mul_f32 v[28:29], v[28:29], s[36:37] op_sel_hi:[1,0]
	v_pk_mul_f32 v[30:31], v[30:31], s[36:37] op_sel_hi:[1,0]
	v_pk_mul_f32 v[32:33], v[32:33], s[36:37] op_sel_hi:[1,0]
	v_pk_mul_f32 v[34:35], v[34:35], s[36:37] op_sel_hi:[1,0]
	v_pk_mul_f32 v[36:37], v[36:37], s[36:37] op_sel_hi:[1,0]
	v_pk_mul_f32 v[38:39], v[38:39], s[36:37] op_sel_hi:[1,0]
	v_pk_mul_f32 v[40:41], v[40:41], s[36:37] op_sel_hi:[1,0]
	v_pk_mul_f32 v[42:43], v[42:43], s[36:37] op_sel_hi:[1,0]
	v_pk_mul_f32 v[44:45], v[44:45], s[36:37] op_sel_hi:[1,0]
	v_pk_mul_f32 v[46:47], v[46:47], s[36:37] op_sel_hi:[1,0]
	v_pk_mul_f32 v[48:49], v[48:49], s[36:37] op_sel_hi:[1,0]
	v_pk_mul_f32 v[50:51], v[50:51], s[36:37] op_sel_hi:[1,0]
	v_pk_mul_f32 v[52:53], v[52:53], s[36:37] op_sel_hi:[1,0]
	v_pk_mul_f32 v[54:55], v[54:55], s[36:37] op_sel_hi:[1,0]
	v_pk_mul_f32 v[56:57], v[56:57], s[36:37] op_sel_hi:[1,0]
	v_pk_mul_f32 v[58:59], v[58:59], s[36:37] op_sel_hi:[1,0]
	v_pk_mul_f32 v[60:61], v[60:61], s[36:37] op_sel_hi:[1,0]
	v_pk_mul_f32 v[62:63], v[62:63], s[36:37] op_sel_hi:[1,0]
	v_pk_mul_f32 v[64:65], v[64:65], s[36:37] op_sel_hi:[1,0]
	v_pk_mul_f32 v[66:67], v[66:67], s[36:37] op_sel_hi:[1,0]
	v_pk_mul_f32 v[68:69], v[68:69], s[36:37] op_sel_hi:[1,0]
	v_pk_mul_f32 v[70:71], v[70:71], s[36:37] op_sel_hi:[1,0]
	v_pk_mul_f32 v[144:145], v[144:145], s[36:37] op_sel_hi:[1,0]
	v_pk_mul_f32 v[146:147], v[146:147], s[36:37] op_sel_hi:[1,0]
	v_pk_mul_f32 v[148:149], v[148:149], s[36:37] op_sel_hi:[1,0]
	v_pk_mul_f32 v[150:151], v[150:151], s[36:37] op_sel_hi:[1,0]
	v_cvt_pk_fp8_f32 v180, v16, v20
	v_cvt_pk_fp8_f32 v180, v24, v28 op_sel:[0,0,1]
	v_cvt_pk_fp8_f32 v181, v32, v36
	v_cvt_pk_fp8_f32 v181, v40, v44 op_sel:[0,0,1]
	v_cvt_pk_fp8_f32 v182, v48, v52
	v_cvt_pk_fp8_f32 v182, v56, v60 op_sel:[0,0,1]
	v_cvt_pk_fp8_f32 v183, v64, v68
	v_cvt_pk_fp8_f32 v183, v144, v148 op_sel:[0,0,1]
	v_cvt_pk_fp8_f32 v184, v17, v21
	v_cvt_pk_fp8_f32 v184, v25, v29 op_sel:[0,0,1]
	v_cvt_pk_fp8_f32 v185, v33, v37
	v_cvt_pk_fp8_f32 v185, v41, v45 op_sel:[0,0,1]
	v_cvt_pk_fp8_f32 v186, v49, v53
	v_cvt_pk_fp8_f32 v186, v57, v61 op_sel:[0,0,1]
	v_cvt_pk_fp8_f32 v187, v65, v69
	v_cvt_pk_fp8_f32 v187, v145, v149 op_sel:[0,0,1]
	v_cvt_pk_fp8_f32 v188, v18, v22
	v_cvt_pk_fp8_f32 v188, v26, v30 op_sel:[0,0,1]
	v_cvt_pk_fp8_f32 v189, v34, v38
	v_cvt_pk_fp8_f32 v189, v42, v46 op_sel:[0,0,1]
	v_cvt_pk_fp8_f32 v190, v50, v54
	v_cvt_pk_fp8_f32 v190, v58, v62 op_sel:[0,0,1]
	v_cvt_pk_fp8_f32 v191, v66, v70
	v_cvt_pk_fp8_f32 v191, v146, v150 op_sel:[0,0,1]
	v_cvt_pk_fp8_f32 v192, v19, v23
	v_cvt_pk_fp8_f32 v192, v27, v31 op_sel:[0,0,1]
	v_cvt_pk_fp8_f32 v193, v35, v39
	v_cvt_pk_fp8_f32 v193, v43, v47 op_sel:[0,0,1]
	v_cvt_pk_fp8_f32 v194, v51, v55
	v_cvt_pk_fp8_f32 v194, v59, v63 op_sel:[0,0,1]
	v_cvt_pk_fp8_f32 v195, v67, v71
	v_cvt_pk_fp8_f32 v195, v147, v151 op_sel:[0,0,1]
	ds_write_b128 v205, v[180:183] offset:36864
	ds_write_b128 v205, v[184:187] offset:37008
	ds_write_b128 v205, v[188:191] offset:37152
	ds_write_b128 v205, v[192:195] offset:37296
	s_mov_b32 s26, s63
	s_add_i32 s26, s26, s17
	s_mul_i32 s26, s26, 0x2b00
	s_add_u32 s26, s26, s62
	s_add_u32 s54, s56, s26
	s_addc_u32 s55, s57, 0
	s_waitcnt lgkmcnt(0)
	s_barrier
	ds_read_b128 v[180:183], v206 offset:36864
	ds_read_b128 v[184:187], v206 offset:38016
	ds_read_b128 v[188:191], v206 offset:39168
	ds_read_b128 v[192:195], v206 offset:40320
	s_waitcnt lgkmcnt(3)
	global_store_dwordx4 v207, v[180:183], s[54:55]
	s_add_u32 s54, s54, 0x15800
	s_addc_u32 s55, s55, 0
	s_waitcnt lgkmcnt(2)
	global_store_dwordx4 v207, v[184:187], s[54:55]
	s_add_u32 s54, s54, 0x15800
	s_addc_u32 s55, s55, 0
	s_waitcnt lgkmcnt(1)
	global_store_dwordx4 v207, v[188:191], s[54:55]
	s_add_u32 s54, s54, 0x15800
	s_addc_u32 s55, s55, 0
	s_waitcnt lgkmcnt(0)
	global_store_dwordx4 v207, v[192:195], s[54:55]
	s_mov_b32 s19, s64
	s_cmp_lt_u32 s19, 0x560
	s_cbranch_scc1 .Lf8t_f1dn0_loop
.Lf8t_f1dn0_end:
	s_waitcnt vmcnt(0) lgkmcnt(0)
	s_barrier
	v_readlane_b32 s3, v240, 2
	s_nop 3
	s_lshl_b32 s3, s3, 14

; #define LAS __attribute__((address_space(3)))
;     if (ldw == 0) ldw = N;
;     LAS float* scr = (LAS float*)(F.lds + F.wave * 16384); const int lane = F.lane;
;     const int nblk = N / 32, nitems = (K / 64) * nblk;
;     for (int item = F.gw; item < nitems; item += F.NGW) { const int kb = item / nblk, nb = item % nblk, k0 = 64 * kb, n0 = 32 * nb;
;         int dr0 = n0; if (MAP == 1) { if (n0 < DFF) dr0 = (n0 >> 7) * 256 + (n0 & 127); else { const int uo = n0 - DFF; dr0 = (uo >> 7) * 256 + 128 + (uo & 127); } }
; #pragma unroll 8
;         for (int i = 0; i < 32; ++i) { const int kk = 2 * i + (lane >> 5); scr[kk * 33 + (lane & 31)] = W[(size_t)(k0 + kk) * ldw + n0 + (lane & 31)]; }
; __device__ __forceinline__ void p0_prologue(Frame& F) {
;     ...
;       transpose_f8_matrix<0, true>(F, W + 8192 + DRIN, D, 8192, w8, I8_W, ldw);
.LBB0_37:
	s_cmpk_gt_i32 s94, 0x3fff
	s_cbranch_scc1 .LBB0_42
	s_barrier
	s_load_dwordx2 s[50:51], s[74:75], 0x58
	v_readlane_b32 s16, v240, 2
	v_lshlrev_b32_e32 v204, 4, v178
	v_mov_b32_e32 v208, 0x42fe0000
	s_mov_b32 s36, 0x44fe0000
	s_mov_b32 s37, 0
	s_mov_b32 s38, 0x4b400000
	s_mov_b32 s39, 0
	s_mov_b32 s40, 0xc2fe0000
	s_mov_b32 s41, 0x0c0c0400
	s_mov_b32 s42, 0x05040100
	s_lshl_b32 s17, s16, 5
	v_mul_u32_u24_e32 v205, 0x240, v178
	s_lshl_b32 s18, s16, 4
	v_add_u32_e32 v205, s18, v205
	v_lshrrev_b32_e32 v196, 3, v178
	v_and_b32_e32 v197, 7, v178
	s_lshl_b32 s18, s16, 5
	v_add_u32_e32 v198, s18, v196
	v_mul_u32_u24_e32 v206, 0x90, v198
	v_lshl_add_u32 v206, v197, 4, v206
	v_mul_u32_u24_e32 v207, 0x1000, v196
	v_lshl_add_u32 v207, v197, 4, v207
	s_lshl_b32 s16, s16, 4
	s_waitcnt lgkmcnt(0)
	s_add_u32 s50, s50, 0xeb80
	s_addc_u32 s51, s51, 0
	s_add_u32 s56, s90, 0x35b00000
	s_addc_u32 s57, s91, 0
	s_mov_b32 s19, s2
	s_cmp_lt_u32 s19, 0x400
	s_cbranch_scc0 .Lf8t_win8a0_end
	s_mul_hi_u32 s20, s19, 0x8000000
	s_mul_i32 s21, s20, 32
	s_sub_i32 s21, s19, s21
	s_lshl_b32 s60, s20, 7
	s_lshl_b32 s61, s21, 8
	s_add_i32 s24, s60, s16
	s_mul_i32 s24, s24, 0x16b80
	s_lshl_b32 s25, s61, 2
	s_add_u32 s24, s24, s25
	s_add_u32 s52, s50, s24
	s_addc_u32 s53, s51, 0
	global_load_dwordx4 v[80:83], v204, s[52:53]
	s_add_u32 s52, s52, 0x16b80
	s_addc_u32 s53, s53, 0
	global_load_dwordx4 v[84:87], v204, s[52:53]
	s_add_u32 s52, s52, 0x16b80
	s_addc_u32 s53, s53, 0
	global_load_dwordx4 v[88:91], v204, s[52:53]
	s_add_u32 s52, s52, 0x16b80
	s_addc_u32 s53, s53, 0
	global_load_dwordx4 v[92:95], v204, s[52:53]
	s_add_u32 s52, s52, 0x16b80
	s_addc_u32 s53, s53, 0
	global_load_dwordx4 v[96:99], v204, s[52:53]
	s_add_u32 s52, s52, 0x16b80
	s_addc_u32 s53, s53, 0
	global_load_dwordx4 v[100:103], v204, s[52:53]
	s_add_u32 s52, s52, 0x16b80
	s_addc_u32 s53, s53, 0
	global_load_dwordx4 v[104:107], v204, s[52:53]
	s_add_u32 s52, s52, 0x16b80
	s_addc_u32 s53, s53, 0
	global_load_dwordx4 v[108:111], v204, s[52:53]
	s_add_u32 s52, s52, 0x16b80
	s_addc_u32 s53, s53, 0
	global_load_dwordx4 v[112:115], v204, s[52:53]
	s_add_u32 s52, s52, 0x16b80
	s_addc_u32 s53, s53, 0
	global_load_dwordx4 v[116:119], v204, s[52:53]
	s_add_u32 s52, s52, 0x16b80
	s_addc_u32 s53, s53, 0
	global_load_dwordx4 v[120:123], v204, s[52:53]
	s_add_u32 s52, s52, 0x16b80
	s_addc_u32 s53, s53, 0
	global_load_dwordx4 v[124:127], v204, s[52:53]
	s_add_u32 s52, s52, 0x16b80
	s_addc_u32 s53, s53, 0
	global_load_dwordx4 v[128:131], v204, s[52:53]
	s_add_u32 s52, s52, 0x16b80
	s_addc_u32 s53, s53, 0
	global_load_dwordx4 v[132:135], v204, s[52:53]
	s_add_u32 s52, s52, 0x16b80
	s_addc_u32 s53, s53, 0
	global_load_dwordx4 v[136:139], v204, s[52:53]
	s_add_u32 s52, s52, 0x16b80
	s_addc_u32 s53, s53, 0
	global_load_dwordx4 v[140:143], v204, s[52:53]
	s_mov_b32 s58, 1
.Lf8t_win8a0_loop:
	s_add_i32 s64, s19, s96
	s_cmp_lt_u32 s64, 0x400
	s_cbranch_scc0 .Lf8t_win8a0_a_nonext
	s_mul_hi_u32 s20, s64, 0x8000000
	s_mul_i32 s21, s20, 32
	s_sub_i32 s21, s64, s21
	s_lshl_b32 s62, s20, 7
	s_lshl_b32 s63, s21, 8
	s_add_i32 s24, s62, s16
	s_mul_i32 s24, s24, 0x16b80
	s_lshl_b32 s25, s63, 2
	s_add_u32 s24, s24, s25
	s_add_u32 s52, s50, s24
	s_addc_u32 s53, s51, 0
	global_load_dwordx4 v[16:19], v204, s[52:53]
	s_add_u32 s52, s52, 0x16b80
	s_addc_u32 s53, s53, 0
	global_load_dwordx4 v[20:23], v204, s[52:53]
	s_add_u32 s52, s52, 0x16b80
	s_addc_u32 s53, s53, 0
	global_load_dwordx4 v[24:27], v204, s[52:53]
	s_add_u32 s52, s52, 0x16b80
	s_addc_u32 s53, s53, 0
	global_load_dwordx4 v[28:31], v204, s[52:53]
	s_add_u32 s52, s52, 0x16b80
	s_addc_u32 s53, s53, 0
	global_load_dwordx4 v[32:35], v204, s[52:53]
	s_add_u32 s52, s52, 0x16b80
	s_addc_u32 s53, s53, 0
	global_load_dwordx4 v[36:39], v204, s[52:53]
	s_add_u32 s52, s52, 0x16b80
	s_addc_u32 s53, s53, 0
	global_load_dwordx4 v[40:43], v204, s[52:53]
	s_add_u32 s52, s52, 0x16b80
	s_addc_u32 s53, s53, 0
	global_load_dwordx4 v[44:47], v204, s[52:53]
	s_add_u32 s52, s52, 0x16b80
	s_addc_u32 s53, s53, 0
	global_load_dwordx4 v[48:51], v204, s[52:53]
	s_add_u32 s52, s52, 0x16b80
	s_addc_u32 s53, s53, 0
	global_load_dwordx4 v[52:55], v204, s[52:53]
	s_add_u32 s52, s52, 0x16b80
	s_addc_u32 s53, s53, 0
	global_load_dwordx4 v[56:59], v204, s[52:53]
	s_add_u32 s52, s52, 0x16b80
	s_addc_u32 s53, s53, 0
	global_load_dwordx4 v[60:63], v204, s[52:53]
	s_add_u32 s52, s52, 0x16b80
	s_addc_u32 s53, s53, 0
	global_load_dwordx4 v[64:67], v204, s[52:53]
	s_add_u32 s52, s52, 0x16b80
	s_addc_u32 s53, s53, 0
	global_load_dwordx4 v[68:71], v204, s[52:53]
	s_add_u32 s52, s52, 0x16b80
	s_addc_u32 s53, s53, 0
	global_load_dwordx4 v[144:147], v204, s[52:53]
	s_add_u32 s52, s52, 0x16b80
	s_addc_u32 s53, s53, 0
	global_load_dwordx4 v[148:151], v204, s[52:53]
	s_cmp_eq_u32 s58, 1
	s_cbranch_scc1 .Lf8t_win8a0_a_first
	s_waitcnt vmcnt(20)
	s_branch .Lf8t_win8a0_a_go

; __device__ __forceinline__ unsigned pk4_i8(float a, float b, float c, float d, float s) {
;     const unsigned ua = __float_as_uint(__builtin_amdgcn_fmed3f(a * s, -127.f, 127.f) + 12582912.f), ub = __float_as_uint(__builtin_amdgcn_fmed3f(b * s, -127.f, 127.f) + 12582912.f);
;     const unsigned uc = __float_as_uint(__builtin_amdgcn_fmed3f(c * s, -127.f, 127.f) + 12582912.f), ud = __float_as_uint(__builtin_amdgcn_fmed3f(d * s, -127.f, 127.f) + 12582912.f);
;     return (ua & 0xffu) | ((ub & 0xffu) << 8) | ((uc & 0xffu) << 16) | (ud << 24);
;     ...
;             if (QI8) { o.x = pk4_i8(sp[0 * 33], sp[1 * 33], sp[2 * 33], sp[3 * 33], scl); o.y = pk4_i8(sp[4 * 33], sp[5 * 33], sp[6 * 33], sp[7 * 33], scl);
;                 o.z = pk4_i8(sp[8 * 33], sp[9 * 33], sp[10 * 33], sp[11 * 33], scl); o.w = pk4_i8(sp[12 * 33], sp[13 * 33], sp[14 * 33], sp[15 * 33], scl); }
.Lf8t_win8a0_a_go:
	s_mov_b32 s58, 0
	v_pk_mul_f32 v[80:81], v[80:81], s[36:37] op_sel_hi:[1,0]
	v_pk_mul_f32 v[82:83], v[82:83], s[36:37] op_sel_hi:[1,0]
	v_pk_mul_f32 v[84:85], v[84:85], s[36:37] op_sel_hi:[1,0]
	v_pk_mul_f32 v[86:87], v[86:87], s[36:37] op_sel_hi:[1,0]
	v_pk_mul_f32 v[88:89], v[88:89], s[36:37] op_sel_hi:[1,0]
	v_pk_mul_f32 v[90:91], v[90:91], s[36:37] op_sel_hi:[1,0]
	v_pk_mul_f32 v[92:93], v[92:93], s[36:37] op_sel_hi:[1,0]
	v_pk_mul_f32 v[94:95], v[94:95], s[36:37] op_sel_hi:[1,0]
	v_pk_mul_f32 v[96:97], v[96:97], s[36:37] op_sel_hi:[1,0]
	v_pk_mul_f32 v[98:99], v[98:99], s[36:37] op_sel_hi:[1,0]
	v_pk_mul_f32 v[100:101], v[100:101], s[36:37] op_sel_hi:[1,0]
	v_pk_mul_f32 v[102:103], v[102:103], s[36:37] op_sel_hi:[1,0]
	v_pk_mul_f32 v[104:105], v[104:105], s[36:37] op_sel_hi:[1,0]
	v_pk_mul_f32 v[106:107], v[106:107], s[36:37] op_sel_hi:[1,0]
	v_pk_mul_f32 v[108:109], v[108:109], s[36:37] op_sel_hi:[1,0]
	v_pk_mul_f32 v[110:111], v[110:111], s[36:37] op_sel_hi:[1,0]
	v_pk_mul_f32 v[112:113], v[112:113], s[36:37] op_sel_hi:[1,0]
	v_pk_mul_f32 v[114:115], v[114:115], s[36:37] op_sel_hi:[1,0]
	v_pk_mul_f32 v[116:117], v[116:117], s[36:37] op_sel_hi:[1,0]
	v_pk_mul_f32 v[118:119], v[118:119], s[36:37] op_sel_hi:[1,0]
	v_pk_mul_f32 v[120:121], v[120:121], s[36:37] op_sel_hi:[1,0]
	v_pk_mul_f32 v[122:123], v[122:123], s[36:37] op_sel_hi:[1,0]
	v_pk_mul_f32 v[124:125], v[124:125], s[36:37] op_sel_hi:[1,0]
	v_pk_mul_f32 v[126:127], v[126:127], s[36:37] op_sel_hi:[1,0]
	v_pk_mul_f32 v[128:129], v[128:129], s[36:37] op_sel_hi:[1,0]
	v_pk_mul_f32 v[130:131], v[130:131], s[36:37] op_sel_hi:[1,0]
	v_pk_mul_f32 v[132:133], v[132:133], s[36:37] op_sel_hi:[1,0]
	v_pk_mul_f32 v[134:135], v[134:135], s[36:37] op_sel_hi:[1,0]
	v_pk_mul_f32 v[136:137], v[136:137], s[36:37] op_sel_hi:[1,0]
	v_pk_mul_f32 v[138:139], v[138:139], s[36:37] op_sel_hi:[1,0]
	v_pk_mul_f32 v[140:141], v[140:141], s[36:37] op_sel_hi:[1,0]
	v_pk_mul_f32 v[142:143], v[142:143], s[36:37] op_sel_hi:[1,0]
	v_med3_f32 v80, v80, s40, v208
	v_med3_f32 v81, v81, s40, v208
	v_med3_f32 v82, v82, s40, v208
	v_med3_f32 v83, v83, s40, v208
	v_med3_f32 v84, v84, s40, v208
	v_med3_f32 v85, v85, s40, v208
	v_med3_f32 v86, v86, s40, v208
	v_med3_f32 v87, v87, s40, v208
	v_med3_f32 v88, v88, s40, v208
	v_med3_f32 v89, v89, s40, v208
	v_med3_f32 v90, v90, s40, v208
	v_med3_f32 v91, v91, s40, v208
	v_med3_f32 v92, v92, s40, v208
	v_med3_f32 v93, v93, s40, v208
	v_med3_f32 v94, v94, s40, v208
	v_med3_f32 v95, v95, s40, v208
	v_med3_f32 v96, v96, s40, v208
	v_med3_f32 v97, v97, s40, v208
	v_med3_f32 v98, v98, s40, v208
	v_med3_f32 v99, v99, s40, v208
	v_med3_f32 v100, v100, s40, v208
	v_med3_f32 v101, v101, s40, v208
	v_med3_f32 v102, v102, s40, v208
	v_med3_f32 v103, v103, s40, v208
	v_med3_f32 v104, v104, s40, v208
	v_med3_f32 v105, v105, s40, v208
	v_med3_f32 v106, v106, s40, v208
	v_med3_f32 v107, v107, s40, v208
	v_med3_f32 v108, v108, s40, v208
	v_med3_f32 v109, v109, s40, v208
	v_med3_f32 v110, v110, s40, v208
	v_med3_f32 v111, v111, s40, v208
	v_med3_f32 v112, v112, s40, v208
	v_med3_f32 v113, v113, s40, v208
	v_med3_f32 v114, v114, s40, v208
	v_med3_f32 v115, v115, s40, v208
	v_med3_f32 v116, v116, s40, v208
	v_med3_f32 v117, v117, s40, v208
	v_med3_f32 v118, v118, s40, v208
	v_med3_f32 v119, v119, s40, v208
	v_med3_f32 v120, v120, s40, v208
	v_med3_f32 v121, v121, s40, v208
	v_med3_f32 v122, v122, s40, v208
	v_med3_f32 v123, v123, s40, v208
	v_med3_f32 v124, v124, s40, v208
	v_med3_f32 v125, v125, s40, v208
	v_med3_f32 v126, v126, s40, v208
	v_med3_f32 v127, v127, s40, v208
	v_med3_f32 v128, v128, s40, v208
	v_med3_f32 v129, v129, s40, v208
	v_med3_f32 v130, v130, s40, v208
	v_med3_f32 v131, v131, s40, v208
	v_med3_f32 v132, v132, s40, v208
	v_med3_f32 v133, v133, s40, v208
	v_med3_f32 v134, v134, s40, v208
	v_med3_f32 v135, v135, s40, v208
	v_med3_f32 v136, v136, s40, v208
	v_med3_f32 v137, v137, s40, v208
	v_med3_f32 v138, v138, s40, v208
	v_med3_f32 v139, v139, s40, v208
	v_med3_f32 v140, v140, s40, v208
	v_med3_f32 v141, v141, s40, v208
	v_med3_f32 v142, v142, s40, v208
	v_med3_f32 v143, v143, s40, v208
	v_pk_add_f32 v[80:81], v[80:81], s[38:39] op_sel_hi:[1,0]
	v_pk_add_f32 v[82:83], v[82:83], s[38:39] op_sel_hi:[1,0]
	v_pk_add_f32 v[84:85], v[84:85], s[38:39] op_sel_hi:[1,0]
	v_pk_add_f32 v[86:87], v[86:87], s[38:39] op_sel_hi:[1,0]
	v_pk_add_f32 v[88:89], v[88:89], s[38:39] op_sel_hi:[1,0]
	v_pk_add_f32 v[90:91], v[90:91], s[38:39] op_sel_hi:[1,0]
	v_pk_add_f32 v[92:93], v[92:93], s[38:39] op_sel_hi:[1,0]
	v_pk_add_f32 v[94:95], v[94:95], s[38:39] op_sel_hi:[1,0]
	v_pk_add_f32 v[96:97], v[96:97], s[38:39] op_sel_hi:[1,0]
	v_pk_add_f32 v[98:99], v[98:99], s[38:39] op_sel_hi:[1,0]
	v_pk_add_f32 v[100:101], v[100:101], s[38:39] op_sel_hi:[1,0]
	v_pk_add_f32 v[102:103], v[102:103], s[38:39] op_sel_hi:[1,0]
	v_pk_add_f32 v[104:105], v[104:105], s[38:39] op_sel_hi:[1,0]
	v_pk_add_f32 v[106:107], v[106:107], s[38:39] op_sel_hi:[1,0]
	v_pk_add_f32 v[108:109], v[108:109], s[38:39] op_sel_hi:[1,0]
	v_pk_add_f32 v[110:111], v[110:111], s[38:39] op_sel_hi:[1,0]
	v_pk_add_f32 v[112:113], v[112:113], s[38:39] op_sel_hi:[1,0]
	v_pk_add_f32 v[114:115], v[114:115], s[38:39] op_sel_hi:[1,0]
	v_pk_add_f32 v[116:117], v[116:117], s[38:39] op_sel_hi:[1,0]
	v_pk_add_f32 v[118:119], v[118:119], s[38:39] op_sel_hi:[1,0]
; #define LAS __attribute__((address_space(3)))
; __device__ __forceinline__ unsigned pk4_f8(float a, float b, float c, float d) { int w = __builtin_amdgcn_cvt_pk_fp8_f32(a, b, 0, false); w = __builtin_amdgcn_cvt_pk_fp8_f32(c, d, w, true); return (unsigned)w; }
; #define LDS_WAIT() asm volatile("s_waitcnt lgkmcnt(0)" ::: "memory")
;     ...
;     for (int item = F.gw; item < nitems; item += F.NGW) { const int kb = item / nblk, nb = item % nblk, k0 = 64 * kb, n0 = 32 * nb;
;         int dr0 = n0; if (MAP == 1) { if (n0 < DFF) dr0 = (n0 >> 7) * 256 + (n0 & 127); else { const int uo = n0 - DFF; dr0 = (uo >> 7) * 256 + 128 + (uo & 127); } }
; #pragma unroll 8
;         for (int i = 0; i < 32; ++i) { const int kk = 2 * i + (lane >> 5); scr[kk * 33 + (lane & 31)] = W[(size_t)(k0 + kk) * ldw + n0 + (lane & 31)]; }
;         LDS_WAIT(); asm volatile("" ::: "memory");
;         const int c = lane & 3;
; #pragma unroll
;         for (int j = 0; j < 2; ++j) { const int n = (lane >> 2) + 16 * j; const LAS float* sp = scr + (16 * c) * 33 + n;
;             u32x4 o;
;             if (QI8) { o.x = pk4_i8(sp[0 * 33], sp[1 * 33], sp[2 * 33], sp[3 * 33], scl); o.y = pk4_i8(sp[4 * 33], sp[5 * 33], sp[6 * 33], sp[7 * 33], scl);
;                 o.z = pk4_i8(sp[8 * 33], sp[9 * 33], sp[10 * 33], sp[11 * 33], scl); o.w = pk4_i8(sp[12 * 33], sp[13 * 33], sp[14 * 33], sp[15 * 33], scl); }
;             else {
;             o.x = pk4_f8(sp[0 * 33] * scl, sp[1 * 33] * scl, sp[2 * 33] * scl, sp[3 * 33] * scl); o.y = pk4_f8(sp[4 * 33] * scl, sp[5 * 33] * scl, sp[6 * 33] * scl, sp[7 * 33] * scl);
;             o.z = pk4_f8(sp[8 * 33] * scl, sp[9 * 33] * scl, sp[10 * 33] * scl, sp[11 * 33] * scl); o.w = pk4_f8(sp[12 * 33] * scl, sp[13 * 33] * scl, sp[14 * 33] * scl, sp[15 * 33] * scl); }
;             *(u32x4*)(WT + (size_t)(dr0 + n) * K + k0 + 16 * c) = o; }
	v_pk_add_f32 v[120:121], v[120:121], s[38:39] op_sel_hi:[1,0]
	v_pk_add_f32 v[122:123], v[122:123], s[38:39] op_sel_hi:[1,0]
	v_pk_add_f32 v[124:125], v[124:125], s[38:39] op_sel_hi:[1,0]
	v_pk_add_f32 v[126:127], v[126:127], s[38:39] op_sel_hi:[1,0]
	v_pk_add_f32 v[128:129], v[128:129], s[38:39] op_sel_hi:[1,0]
	v_pk_add_f32 v[130:131], v[130:131], s[38:39] op_sel_hi:[1,0]
	v_pk_add_f32 v[132:133], v[132:133], s[38:39] op_sel_hi:[1,0]
	v_pk_add_f32 v[134:135], v[134:135], s[38:39] op_sel_hi:[1,0]
	v_pk_add_f32 v[136:137], v[136:137], s[38:39] op_sel_hi:[1,0]
	v_pk_add_f32 v[138:139], v[138:139], s[38:39] op_sel_hi:[1,0]
	v_pk_add_f32 v[140:141], v[140:141], s[38:39] op_sel_hi:[1,0]
	v_pk_add_f32 v[142:143], v[142:143], s[38:39] op_sel_hi:[1,0]
	v_perm_b32 v196, v84, v80, s41
	v_perm_b32 v197, v92, v88, s41
	v_perm_b32 v180, v197, v196, s42
	v_perm_b32 v196, v100, v96, s41
	v_perm_b32 v197, v108, v104, s41
	v_perm_b32 v181, v197, v196, s42
	v_perm_b32 v196, v116, v112, s41
	v_perm_b32 v197, v124, v120, s41
	v_perm_b32 v182, v197, v196, s42
	v_perm_b32 v196, v132, v128, s41
	v_perm_b32 v197, v140, v136, s41
	v_perm_b32 v183, v197, v196, s42
	v_perm_b32 v196, v85, v81, s41
	v_perm_b32 v197, v93, v89, s41
	v_perm_b32 v184, v197, v196, s42
	v_perm_b32 v196, v101, v97, s41
	v_perm_b32 v197, v109, v105, s41
	v_perm_b32 v185, v197, v196, s42
	v_perm_b32 v196, v117, v113, s41
	v_perm_b32 v197, v125, v121, s41
	v_perm_b32 v186, v197, v196, s42
	v_perm_b32 v196, v133, v129, s41
	v_perm_b32 v197, v141, v137, s41
	v_perm_b32 v187, v197, v196, s42
	v_perm_b32 v196, v86, v82, s41
	v_perm_b32 v197, v94, v90, s41
	v_perm_b32 v188, v197, v196, s42
	v_perm_b32 v196, v102, v98, s41
	v_perm_b32 v197, v110, v106, s41
	v_perm_b32 v189, v197, v196, s42
	v_perm_b32 v196, v118, v114, s41
	v_perm_b32 v197, v126, v122, s41
	v_perm_b32 v190, v197, v196, s42
	v_perm_b32 v196, v134, v130, s41
	v_perm_b32 v197, v142, v138, s41
	v_perm_b32 v191, v197, v196, s42
	v_perm_b32 v196, v87, v83, s41
	v_perm_b32 v197, v95, v91, s41
	v_perm_b32 v192, v197, v196, s42
	v_perm_b32 v196, v103, v99, s41
	v_perm_b32 v197, v111, v107, s41
	v_perm_b32 v193, v197, v196, s42
	v_perm_b32 v196, v119, v115, s41
	v_perm_b32 v197, v127, v123, s41
	v_perm_b32 v194, v197, v196, s42
	v_perm_b32 v196, v135, v131, s41
	v_perm_b32 v197, v143, v139, s41
	v_perm_b32 v195, v197, v196, s42
	ds_write_b128 v205, v[180:183] offset:0
	ds_write_b128 v205, v[184:187] offset:144
	ds_write_b128 v205, v[188:191] offset:288
	ds_write_b128 v205, v[192:195] offset:432
	s_mov_b32 s26, s61
	s_add_i32 s26, s26, s17
	s_mul_i32 s26, s26, 0x1000
	s_add_u32 s26, s26, s60
	s_add_u32 s54, s56, s26
	s_addc_u32 s55, s57, 0
	s_waitcnt lgkmcnt(0)
	s_barrier
	ds_read_b128 v[180:183], v206 offset:0
	ds_read_b128 v[184:187], v206 offset:1152
	ds_read_b128 v[188:191], v206 offset:2304
	ds_read_b128 v[192:195], v206 offset:3456
	s_waitcnt lgkmcnt(3)
	global_store_dwordx4 v207, v[180:183], s[54:55]
	s_add_u32 s54, s54, 0x8000
	s_addc_u32 s55, s55, 0
	s_waitcnt lgkmcnt(2)
	global_store_dwordx4 v207, v[184:187], s[54:55]
	s_add_u32 s54, s54, 0x8000
	s_addc_u32 s55, s55, 0
	s_waitcnt lgkmcnt(1)
	global_store_dwordx4 v207, v[188:191], s[54:55]
	s_add_u32 s54, s54, 0x8000
	s_addc_u32 s55, s55, 0
	s_waitcnt lgkmcnt(0)
	global_store_dwordx4 v207, v[192:195], s[54:55]
	s_mov_b32 s19, s64
	s_cmp_lt_u32 s19, 0x400
	s_cbranch_scc0 .Lf8t_win8a0_end
	s_add_i32 s64, s19, s96
	s_cmp_lt_u32 s64, 0x400
	s_cbranch_scc0 .Lf8t_win8a0_b_nonext
	s_mul_hi_u32 s20, s64, 0x8000000
	s_mul_i32 s21, s20, 32
	s_sub_i32 s21, s64, s21
	s_lshl_b32 s60, s20, 7
	s_lshl_b32 s61, s21, 8
	s_add_i32 s24, s60, s16
	s_mul_i32 s24, s24, 0x16b80
	s_lshl_b32 s25, s61, 2
	s_add_u32 s24, s24, s25
	s_add_u32 s52, s50, s24
	s_addc_u32 s53, s51, 0
	global_load_dwordx4 v[80:83], v204, s[52:53]
	s_add_u32 s52, s52, 0x16b80
	s_addc_u32 s53, s53, 0
	global_load_dwordx4 v[84:87], v204, s[52:53]
	s_add_u32 s52, s52, 0x16b80
	s_addc_u32 s53, s53, 0
	global_load_dwordx4 v[88:91], v204, s[52:53]
	s_add_u32 s52, s52, 0x16b80
	s_addc_u32 s53, s53, 0
	global_load_dwordx4 v[92:95], v204, s[52:53]
	s_add_u32 s52, s52, 0x16b80
	s_addc_u32 s53, s53, 0
	global_load_dwordx4 v[96:99], v204, s[52:53]
	s_add_u32 s52, s52, 0x16b80
	s_addc_u32 s53, s53, 0
	global_load_dwordx4 v[100:103], v204, s[52:53]
	s_add_u32 s52, s52, 0x16b80
	s_addc_u32 s53, s53, 0
	global_load_dwordx4 v[104:107], v204, s[52:53]
	s_add_u32 s52, s52, 0x16b80
	s_addc_u32 s53, s53, 0
	global_load_dwordx4 v[108:111], v204, s[52:53]
	s_add_u32 s52, s52, 0x16b80
	s_addc_u32 s53, s53, 0
	global_load_dwordx4 v[112:115], v204, s[52:53]
	s_add_u32 s52, s52, 0x16b80
	s_addc_u32 s53, s53, 0
	global_load_dwordx4 v[116:119], v204, s[52:53]
	s_add_u32 s52, s52, 0x16b80
	s_addc_u32 s53, s53, 0
	global_load_dwordx4 v[120:123], v204, s[52:53]
	s_add_u32 s52, s52, 0x16b80
	s_addc_u32 s53, s53, 0
	global_load_dwordx4 v[124:127], v204, s[52:53]
	s_add_u32 s52, s52, 0x16b80
	s_addc_u32 s53, s53, 0
	global_load_dwordx4 v[128:131], v204, s[52:53]
	s_add_u32 s52, s52, 0x16b80
	s_addc_u32 s53, s53, 0
	global_load_dwordx4 v[132:135], v204, s[52:53]
	s_add_u32 s52, s52, 0x16b80
	s_addc_u32 s53, s53, 0
	global_load_dwordx4 v[136:139], v204, s[52:53]
	s_add_u32 s52, s52, 0x16b80
	s_addc_u32 s53, s53, 0
	global_load_dwordx4 v[140:143], v204, s[52:53]
	s_waitcnt vmcnt(20)
	s_branch .Lf8t_win8a0_b_go

; __device__ __forceinline__ unsigned pk4_i8(float a, float b, float c, float d, float s) {
;     const unsigned ua = __float_as_uint(__builtin_amdgcn_fmed3f(a * s, -127.f, 127.f) + 12582912.f), ub = __float_as_uint(__builtin_amdgcn_fmed3f(b * s, -127.f, 127.f) + 12582912.f);
;     const unsigned uc = __float_as_uint(__builtin_amdgcn_fmed3f(c * s, -127.f, 127.f) + 12582912.f), ud = __float_as_uint(__builtin_amdgcn_fmed3f(d * s, -127.f, 127.f) + 12582912.f);
.Lf8t_win8a0_b_go:
	v_pk_mul_f32 v[16:17], v[16:17], s[36:37] op_sel_hi:[1,0]
	v_pk_mul_f32 v[18:19], v[18:19], s[36:37] op_sel_hi:[1,0]
	v_pk_mul_f32 v[20:21], v[20:21], s[36:37] op_sel_hi:[1,0]
	v_pk_mul_f32 v[22:23], v[22:23], s[36:37] op_sel_hi:[1,0]
	v_pk_mul_f32 v[24:25], v[24:25], s[36:37] op_sel_hi:[1,0]
	v_pk_mul_f32 v[26:27], v[26:27], s[36:37] op_sel_hi:[1,0]
	v_pk_mul_f32 v[28:29], v[28:29], s[36:37] op_sel_hi:[1,0]
	v_pk_mul_f32 v[30:31], v[30:31], s[36:37] op_sel_hi:[1,0]
	v_pk_mul_f32 v[32:33], v[32:33], s[36:37] op_sel_hi:[1,0]
	v_pk_mul_f32 v[34:35], v[34:35], s[36:37] op_sel_hi:[1,0]
	v_pk_mul_f32 v[36:37], v[36:37], s[36:37] op_sel_hi:[1,0]
	v_pk_mul_f32 v[38:39], v[38:39], s[36:37] op_sel_hi:[1,0]
	v_pk_mul_f32 v[40:41], v[40:41], s[36:37] op_sel_hi:[1,0]
	v_pk_mul_f32 v[42:43], v[42:43], s[36:37] op_sel_hi:[1,0]
	v_pk_mul_f32 v[44:45], v[44:45], s[36:37] op_sel_hi:[1,0]
	v_pk_mul_f32 v[46:47], v[46:47], s[36:37] op_sel_hi:[1,0]
	v_pk_mul_f32 v[48:49], v[48:49], s[36:37] op_sel_hi:[1,0]
	v_pk_mul_f32 v[50:51], v[50:51], s[36:37] op_sel_hi:[1,0]
	v_pk_mul_f32 v[52:53], v[52:53], s[36:37] op_sel_hi:[1,0]
	v_pk_mul_f32 v[54:55], v[54:55], s[36:37] op_sel_hi:[1,0]
	v_pk_mul_f32 v[56:57], v[56:57], s[36:37] op_sel_hi:[1,0]
	v_pk_mul_f32 v[58:59], v[58:59], s[36:37] op_sel_hi:[1,0]
	v_pk_mul_f32 v[60:61], v[60:61], s[36:37] op_sel_hi:[1,0]
	v_pk_mul_f32 v[62:63], v[62:63], s[36:37] op_sel_hi:[1,0]
	v_pk_mul_f32 v[64:65], v[64:65], s[36:37] op_sel_hi:[1,0]
	v_pk_mul_f32 v[66:67], v[66:67], s[36:37] op_sel_hi:[1,0]
	v_pk_mul_f32 v[68:69], v[68:69], s[36:37] op_sel_hi:[1,0]
	v_pk_mul_f32 v[70:71], v[70:71], s[36:37] op_sel_hi:[1,0]
	v_pk_mul_f32 v[144:145], v[144:145], s[36:37] op_sel_hi:[1,0]
	v_pk_mul_f32 v[146:147], v[146:147], s[36:37] op_sel_hi:[1,0]
	v_pk_mul_f32 v[148:149], v[148:149], s[36:37] op_sel_hi:[1,0]
	v_pk_mul_f32 v[150:151], v[150:151], s[36:37] op_sel_hi:[1,0]
	v_med3_f32 v16, v16, s40, v208
	v_med3_f32 v17, v17, s40, v208
	v_med3_f32 v18, v18, s40, v208
	v_med3_f32 v19, v19, s40, v208
	v_med3_f32 v20, v20, s40, v208
	v_med3_f32 v21, v21, s40, v208
	v_med3_f32 v22, v22, s40, v208
	v_med3_f32 v23, v23, s40, v208
	v_med3_f32 v24, v24, s40, v208
	v_med3_f32 v25, v25, s40, v208
	v_med3_f32 v26, v26, s40, v208
	v_med3_f32 v27, v27, s40, v208
	v_med3_f32 v28, v28, s40, v208
	v_med3_f32 v29, v29, s40, v208
	v_med3_f32 v30, v30, s40, v208
	v_med3_f32 v31, v31, s40, v208
	v_med3_f32 v32, v32, s40, v208
	v_med3_f32 v33, v33, s40, v208
	v_med3_f32 v34, v34, s40, v208
	v_med3_f32 v35, v35, s40, v208
	v_med3_f32 v36, v36, s40, v208
	v_med3_f32 v37, v37, s40, v208
	v_med3_f32 v38, v38, s40, v208
	v_med3_f32 v39, v39, s40, v208
	v_med3_f32 v40, v40, s40, v208
	v_med3_f32 v41, v41, s40, v208
	v_med3_f32 v42, v42, s40, v208
	v_med3_f32 v43, v43, s40, v208
	v_med3_f32 v44, v44, s40, v208
	v_med3_f32 v45, v45, s40, v208
	v_med3_f32 v46, v46, s40, v208
	v_med3_f32 v47, v47, s40, v208
	v_med3_f32 v48, v48, s40, v208
	v_med3_f32 v49, v49, s40, v208
	v_med3_f32 v50, v50, s40, v208
	v_med3_f32 v51, v51, s40, v208
	v_med3_f32 v52, v52, s40, v208
	v_med3_f32 v53, v53, s40, v208
	v_med3_f32 v54, v54, s40, v208
	v_med3_f32 v55, v55, s40, v208
	v_med3_f32 v56, v56, s40, v208
	v_med3_f32 v57, v57, s40, v208
	v_med3_f32 v58, v58, s40, v208
	v_med3_f32 v59, v59, s40, v208
	v_med3_f32 v60, v60, s40, v208
	v_med3_f32 v61, v61, s40, v208
	v_med3_f32 v62, v62, s40, v208
	v_med3_f32 v63, v63, s40, v208
	v_med3_f32 v64, v64, s40, v208
	v_med3_f32 v65, v65, s40, v208
	v_med3_f32 v66, v66, s40, v208
	v_med3_f32 v67, v67, s40, v208
	v_med3_f32 v68, v68, s40, v208
	v_med3_f32 v69, v69, s40, v208
	v_med3_f32 v70, v70, s40, v208
	v_med3_f32 v71, v71, s40, v208
	v_med3_f32 v144, v144, s40, v208
	v_med3_f32 v145, v145, s40, v208
	v_med3_f32 v146, v146, s40, v208
	v_med3_f32 v147, v147, s40, v208
	v_med3_f32 v148, v148, s40, v208
	v_med3_f32 v149, v149, s40, v208
	v_med3_f32 v150, v150, s40, v208
	v_med3_f32 v151, v151, s40, v208
	v_pk_add_f32 v[16:17], v[16:17], s[38:39] op_sel_hi:[1,0]
	v_pk_add_f32 v[18:19], v[18:19], s[38:39] op_sel_hi:[1,0]
	v_pk_add_f32 v[20:21], v[20:21], s[38:39] op_sel_hi:[1,0]
	v_pk_add_f32 v[22:23], v[22:23], s[38:39] op_sel_hi:[1,0]
	v_pk_add_f32 v[24:25], v[24:25], s[38:39] op_sel_hi:[1,0]
; #define LAS __attribute__((address_space(3)))
; __device__ __forceinline__ unsigned pk4_f8(float a, float b, float c, float d) { int w = __builtin_amdgcn_cvt_pk_fp8_f32(a, b, 0, false); w = __builtin_amdgcn_cvt_pk_fp8_f32(c, d, w, true); return (unsigned)w; }
; #define LDS_WAIT() asm volatile("s_waitcnt lgkmcnt(0)" ::: "memory")
; __device__ __forceinline__ unsigned pk4_i8(float a, float b, float c, float d, float s) {
;     ...
;     return (ua & 0xffu) | ((ub & 0xffu) << 8) | ((uc & 0xffu) << 16) | (ud << 24);
;     ...
;         for (int j = 0; j < 2; ++j) { const int n = (lane >> 2) + 16 * j; const LAS float* sp = scr + (16 * c) * 33 + n;
;             u32x4 o;
;             if (QI8) { o.x = pk4_i8(sp[0 * 33], sp[1 * 33], sp[2 * 33], sp[3 * 33], scl); o.y = pk4_i8(sp[4 * 33], sp[5 * 33], sp[6 * 33], sp[7 * 33], scl);
;                 o.z = pk4_i8(sp[8 * 33], sp[9 * 33], sp[10 * 33], sp[11 * 33], scl); o.w = pk4_i8(sp[12 * 33], sp[13 * 33], sp[14 * 33], sp[15 * 33], scl); }
;             else {
;             o.x = pk4_f8(sp[0 * 33] * scl, sp[1 * 33] * scl, sp[2 * 33] * scl, sp[3 * 33] * scl); o.y = pk4_f8(sp[4 * 33] * scl, sp[5 * 33] * scl, sp[6 * 33] * scl, sp[7 * 33] * scl);
;             o.z = pk4_f8(sp[8 * 33] * scl, sp[9 * 33] * scl, sp[10 * 33] * scl, sp[11 * 33] * scl); o.w = pk4_f8(sp[12 * 33] * scl, sp[13 * 33] * scl, sp[14 * 33] * scl, sp[15 * 33] * scl); }
;             *(u32x4*)(WT + (size_t)(dr0 + n) * K + k0 + 16 * c) = o; }
;         LDS_WAIT(); asm volatile("" ::: "memory"); }
	v_pk_add_f32 v[26:27], v[26:27], s[38:39] op_sel_hi:[1,0]
	v_pk_add_f32 v[28:29], v[28:29], s[38:39] op_sel_hi:[1,0]
	v_pk_add_f32 v[30:31], v[30:31], s[38:39] op_sel_hi:[1,0]
	v_pk_add_f32 v[32:33], v[32:33], s[38:39] op_sel_hi:[1,0]
	v_pk_add_f32 v[34:35], v[34:35], s[38:39] op_sel_hi:[1,0]
	v_pk_add_f32 v[36:37], v[36:37], s[38:39] op_sel_hi:[1,0]
	v_pk_add_f32 v[38:39], v[38:39], s[38:39] op_sel_hi:[1,0]
	v_pk_add_f32 v[40:41], v[40:41], s[38:39] op_sel_hi:[1,0]
	v_pk_add_f32 v[42:43], v[42:43], s[38:39] op_sel_hi:[1,0]
	v_pk_add_f32 v[44:45], v[44:45], s[38:39] op_sel_hi:[1,0]
	v_pk_add_f32 v[46:47], v[46:47], s[38:39] op_sel_hi:[1,0]
	v_pk_add_f32 v[48:49], v[48:49], s[38:39] op_sel_hi:[1,0]
	v_pk_add_f32 v[50:51], v[50:51], s[38:39] op_sel_hi:[1,0]
	v_pk_add_f32 v[52:53], v[52:53], s[38:39] op_sel_hi:[1,0]
	v_pk_add_f32 v[54:55], v[54:55], s[38:39] op_sel_hi:[1,0]
	v_pk_add_f32 v[56:57], v[56:57], s[38:39] op_sel_hi:[1,0]
	v_pk_add_f32 v[58:59], v[58:59], s[38:39] op_sel_hi:[1,0]
	v_pk_add_f32 v[60:61], v[60:61], s[38:39] op_sel_hi:[1,0]
	v_pk_add_f32 v[62:63], v[62:63], s[38:39] op_sel_hi:[1,0]
	v_pk_add_f32 v[64:65], v[64:65], s[38:39] op_sel_hi:[1,0]
	v_pk_add_f32 v[66:67], v[66:67], s[38:39] op_sel_hi:[1,0]
	v_pk_add_f32 v[68:69], v[68:69], s[38:39] op_sel_hi:[1,0]
	v_pk_add_f32 v[70:71], v[70:71], s[38:39] op_sel_hi:[1,0]
	v_pk_add_f32 v[144:145], v[144:145], s[38:39] op_sel_hi:[1,0]
	v_pk_add_f32 v[146:147], v[146:147], s[38:39] op_sel_hi:[1,0]
	v_pk_add_f32 v[148:149], v[148:149], s[38:39] op_sel_hi:[1,0]
	v_pk_add_f32 v[150:151], v[150:151], s[38:39] op_sel_hi:[1,0]
	v_perm_b32 v196, v20, v16, s41
	v_perm_b32 v197, v28, v24, s41
	v_perm_b32 v180, v197, v196, s42
	v_perm_b32 v196, v36, v32, s41
	v_perm_b32 v197, v44, v40, s41
	v_perm_b32 v181, v197, v196, s42
	v_perm_b32 v196, v52, v48, s41
	v_perm_b32 v197, v60, v56, s41
	v_perm_b32 v182, v197, v196, s42
	v_perm_b32 v196, v68, v64, s41
	v_perm_b32 v197, v148, v144, s41
	v_perm_b32 v183, v197, v196, s42
	v_perm_b32 v196, v21, v17, s41
	v_perm_b32 v197, v29, v25, s41
	v_perm_b32 v184, v197, v196, s42
	v_perm_b32 v196, v37, v33, s41
	v_perm_b32 v197, v45, v41, s41
	v_perm_b32 v185, v197, v196, s42
	v_perm_b32 v196, v53, v49, s41
	v_perm_b32 v197, v61, v57, s41
	v_perm_b32 v186, v197, v196, s42
	v_perm_b32 v196, v69, v65, s41
	v_perm_b32 v197, v149, v145, s41
	v_perm_b32 v187, v197, v196, s42
	v_perm_b32 v196, v22, v18, s41
	v_perm_b32 v197, v30, v26, s41
	v_perm_b32 v188, v197, v196, s42
	v_perm_b32 v196, v38, v34, s41
	v_perm_b32 v197, v46, v42, s41
	v_perm_b32 v189, v197, v196, s42
	v_perm_b32 v196, v54, v50, s41
	v_perm_b32 v197, v62, v58, s41
	v_perm_b32 v190, v197, v196, s42
	v_perm_b32 v196, v70, v66, s41
	v_perm_b32 v197, v150, v146, s41
	v_perm_b32 v191, v197, v196, s42
	v_perm_b32 v196, v23, v19, s41
	v_perm_b32 v197, v31, v27, s41
	v_perm_b32 v192, v197, v196, s42
	v_perm_b32 v196, v39, v35, s41
	v_perm_b32 v197, v47, v43, s41
	v_perm_b32 v193, v197, v196, s42
	v_perm_b32 v196, v55, v51, s41
	v_perm_b32 v197, v63, v59, s41
	v_perm_b32 v194, v197, v196, s42
	v_perm_b32 v196, v71, v67, s41
	v_perm_b32 v197, v151, v147, s41
	v_perm_b32 v195, v197, v196, s42
	ds_write_b128 v205, v[180:183] offset:36864
	ds_write_b128 v205, v[184:187] offset:37008
	ds_write_b128 v205, v[188:191] offset:37152
	ds_write_b128 v205, v[192:195] offset:37296
	s_mov_b32 s26, s63
	s_add_i32 s26, s26, s17
	s_mul_i32 s26, s26, 0x1000
	s_add_u32 s26, s26, s62
	s_add_u32 s54, s56, s26
	s_addc_u32 s55, s57, 0
	s_waitcnt lgkmcnt(0)
	s_barrier
	ds_read_b128 v[180:183], v206 offset:36864
	ds_read_b128 v[184:187], v206 offset:38016
	ds_read_b128 v[188:191], v206 offset:39168
	ds_read_b128 v[192:195], v206 offset:40320
	s_waitcnt lgkmcnt(3)
	global_store_dwordx4 v207, v[180:183], s[54:55]
	s_add_u32 s54, s54, 0x8000
	s_addc_u32 s55, s55, 0
	s_waitcnt lgkmcnt(2)
	global_store_dwordx4 v207, v[184:187], s[54:55]
	s_add_u32 s54, s54, 0x8000
	s_addc_u32 s55, s55, 0
	s_waitcnt lgkmcnt(1)
	global_store_dwordx4 v207, v[188:191], s[54:55]
	s_add_u32 s54, s54, 0x8000
	s_addc_u32 s55, s55, 0
	s_waitcnt lgkmcnt(0)
	global_store_dwordx4 v207, v[192:195], s[54:55]
	s_mov_b32 s19, s64
	s_cmp_lt_u32 s19, 0x400
	s_cbranch_scc1 .Lf8t_win8a0_loop

; #define LAS __attribute__((address_space(3)))
;     if (ldw == 0) ldw = N;
;     LAS float* scr = (LAS float*)(F.lds + F.wave * 16384); const int lane = F.lane;
;     const int nblk = N / 32, nitems = (K / 64) * nblk;
;     for (int item = F.gw; item < nitems; item += F.NGW) { const int kb = item / nblk, nb = item % nblk, k0 = 64 * kb, n0 = 32 * nb;
;         int dr0 = n0; if (MAP == 1) { if (n0 < DFF) dr0 = (n0 >> 7) * 256 + (n0 & 127); else { const int uo = n0 - DFF; dr0 = (uo >> 7) * 256 + 128 + (uo & 127); } }
; #pragma unroll 8
;         for (int i = 0; i < 32; ++i) { const int kk = 2 * i + (lane >> 5); scr[kk * 33 + (lane & 31)] = W[(size_t)(k0 + kk) * ldw + n0 + (lane & 31)]; }
; __device__ __forceinline__ void p0_prologue(Frame& F) {
;     ...
;       transpose_f8_matrix<0, true>(F, W, D, 2048, w8 + (size_t)8192 * D, I8_W, ldw);
.LBB0_42:
	s_cmpk_lt_i32 s94, 0x1000
	s_cselect_b64 s[4:5], -1, 0
	s_cmpk_gt_i32 s94, 0xfff
	s_cbranch_scc1 .LBB0_55
	s_barrier
	s_load_dwordx2 s[50:51], s[74:75], 0x58
	v_readlane_b32 s16, v240, 2
	v_lshlrev_b32_e32 v204, 4, v178
	v_mov_b32_e32 v208, 0x42fe0000
	s_mov_b32 s36, 0x44fe0000
	s_mov_b32 s37, 0
	s_mov_b32 s38, 0x4b400000
	s_mov_b32 s39, 0
	s_mov_b32 s40, 0xc2fe0000
	s_mov_b32 s41, 0x0c0c0400
	s_mov_b32 s42, 0x05040100
	s_lshl_b32 s17, s16, 5
	v_mul_u32_u24_e32 v205, 0x240, v178
	s_lshl_b32 s18, s16, 4
	v_add_u32_e32 v205, s18, v205
	v_lshrrev_b32_e32 v196, 3, v178
	v_and_b32_e32 v197, 7, v178
	s_lshl_b32 s18, s16, 5
	v_add_u32_e32 v198, s18, v196
	v_mul_u32_u24_e32 v206, 0x90, v198
	v_lshl_add_u32 v206, v197, 4, v206
	v_mul_u32_u24_e32 v207, 0x1000, v196
	v_lshl_add_u32 v207, v197, 4, v207
	s_lshl_b32 s16, s16, 4
	s_waitcnt lgkmcnt(0)
	s_add_u32 s56, s90, 0x37b00000
	s_addc_u32 s57, s91, 0
	s_mov_b32 s19, s2
	s_cmp_lt_u32 s19, 0x100
	s_cbranch_scc0 .Lf8t_win8bcd0_end
	s_mul_hi_u32 s20, s19, 0x20000000
	s_mul_i32 s21, s20, 8
	s_sub_i32 s21, s19, s21
	s_lshl_b32 s60, s20, 7
	s_lshl_b32 s61, s21, 8
	s_add_i32 s24, s60, s16
	s_mul_i32 s24, s24, 0x16b80
	s_lshl_b32 s25, s61, 2
	s_add_u32 s24, s24, s25
	s_add_u32 s52, s50, s24
	s_addc_u32 s53, s51, 0
	global_load_dwordx4 v[80:83], v204, s[52:53]
	s_add_u32 s52, s52, 0x16b80
	s_addc_u32 s53, s53, 0
	global_load_dwordx4 v[84:87], v204, s[52:53]
	s_add_u32 s52, s52, 0x16b80
	s_addc_u32 s53, s53, 0
	global_load_dwordx4 v[88:91], v204, s[52:53]
	s_add_u32 s52, s52, 0x16b80
	s_addc_u32 s53, s53, 0
	global_load_dwordx4 v[92:95], v204, s[52:53]
	s_add_u32 s52, s52, 0x16b80
	s_addc_u32 s53, s53, 0
	global_load_dwordx4 v[96:99], v204, s[52:53]
	s_add_u32 s52, s52, 0x16b80
	s_addc_u32 s53, s53, 0
	global_load_dwordx4 v[100:103], v204, s[52:53]
	s_add_u32 s52, s52, 0x16b80
	s_addc_u32 s53, s53, 0
	global_load_dwordx4 v[104:107], v204, s[52:53]
	s_add_u32 s52, s52, 0x16b80
	s_addc_u32 s53, s53, 0
	global_load_dwordx4 v[108:111], v204, s[52:53]
	s_add_u32 s52, s52, 0x16b80
	s_addc_u32 s53, s53, 0
	global_load_dwordx4 v[112:115], v204, s[52:53]
	s_add_u32 s52, s52, 0x16b80
	s_addc_u32 s53, s53, 0
	global_load_dwordx4 v[116:119], v204, s[52:53]
	s_add_u32 s52, s52, 0x16b80
	s_addc_u32 s53, s53, 0
	global_load_dwordx4 v[120:123], v204, s[52:53]
	s_add_u32 s52, s52, 0x16b80
	s_addc_u32 s53, s53, 0
	global_load_dwordx4 v[124:127], v204, s[52:53]
	s_add_u32 s52, s52, 0x16b80
	s_addc_u32 s53, s53, 0
	global_load_dwordx4 v[128:131], v204, s[52:53]
	s_add_u32 s52, s52, 0x16b80
	s_addc_u32 s53, s53, 0
	global_load_dwordx4 v[132:135], v204, s[52:53]
	s_add_u32 s52, s52, 0x16b80
	s_addc_u32 s53, s53, 0
	global_load_dwordx4 v[136:139], v204, s[52:53]
	s_add_u32 s52, s52, 0x16b80
	s_addc_u32 s53, s53, 0
	global_load_dwordx4 v[140:143], v204, s[52:53]
	s_mov_b32 s58, 1
.Lf8t_win8bcd0_loop:
	s_add_i32 s64, s19, s96
	s_cmp_lt_u32 s64, 0x100
	s_cbranch_scc0 .Lf8t_win8bcd0_a_nonext
	s_mul_hi_u32 s20, s64, 0x20000000
	s_mul_i32 s21, s20, 8
	s_sub_i32 s21, s64, s21
	s_lshl_b32 s62, s20, 7
	s_lshl_b32 s63, s21, 8
	s_add_i32 s24, s62, s16
	s_mul_i32 s24, s24, 0x16b80
	s_lshl_b32 s25, s63, 2
	s_add_u32 s24, s24, s25
	s_add_u32 s52, s50, s24
	s_addc_u32 s53, s51, 0
	global_load_dwordx4 v[16:19], v204, s[52:53]
	s_add_u32 s52, s52, 0x16b80
	s_addc_u32 s53, s53, 0
	global_load_dwordx4 v[20:23], v204, s[52:53]
	s_add_u32 s52, s52, 0x16b80
	s_addc_u32 s53, s53, 0
	global_load_dwordx4 v[24:27], v204, s[52:53]
	s_add_u32 s52, s52, 0x16b80
	s_addc_u32 s53, s53, 0
	global_load_dwordx4 v[28:31], v204, s[52:53]
	s_add_u32 s52, s52, 0x16b80
	s_addc_u32 s53, s53, 0
	global_load_dwordx4 v[32:35], v204, s[52:53]
	s_add_u32 s52, s52, 0x16b80
	s_addc_u32 s53, s53, 0
	global_load_dwordx4 v[36:39], v204, s[52:53]
	s_add_u32 s52, s52, 0x16b80
	s_addc_u32 s53, s53, 0
	global_load_dwordx4 v[40:43], v204, s[52:53]
	s_add_u32 s52, s52, 0x16b80
	s_addc_u32 s53, s53, 0
	global_load_dwordx4 v[44:47], v204, s[52:53]
	s_add_u32 s52, s52, 0x16b80
	s_addc_u32 s53, s53, 0
	global_load_dwordx4 v[48:51], v204, s[52:53]
	s_add_u32 s52, s52, 0x16b80
	s_addc_u32 s53, s53, 0
	global_load_dwordx4 v[52:55], v204, s[52:53]
	s_add_u32 s52, s52, 0x16b80
	s_addc_u32 s53, s53, 0
	global_load_dwordx4 v[56:59], v204, s[52:53]
	s_add_u32 s52, s52, 0x16b80
	s_addc_u32 s53, s53, 0
	global_load_dwordx4 v[60:63], v204, s[52:53]
	s_add_u32 s52, s52, 0x16b80
	s_addc_u32 s53, s53, 0
	global_load_dwordx4 v[64:67], v204, s[52:53]
	s_add_u32 s52, s52, 0x16b80
	s_addc_u32 s53, s53, 0
	global_load_dwordx4 v[68:71], v204, s[52:53]
	s_add_u32 s52, s52, 0x16b80
	s_addc_u32 s53, s53, 0
	global_load_dwordx4 v[144:147], v204, s[52:53]
	s_add_u32 s52, s52, 0x16b80
	s_addc_u32 s53, s53, 0
	global_load_dwordx4 v[148:151], v204, s[52:53]
	s_cmp_eq_u32 s58, 1
	s_cbranch_scc1 .Lf8t_win8bcd0_a_first
	s_waitcnt vmcnt(20)
	s_branch .Lf8t_win8bcd0_a_go

; __device__ __forceinline__ unsigned pk4_i8(float a, float b, float c, float d, float s) {
;     const unsigned ua = __float_as_uint(__builtin_amdgcn_fmed3f(a * s, -127.f, 127.f) + 12582912.f), ub = __float_as_uint(__builtin_amdgcn_fmed3f(b * s, -127.f, 127.f) + 12582912.f);
;     const unsigned uc = __float_as_uint(__builtin_amdgcn_fmed3f(c * s, -127.f, 127.f) + 12582912.f), ud = __float_as_uint(__builtin_amdgcn_fmed3f(d * s, -127.f, 127.f) + 12582912.f);
.Lf8t_win8bcd0_a_go:
	s_mov_b32 s58, 0
	v_pk_mul_f32 v[80:81], v[80:81], s[36:37] op_sel_hi:[1,0]
	v_pk_mul_f32 v[82:83], v[82:83], s[36:37] op_sel_hi:[1,0]
	v_pk_mul_f32 v[84:85], v[84:85], s[36:37] op_sel_hi:[1,0]
	v_pk_mul_f32 v[86:87], v[86:87], s[36:37] op_sel_hi:[1,0]
	v_pk_mul_f32 v[88:89], v[88:89], s[36:37] op_sel_hi:[1,0]
	v_pk_mul_f32 v[90:91], v[90:91], s[36:37] op_sel_hi:[1,0]
	v_pk_mul_f32 v[92:93], v[92:93], s[36:37] op_sel_hi:[1,0]
	v_pk_mul_f32 v[94:95], v[94:95], s[36:37] op_sel_hi:[1,0]
	v_pk_mul_f32 v[96:97], v[96:97], s[36:37] op_sel_hi:[1,0]
	v_pk_mul_f32 v[98:99], v[98:99], s[36:37] op_sel_hi:[1,0]
	v_pk_mul_f32 v[100:101], v[100:101], s[36:37] op_sel_hi:[1,0]
	v_pk_mul_f32 v[102:103], v[102:103], s[36:37] op_sel_hi:[1,0]
	v_pk_mul_f32 v[104:105], v[104:105], s[36:37] op_sel_hi:[1,0]
	v_pk_mul_f32 v[106:107], v[106:107], s[36:37] op_sel_hi:[1,0]
	v_pk_mul_f32 v[108:109], v[108:109], s[36:37] op_sel_hi:[1,0]
	v_pk_mul_f32 v[110:111], v[110:111], s[36:37] op_sel_hi:[1,0]
	v_pk_mul_f32 v[112:113], v[112:113], s[36:37] op_sel_hi:[1,0]
	v_pk_mul_f32 v[114:115], v[114:115], s[36:37] op_sel_hi:[1,0]
	v_pk_mul_f32 v[116:117], v[116:117], s[36:37] op_sel_hi:[1,0]
	v_pk_mul_f32 v[118:119], v[118:119], s[36:37] op_sel_hi:[1,0]
	v_pk_mul_f32 v[120:121], v[120:121], s[36:37] op_sel_hi:[1,0]
	v_pk_mul_f32 v[122:123], v[122:123], s[36:37] op_sel_hi:[1,0]
	v_pk_mul_f32 v[124:125], v[124:125], s[36:37] op_sel_hi:[1,0]
	v_pk_mul_f32 v[126:127], v[126:127], s[36:37] op_sel_hi:[1,0]
	v_pk_mul_f32 v[128:129], v[128:129], s[36:37] op_sel_hi:[1,0]
	v_pk_mul_f32 v[130:131], v[130:131], s[36:37] op_sel_hi:[1,0]
	v_pk_mul_f32 v[132:133], v[132:133], s[36:37] op_sel_hi:[1,0]
	v_pk_mul_f32 v[134:135], v[134:135], s[36:37] op_sel_hi:[1,0]
	v_pk_mul_f32 v[136:137], v[136:137], s[36:37] op_sel_hi:[1,0]
	v_pk_mul_f32 v[138:139], v[138:139], s[36:37] op_sel_hi:[1,0]
	v_pk_mul_f32 v[140:141], v[140:141], s[36:37] op_sel_hi:[1,0]
	v_pk_mul_f32 v[142:143], v[142:143], s[36:37] op_sel_hi:[1,0]
	v_med3_f32 v80, v80, s40, v208
	v_med3_f32 v81, v81, s40, v208
	v_med3_f32 v82, v82, s40, v208
	v_med3_f32 v83, v83, s40, v208
	v_med3_f32 v84, v84, s40, v208
	v_med3_f32 v85, v85, s40, v208
	v_med3_f32 v86, v86, s40, v208
	v_med3_f32 v87, v87, s40, v208
	v_med3_f32 v88, v88, s40, v208
	v_med3_f32 v89, v89, s40, v208
	v_med3_f32 v90, v90, s40, v208
	v_med3_f32 v91, v91, s40, v208
	v_med3_f32 v92, v92, s40, v208
	v_med3_f32 v93, v93, s40, v208
	v_med3_f32 v94, v94, s40, v208
	v_med3_f32 v95, v95, s40, v208
	v_med3_f32 v96, v96, s40, v208
	v_med3_f32 v97, v97, s40, v208
	v_med3_f32 v98, v98, s40, v208
	v_med3_f32 v99, v99, s40, v208
	v_med3_f32 v100, v100, s40, v208
	v_med3_f32 v101, v101, s40, v208
	v_med3_f32 v102, v102, s40, v208
	v_med3_f32 v103, v103, s40, v208
	v_med3_f32 v104, v104, s40, v208
	v_med3_f32 v105, v105, s40, v208
	v_med3_f32 v106, v106, s40, v208
	v_med3_f32 v107, v107, s40, v208
	v_med3_f32 v108, v108, s40, v208
	v_med3_f32 v109, v109, s40, v208
	v_med3_f32 v110, v110, s40, v208
	v_med3_f32 v111, v111, s40, v208
	v_med3_f32 v112, v112, s40, v208
	v_med3_f32 v113, v113, s40, v208
	v_med3_f32 v114, v114, s40, v208
	v_med3_f32 v115, v115, s40, v208
	v_med3_f32 v116, v116, s40, v208
	v_med3_f32 v117, v117, s40, v208
	v_med3_f32 v118, v118, s40, v208
	v_med3_f32 v119, v119, s40, v208
	v_med3_f32 v120, v120, s40, v208
	v_med3_f32 v121, v121, s40, v208
	v_med3_f32 v122, v122, s40, v208
	v_med3_f32 v123, v123, s40, v208
	v_med3_f32 v124, v124, s40, v208
	v_med3_f32 v125, v125, s40, v208
	v_med3_f32 v126, v126, s40, v208
	v_med3_f32 v127, v127, s40, v208
	v_med3_f32 v128, v128, s40, v208
	v_med3_f32 v129, v129, s40, v208
	v_med3_f32 v130, v130, s40, v208
	v_med3_f32 v131, v131, s40, v208
	v_med3_f32 v132, v132, s40, v208
	v_med3_f32 v133, v133, s40, v208
	v_med3_f32 v134, v134, s40, v208
	v_med3_f32 v135, v135, s40, v208
	v_med3_f32 v136, v136, s40, v208
	v_med3_f32 v137, v137, s40, v208
	v_med3_f32 v138, v138, s40, v208
	v_med3_f32 v139, v139, s40, v208
	v_med3_f32 v140, v140, s40, v208
	v_med3_f32 v141, v141, s40, v208
	v_med3_f32 v142, v142, s40, v208
	v_med3_f32 v143, v143, s40, v208
	v_pk_add_f32 v[80:81], v[80:81], s[38:39] op_sel_hi:[1,0]
	v_pk_add_f32 v[82:83], v[82:83], s[38:39] op_sel_hi:[1,0]
	v_pk_add_f32 v[84:85], v[84:85], s[38:39] op_sel_hi:[1,0]
	v_pk_add_f32 v[86:87], v[86:87], s[38:39] op_sel_hi:[1,0]
	v_pk_add_f32 v[88:89], v[88:89], s[38:39] op_sel_hi:[1,0]
	v_pk_add_f32 v[90:91], v[90:91], s[38:39] op_sel_hi:[1,0]
	v_pk_add_f32 v[92:93], v[92:93], s[38:39] op_sel_hi:[1,0]
	v_pk_add_f32 v[94:95], v[94:95], s[38:39] op_sel_hi:[1,0]
	v_pk_add_f32 v[96:97], v[96:97], s[38:39] op_sel_hi:[1,0]
	v_pk_add_f32 v[98:99], v[98:99], s[38:39] op_sel_hi:[1,0]
	v_pk_add_f32 v[100:101], v[100:101], s[38:39] op_sel_hi:[1,0]
	v_pk_add_f32 v[102:103], v[102:103], s[38:39] op_sel_hi:[1,0]
	v_pk_add_f32 v[104:105], v[104:105], s[38:39] op_sel_hi:[1,0]
	v_pk_add_f32 v[106:107], v[106:107], s[38:39] op_sel_hi:[1,0]
	v_pk_add_f32 v[108:109], v[108:109], s[38:39] op_sel_hi:[1,0]
	v_pk_add_f32 v[110:111], v[110:111], s[38:39] op_sel_hi:[1,0]
	v_pk_add_f32 v[112:113], v[112:113], s[38:39] op_sel_hi:[1,0]
	v_pk_add_f32 v[114:115], v[114:115], s[38:39] op_sel_hi:[1,0]
	v_pk_add_f32 v[116:117], v[116:117], s[38:39] op_sel_hi:[1,0]
	v_pk_add_f32 v[118:119], v[118:119], s[38:39] op_sel_hi:[1,0]
; #define LAS __attribute__((address_space(3)))
; __device__ __forceinline__ unsigned pk4_f8(float a, float b, float c, float d) { int w = __builtin_amdgcn_cvt_pk_fp8_f32(a, b, 0, false); w = __builtin_amdgcn_cvt_pk_fp8_f32(c, d, w, true); return (unsigned)w; }
; #define LDS_WAIT() asm volatile("s_waitcnt lgkmcnt(0)" ::: "memory")
;     ...
;     for (int item = F.gw; item < nitems; item += F.NGW) { const int kb = item / nblk, nb = item % nblk, k0 = 64 * kb, n0 = 32 * nb;
;         int dr0 = n0; if (MAP == 1) { if (n0 < DFF) dr0 = (n0 >> 7) * 256 + (n0 & 127); else { const int uo = n0 - DFF; dr0 = (uo >> 7) * 256 + 128 + (uo & 127); } }
; #pragma unroll 8
;         for (int i = 0; i < 32; ++i) { const int kk = 2 * i + (lane >> 5); scr[kk * 33 + (lane & 31)] = W[(size_t)(k0 + kk) * ldw + n0 + (lane & 31)]; }
;         LDS_WAIT(); asm volatile("" ::: "memory");
;         const int c = lane & 3;
; #pragma unroll
;         for (int j = 0; j < 2; ++j) { const int n = (lane >> 2) + 16 * j; const LAS float* sp = scr + (16 * c) * 33 + n;
;             u32x4 o;
;             if (QI8) { o.x = pk4_i8(sp[0 * 33], sp[1 * 33], sp[2 * 33], sp[3 * 33], scl); o.y = pk4_i8(sp[4 * 33], sp[5 * 33], sp[6 * 33], sp[7 * 33], scl);
;                 o.z = pk4_i8(sp[8 * 33], sp[9 * 33], sp[10 * 33], sp[11 * 33], scl); o.w = pk4_i8(sp[12 * 33], sp[13 * 33], sp[14 * 33], sp[15 * 33], scl); }
;             else {
;             o.x = pk4_f8(sp[0 * 33] * scl, sp[1 * 33] * scl, sp[2 * 33] * scl, sp[3 * 33] * scl); o.y = pk4_f8(sp[4 * 33] * scl, sp[5 * 33] * scl, sp[6 * 33] * scl, sp[7 * 33] * scl);
;             o.z = pk4_f8(sp[8 * 33] * scl, sp[9 * 33] * scl, sp[10 * 33] * scl, sp[11 * 33] * scl); o.w = pk4_f8(sp[12 * 33] * scl, sp[13 * 33] * scl, sp[14 * 33] * scl, sp[15 * 33] * scl); }
;             *(u32x4*)(WT + (size_t)(dr0 + n) * K + k0 + 16 * c) = o; }
	v_pk_add_f32 v[120:121], v[120:121], s[38:39] op_sel_hi:[1,0]
	v_pk_add_f32 v[122:123], v[122:123], s[38:39] op_sel_hi:[1,0]
	v_pk_add_f32 v[124:125], v[124:125], s[38:39] op_sel_hi:[1,0]
	v_pk_add_f32 v[126:127], v[126:127], s[38:39] op_sel_hi:[1,0]
	v_pk_add_f32 v[128:129], v[128:129], s[38:39] op_sel_hi:[1,0]
	v_pk_add_f32 v[130:131], v[130:131], s[38:39] op_sel_hi:[1,0]
	v_pk_add_f32 v[132:133], v[132:133], s[38:39] op_sel_hi:[1,0]
	v_pk_add_f32 v[134:135], v[134:135], s[38:39] op_sel_hi:[1,0]
	v_pk_add_f32 v[136:137], v[136:137], s[38:39] op_sel_hi:[1,0]
	v_pk_add_f32 v[138:139], v[138:139], s[38:39] op_sel_hi:[1,0]
	v_pk_add_f32 v[140:141], v[140:141], s[38:39] op_sel_hi:[1,0]
	v_pk_add_f32 v[142:143], v[142:143], s[38:39] op_sel_hi:[1,0]
	v_perm_b32 v196, v84, v80, s41
	v_perm_b32 v197, v92, v88, s41
	v_perm_b32 v180, v197, v196, s42
	v_perm_b32 v196, v100, v96, s41
	v_perm_b32 v197, v108, v104, s41
	v_perm_b32 v181, v197, v196, s42
	v_perm_b32 v196, v116, v112, s41
	v_perm_b32 v197, v124, v120, s41
	v_perm_b32 v182, v197, v196, s42
	v_perm_b32 v196, v132, v128, s41
	v_perm_b32 v197, v140, v136, s41
	v_perm_b32 v183, v197, v196, s42
	v_perm_b32 v196, v85, v81, s41
	v_perm_b32 v197, v93, v89, s41
	v_perm_b32 v184, v197, v196, s42
	v_perm_b32 v196, v101, v97, s41
	v_perm_b32 v197, v109, v105, s41
	v_perm_b32 v185, v197, v196, s42
	v_perm_b32 v196, v117, v113, s41
	v_perm_b32 v197, v125, v121, s41
	v_perm_b32 v186, v197, v196, s42
	v_perm_b32 v196, v133, v129, s41
	v_perm_b32 v197, v141, v137, s41
	v_perm_b32 v187, v197, v196, s42
	v_perm_b32 v196, v86, v82, s41
	v_perm_b32 v197, v94, v90, s41
	v_perm_b32 v188, v197, v196, s42
	v_perm_b32 v196, v102, v98, s41
	v_perm_b32 v197, v110, v106, s41
	v_perm_b32 v189, v197, v196, s42
	v_perm_b32 v196, v118, v114, s41
	v_perm_b32 v197, v126, v122, s41
	v_perm_b32 v190, v197, v196, s42
	v_perm_b32 v196, v134, v130, s41
	v_perm_b32 v197, v142, v138, s41
	v_perm_b32 v191, v197, v196, s42
	v_perm_b32 v196, v87, v83, s41
	v_perm_b32 v197, v95, v91, s41
	v_perm_b32 v192, v197, v196, s42
	v_perm_b32 v196, v103, v99, s41
	v_perm_b32 v197, v111, v107, s41
	v_perm_b32 v193, v197, v196, s42
	v_perm_b32 v196, v119, v115, s41
	v_perm_b32 v197, v127, v123, s41
	v_perm_b32 v194, v197, v196, s42
	v_perm_b32 v196, v135, v131, s41
	v_perm_b32 v197, v143, v139, s41
	v_perm_b32 v195, v197, v196, s42
	ds_write_b128 v205, v[180:183] offset:0
	ds_write_b128 v205, v[184:187] offset:144
	ds_write_b128 v205, v[188:191] offset:288
	ds_write_b128 v205, v[192:195] offset:432
	s_mov_b32 s26, s61
	s_add_i32 s26, s26, s17
	s_mul_i32 s26, s26, 0x1000
	s_add_u32 s26, s26, s60
	s_add_u32 s54, s56, s26
	s_addc_u32 s55, s57, 0
	s_waitcnt lgkmcnt(0)
	s_barrier
	ds_read_b128 v[180:183], v206 offset:0
	ds_read_b128 v[184:187], v206 offset:1152
	ds_read_b128 v[188:191], v206 offset:2304
	ds_read_b128 v[192:195], v206 offset:3456
	s_waitcnt lgkmcnt(3)
	global_store_dwordx4 v207, v[180:183], s[54:55]
	s_add_u32 s54, s54, 0x8000
	s_addc_u32 s55, s55, 0
	s_waitcnt lgkmcnt(2)
	global_store_dwordx4 v207, v[184:187], s[54:55]
	s_add_u32 s54, s54, 0x8000
	s_addc_u32 s55, s55, 0
	s_waitcnt lgkmcnt(1)
	global_store_dwordx4 v207, v[188:191], s[54:55]
	s_add_u32 s54, s54, 0x8000
	s_addc_u32 s55, s55, 0
	s_waitcnt lgkmcnt(0)
	global_store_dwordx4 v207, v[192:195], s[54:55]
	s_mov_b32 s19, s64
	s_cmp_lt_u32 s19, 0x100
	s_cbranch_scc0 .Lf8t_win8bcd0_end
	s_add_i32 s64, s19, s96
	s_cmp_lt_u32 s64, 0x100
	s_cbranch_scc0 .Lf8t_win8bcd0_b_nonext
	s_mul_hi_u32 s20, s64, 0x20000000
	s_mul_i32 s21, s20, 8
	s_sub_i32 s21, s64, s21
	s_lshl_b32 s60, s20, 7
	s_lshl_b32 s61, s21, 8
	s_add_i32 s24, s60, s16
	s_mul_i32 s24, s24, 0x16b80
	s_lshl_b32 s25, s61, 2
	s_add_u32 s24, s24, s25
	s_add_u32 s52, s50, s24
	s_addc_u32 s53, s51, 0
	global_load_dwordx4 v[80:83], v204, s[52:53]
	s_add_u32 s52, s52, 0x16b80
	s_addc_u32 s53, s53, 0
	global_load_dwordx4 v[84:87], v204, s[52:53]
	s_add_u32 s52, s52, 0x16b80
	s_addc_u32 s53, s53, 0
	global_load_dwordx4 v[88:91], v204, s[52:53]
	s_add_u32 s52, s52, 0x16b80
	s_addc_u32 s53, s53, 0
	global_load_dwordx4 v[92:95], v204, s[52:53]
	s_add_u32 s52, s52, 0x16b80
	s_addc_u32 s53, s53, 0
	global_load_dwordx4 v[96:99], v204, s[52:53]
	s_add_u32 s52, s52, 0x16b80
	s_addc_u32 s53, s53, 0
	global_load_dwordx4 v[100:103], v204, s[52:53]
	s_add_u32 s52, s52, 0x16b80
	s_addc_u32 s53, s53, 0
	global_load_dwordx4 v[104:107], v204, s[52:53]
	s_add_u32 s52, s52, 0x16b80
	s_addc_u32 s53, s53, 0
	global_load_dwordx4 v[108:111], v204, s[52:53]
	s_add_u32 s52, s52, 0x16b80
	s_addc_u32 s53, s53, 0
	global_load_dwordx4 v[112:115], v204, s[52:53]
	s_add_u32 s52, s52, 0x16b80
	s_addc_u32 s53, s53, 0
	global_load_dwordx4 v[116:119], v204, s[52:53]
	s_add_u32 s52, s52, 0x16b80
	s_addc_u32 s53, s53, 0
	global_load_dwordx4 v[120:123], v204, s[52:53]
	s_add_u32 s52, s52, 0x16b80
	s_addc_u32 s53, s53, 0
	global_load_dwordx4 v[124:127], v204, s[52:53]
	s_add_u32 s52, s52, 0x16b80
	s_addc_u32 s53, s53, 0
	global_load_dwordx4 v[128:131], v204, s[52:53]
	s_add_u32 s52, s52, 0x16b80
	s_addc_u32 s53, s53, 0
	global_load_dwordx4 v[132:135], v204, s[52:53]
	s_add_u32 s52, s52, 0x16b80
	s_addc_u32 s53, s53, 0
	global_load_dwordx4 v[136:139], v204, s[52:53]
	s_add_u32 s52, s52, 0x16b80
	s_addc_u32 s53, s53, 0
	global_load_dwordx4 v[140:143], v204, s[52:53]
	s_waitcnt vmcnt(20)
	s_branch .Lf8t_win8bcd0_b_go

; __device__ __forceinline__ unsigned pk4_i8(float a, float b, float c, float d, float s) {
;     const unsigned ua = __float_as_uint(__builtin_amdgcn_fmed3f(a * s, -127.f, 127.f) + 12582912.f), ub = __float_as_uint(__builtin_amdgcn_fmed3f(b * s, -127.f, 127.f) + 12582912.f);
;     const unsigned uc = __float_as_uint(__builtin_amdgcn_fmed3f(c * s, -127.f, 127.f) + 12582912.f), ud = __float_as_uint(__builtin_amdgcn_fmed3f(d * s, -127.f, 127.f) + 12582912.f);
.Lf8t_win8bcd0_b_go:
	v_pk_mul_f32 v[16:17], v[16:17], s[36:37] op_sel_hi:[1,0]
	v_pk_mul_f32 v[18:19], v[18:19], s[36:37] op_sel_hi:[1,0]
	v_pk_mul_f32 v[20:21], v[20:21], s[36:37] op_sel_hi:[1,0]
	v_pk_mul_f32 v[22:23], v[22:23], s[36:37] op_sel_hi:[1,0]
	v_pk_mul_f32 v[24:25], v[24:25], s[36:37] op_sel_hi:[1,0]
	v_pk_mul_f32 v[26:27], v[26:27], s[36:37] op_sel_hi:[1,0]
	v_pk_mul_f32 v[28:29], v[28:29], s[36:37] op_sel_hi:[1,0]
	v_pk_mul_f32 v[30:31], v[30:31], s[36:37] op_sel_hi:[1,0]
	v_pk_mul_f32 v[32:33], v[32:33], s[36:37] op_sel_hi:[1,0]
	v_pk_mul_f32 v[34:35], v[34:35], s[36:37] op_sel_hi:[1,0]
	v_pk_mul_f32 v[36:37], v[36:37], s[36:37] op_sel_hi:[1,0]
	v_pk_mul_f32 v[38:39], v[38:39], s[36:37] op_sel_hi:[1,0]
	v_pk_mul_f32 v[40:41], v[40:41], s[36:37] op_sel_hi:[1,0]
	v_pk_mul_f32 v[42:43], v[42:43], s[36:37] op_sel_hi:[1,0]
	v_pk_mul_f32 v[44:45], v[44:45], s[36:37] op_sel_hi:[1,0]
	v_pk_mul_f32 v[46:47], v[46:47], s[36:37] op_sel_hi:[1,0]
	v_pk_mul_f32 v[48:49], v[48:49], s[36:37] op_sel_hi:[1,0]
	v_pk_mul_f32 v[50:51], v[50:51], s[36:37] op_sel_hi:[1,0]
	v_pk_mul_f32 v[52:53], v[52:53], s[36:37] op_sel_hi:[1,0]
	v_pk_mul_f32 v[54:55], v[54:55], s[36:37] op_sel_hi:[1,0]
	v_pk_mul_f32 v[56:57], v[56:57], s[36:37] op_sel_hi:[1,0]
	v_pk_mul_f32 v[58:59], v[58:59], s[36:37] op_sel_hi:[1,0]
	v_pk_mul_f32 v[60:61], v[60:61], s[36:37] op_sel_hi:[1,0]
	v_pk_mul_f32 v[62:63], v[62:63], s[36:37] op_sel_hi:[1,0]
	v_pk_mul_f32 v[64:65], v[64:65], s[36:37] op_sel_hi:[1,0]
	v_pk_mul_f32 v[66:67], v[66:67], s[36:37] op_sel_hi:[1,0]
	v_pk_mul_f32 v[68:69], v[68:69], s[36:37] op_sel_hi:[1,0]
	v_pk_mul_f32 v[70:71], v[70:71], s[36:37] op_sel_hi:[1,0]
	v_pk_mul_f32 v[144:145], v[144:145], s[36:37] op_sel_hi:[1,0]
	v_pk_mul_f32 v[146:147], v[146:147], s[36:37] op_sel_hi:[1,0]
	v_pk_mul_f32 v[148:149], v[148:149], s[36:37] op_sel_hi:[1,0]
	v_pk_mul_f32 v[150:151], v[150:151], s[36:37] op_sel_hi:[1,0]
	v_med3_f32 v16, v16, s40, v208
	v_med3_f32 v17, v17, s40, v208
	v_med3_f32 v18, v18, s40, v208
	v_med3_f32 v19, v19, s40, v208
	v_med3_f32 v20, v20, s40, v208
	v_med3_f32 v21, v21, s40, v208
	v_med3_f32 v22, v22, s40, v208
	v_med3_f32 v23, v23, s40, v208
	v_med3_f32 v24, v24, s40, v208
	v_med3_f32 v25, v25, s40, v208
	v_med3_f32 v26, v26, s40, v208
	v_med3_f32 v27, v27, s40, v208
	v_med3_f32 v28, v28, s40, v208
	v_med3_f32 v29, v29, s40, v208
	v_med3_f32 v30, v30, s40, v208
	v_med3_f32 v31, v31, s40, v208
	v_med3_f32 v32, v32, s40, v208
	v_med3_f32 v33, v33, s40, v208
	v_med3_f32 v34, v34, s40, v208
	v_med3_f32 v35, v35, s40, v208
	v_med3_f32 v36, v36, s40, v208
	v_med3_f32 v37, v37, s40, v208
	v_med3_f32 v38, v38, s40, v208
	v_med3_f32 v39, v39, s40, v208
	v_med3_f32 v40, v40, s40, v208
	v_med3_f32 v41, v41, s40, v208
	v_med3_f32 v42, v42, s40, v208
	v_med3_f32 v43, v43, s40, v208
	v_med3_f32 v44, v44, s40, v208
	v_med3_f32 v45, v45, s40, v208
	v_med3_f32 v46, v46, s40, v208
	v_med3_f32 v47, v47, s40, v208
	v_med3_f32 v48, v48, s40, v208
	v_med3_f32 v49, v49, s40, v208
	v_med3_f32 v50, v50, s40, v208
	v_med3_f32 v51, v51, s40, v208
	v_med3_f32 v52, v52, s40, v208
	v_med3_f32 v53, v53, s40, v208
	v_med3_f32 v54, v54, s40, v208
	v_med3_f32 v55, v55, s40, v208
	v_med3_f32 v56, v56, s40, v208
	v_med3_f32 v57, v57, s40, v208
	v_med3_f32 v58, v58, s40, v208
	v_med3_f32 v59, v59, s40, v208
	v_med3_f32 v60, v60, s40, v208
	v_med3_f32 v61, v61, s40, v208
	v_med3_f32 v62, v62, s40, v208
	v_med3_f32 v63, v63, s40, v208
	v_med3_f32 v64, v64, s40, v208
	v_med3_f32 v65, v65, s40, v208
	v_med3_f32 v66, v66, s40, v208
	v_med3_f32 v67, v67, s40, v208
	v_med3_f32 v68, v68, s40, v208
	v_med3_f32 v69, v69, s40, v208
	v_med3_f32 v70, v70, s40, v208
	v_med3_f32 v71, v71, s40, v208
	v_med3_f32 v144, v144, s40, v208
	v_med3_f32 v145, v145, s40, v208
	v_med3_f32 v146, v146, s40, v208
	v_med3_f32 v147, v147, s40, v208
	v_med3_f32 v148, v148, s40, v208
	v_med3_f32 v149, v149, s40, v208
	v_med3_f32 v150, v150, s40, v208
	v_med3_f32 v151, v151, s40, v208
	v_pk_add_f32 v[16:17], v[16:17], s[38:39] op_sel_hi:[1,0]
	v_pk_add_f32 v[18:19], v[18:19], s[38:39] op_sel_hi:[1,0]
	v_pk_add_f32 v[20:21], v[20:21], s[38:39] op_sel_hi:[1,0]
	v_pk_add_f32 v[22:23], v[22:23], s[38:39] op_sel_hi:[1,0]
	v_pk_add_f32 v[24:25], v[24:25], s[38:39] op_sel_hi:[1,0]
	v_pk_add_f32 v[26:27], v[26:27], s[38:39] op_sel_hi:[1,0]
	v_pk_add_f32 v[28:29], v[28:29], s[38:39] op_sel_hi:[1,0]
	v_pk_add_f32 v[30:31], v[30:31], s[38:39] op_sel_hi:[1,0]
	v_pk_add_f32 v[32:33], v[32:33], s[38:39] op_sel_hi:[1,0]
	v_pk_add_f32 v[34:35], v[34:35], s[38:39] op_sel_hi:[1,0]
	v_pk_add_f32 v[36:37], v[36:37], s[38:39] op_sel_hi:[1,0]
	v_pk_add_f32 v[38:39], v[38:39], s[38:39] op_sel_hi:[1,0]
	v_pk_add_f32 v[40:41], v[40:41], s[38:39] op_sel_hi:[1,0]
	v_pk_add_f32 v[42:43], v[42:43], s[38:39] op_sel_hi:[1,0]
	v_pk_add_f32 v[44:45], v[44:45], s[38:39] op_sel_hi:[1,0]
	v_pk_add_f32 v[46:47], v[46:47], s[38:39] op_sel_hi:[1,0]
	v_pk_add_f32 v[48:49], v[48:49], s[38:39] op_sel_hi:[1,0]
	v_pk_add_f32 v[50:51], v[50:51], s[38:39] op_sel_hi:[1,0]
	v_pk_add_f32 v[52:53], v[52:53], s[38:39] op_sel_hi:[1,0]
	v_pk_add_f32 v[54:55], v[54:55], s[38:39] op_sel_hi:[1,0]
	v_pk_add_f32 v[56:57], v[56:57], s[38:39] op_sel_hi:[1,0]
	v_pk_add_f32 v[58:59], v[58:59], s[38:39] op_sel_hi:[1,0]
	v_pk_add_f32 v[60:61], v[60:61], s[38:39] op_sel_hi:[1,0]
	v_pk_add_f32 v[62:63], v[62:63], s[38:39] op_sel_hi:[1,0]
	v_pk_add_f32 v[64:65], v[64:65], s[38:39] op_sel_hi:[1,0]
	v_pk_add_f32 v[66:67], v[66:67], s[38:39] op_sel_hi:[1,0]
	v_pk_add_f32 v[68:69], v[68:69], s[38:39] op_sel_hi:[1,0]
	v_pk_add_f32 v[70:71], v[70:71], s[38:39] op_sel_hi:[1,0]
; #define LAS __attribute__((address_space(3)))
; __device__ __forceinline__ unsigned pk4_f8(float a, float b, float c, float d) { int w = __builtin_amdgcn_cvt_pk_fp8_f32(a, b, 0, false); w = __builtin_amdgcn_cvt_pk_fp8_f32(c, d, w, true); return (unsigned)w; }
; #define LDS_WAIT() asm volatile("s_waitcnt lgkmcnt(0)" ::: "memory")
; __device__ __forceinline__ unsigned pk4_i8(float a, float b, float c, float d, float s) {
;     ...
;     return (ua & 0xffu) | ((ub & 0xffu) << 8) | ((uc & 0xffu) << 16) | (ud << 24);
;     ...
;         for (int j = 0; j < 2; ++j) { const int n = (lane >> 2) + 16 * j; const LAS float* sp = scr + (16 * c) * 33 + n;
;             u32x4 o;
;             if (QI8) { o.x = pk4_i8(sp[0 * 33], sp[1 * 33], sp[2 * 33], sp[3 * 33], scl); o.y = pk4_i8(sp[4 * 33], sp[5 * 33], sp[6 * 33], sp[7 * 33], scl);
;                 o.z = pk4_i8(sp[8 * 33], sp[9 * 33], sp[10 * 33], sp[11 * 33], scl); o.w = pk4_i8(sp[12 * 33], sp[13 * 33], sp[14 * 33], sp[15 * 33], scl); }
;             else {
;             o.x = pk4_f8(sp[0 * 33] * scl, sp[1 * 33] * scl, sp[2 * 33] * scl, sp[3 * 33] * scl); o.y = pk4_f8(sp[4 * 33] * scl, sp[5 * 33] * scl, sp[6 * 33] * scl, sp[7 * 33] * scl);
;             o.z = pk4_f8(sp[8 * 33] * scl, sp[9 * 33] * scl, sp[10 * 33] * scl, sp[11 * 33] * scl); o.w = pk4_f8(sp[12 * 33] * scl, sp[13 * 33] * scl, sp[14 * 33] * scl, sp[15 * 33] * scl); }
;             *(u32x4*)(WT + (size_t)(dr0 + n) * K + k0 + 16 * c) = o; }
;         LDS_WAIT(); asm volatile("" ::: "memory"); }
	v_pk_add_f32 v[144:145], v[144:145], s[38:39] op_sel_hi:[1,0]
	v_pk_add_f32 v[146:147], v[146:147], s[38:39] op_sel_hi:[1,0]
	v_pk_add_f32 v[148:149], v[148:149], s[38:39] op_sel_hi:[1,0]
	v_pk_add_f32 v[150:151], v[150:151], s[38:39] op_sel_hi:[1,0]
	v_perm_b32 v196, v20, v16, s41
	v_perm_b32 v197, v28, v24, s41
	v_perm_b32 v180, v197, v196, s42
	v_perm_b32 v196, v36, v32, s41
	v_perm_b32 v197, v44, v40, s41
	v_perm_b32 v181, v197, v196, s42
	v_perm_b32 v196, v52, v48, s41
	v_perm_b32 v197, v60, v56, s41
	v_perm_b32 v182, v197, v196, s42
	v_perm_b32 v196, v68, v64, s41
	v_perm_b32 v197, v148, v144, s41
	v_perm_b32 v183, v197, v196, s42
	v_perm_b32 v196, v21, v17, s41
	v_perm_b32 v197, v29, v25, s41
	v_perm_b32 v184, v197, v196, s42
	v_perm_b32 v196, v37, v33, s41
	v_perm_b32 v197, v45, v41, s41
	v_perm_b32 v185, v197, v196, s42
	v_perm_b32 v196, v53, v49, s41
	v_perm_b32 v197, v61, v57, s41
	v_perm_b32 v186, v197, v196, s42
	v_perm_b32 v196, v69, v65, s41
	v_perm_b32 v197, v149, v145, s41
	v_perm_b32 v187, v197, v196, s42
	v_perm_b32 v196, v22, v18, s41
	v_perm_b32 v197, v30, v26, s41
	v_perm_b32 v188, v197, v196, s42
	v_perm_b32 v196, v38, v34, s41
	v_perm_b32 v197, v46, v42, s41
	v_perm_b32 v189, v197, v196, s42
	v_perm_b32 v196, v54, v50, s41
	v_perm_b32 v197, v62, v58, s41
	v_perm_b32 v190, v197, v196, s42
	v_perm_b32 v196, v70, v66, s41
	v_perm_b32 v197, v150, v146, s41
	v_perm_b32 v191, v197, v196, s42
	v_perm_b32 v196, v23, v19, s41
	v_perm_b32 v197, v31, v27, s41
	v_perm_b32 v192, v197, v196, s42
	v_perm_b32 v196, v39, v35, s41
	v_perm_b32 v197, v47, v43, s41
	v_perm_b32 v193, v197, v196, s42
	v_perm_b32 v196, v55, v51, s41
	v_perm_b32 v197, v63, v59, s41
	v_perm_b32 v194, v197, v196, s42
	v_perm_b32 v196, v71, v67, s41
	v_perm_b32 v197, v151, v147, s41
	v_perm_b32 v195, v197, v196, s42
	ds_write_b128 v205, v[180:183] offset:36864
	ds_write_b128 v205, v[184:187] offset:37008
	ds_write_b128 v205, v[188:191] offset:37152
	ds_write_b128 v205, v[192:195] offset:37296
	s_mov_b32 s26, s63
	s_add_i32 s26, s26, s17
	s_mul_i32 s26, s26, 0x1000
	s_add_u32 s26, s26, s62
	s_add_u32 s54, s56, s26
	s_addc_u32 s55, s57, 0
	s_waitcnt lgkmcnt(0)
	s_barrier
	ds_read_b128 v[180:183], v206 offset:36864
	ds_read_b128 v[184:187], v206 offset:38016
	ds_read_b128 v[188:191], v206 offset:39168
	ds_read_b128 v[192:195], v206 offset:40320
	s_waitcnt lgkmcnt(3)
	global_store_dwordx4 v207, v[180:183], s[54:55]
	s_add_u32 s54, s54, 0x8000
	s_addc_u32 s55, s55, 0
	s_waitcnt lgkmcnt(2)
	global_store_dwordx4 v207, v[184:187], s[54:55]
	s_add_u32 s54, s54, 0x8000
	s_addc_u32 s55, s55, 0
	s_waitcnt lgkmcnt(1)
	global_store_dwordx4 v207, v[188:191], s[54:55]
	s_add_u32 s54, s54, 0x8000
	s_addc_u32 s55, s55, 0
	s_waitcnt lgkmcnt(0)
	global_store_dwordx4 v207, v[192:195], s[54:55]
	s_mov_b32 s19, s64
	s_cmp_lt_u32 s19, 0x100
	s_cbranch_scc1 .Lf8t_win8bcd0_loop
;     ...
;     for (int item = F.gw; item < nitems; item += F.NGW) { const int kb = item / nblk, nb = item % nblk, k0 = 64 * kb, n0 = 32 * nb;
;         int dr0 = n0; if (MAP == 1) { if (n0 < DFF) dr0 = (n0 >> 7) * 256 + (n0 & 127); else { const int uo = n0 - DFF; dr0 = (uo >> 7) * 256 + 128 + (uo & 127); } }
; #pragma unroll 8
;         for (int i = 0; i < 32; ++i) { const int kk = 2 * i + (lane >> 5); scr[kk * 33 + (lane & 31)] = W[(size_t)(k0 + kk) * ldw + n0 + (lane & 31)]; }
; __device__ __forceinline__ void p0_prologue(Frame& F) {
;     ...
;       transpose_f8_matrix<0, true>(F, W + 6144, D, 2048, w8 + (size_t)10240 * D, I8_W, ldw);
.Lf8t_win8bcd0_end:
	s_waitcnt vmcnt(0) lgkmcnt(0)
	s_barrier
	s_barrier
	s_load_dwordx2 s[50:51], s[74:75], 0x58
	v_readlane_b32 s16, v240, 2
	v_lshlrev_b32_e32 v204, 4, v178
	v_mov_b32_e32 v208, 0x42fe0000
	s_mov_b32 s36, 0x44fe0000
	s_mov_b32 s37, 0
	s_mov_b32 s38, 0x4b400000
	s_mov_b32 s39, 0
	s_mov_b32 s40, 0xc2fe0000
	s_mov_b32 s41, 0x0c0c0400
	s_mov_b32 s42, 0x05040100
	s_lshl_b32 s17, s16, 5
	v_mul_u32_u24_e32 v205, 0x240, v178
	s_lshl_b32 s18, s16, 4
	v_add_u32_e32 v205, s18, v205
	v_lshrrev_b32_e32 v196, 3, v178
	v_and_b32_e32 v197, 7, v178
	s_lshl_b32 s18, s16, 5
	v_add_u32_e32 v198, s18, v196
	v_mul_u32_u24_e32 v206, 0x90, v198
	v_lshl_add_u32 v206, v197, 4, v206
	v_mul_u32_u24_e32 v207, 0x1000, v196
	v_lshl_add_u32 v207, v197, 4, v207
	s_lshl_b32 s16, s16, 4
	s_waitcnt lgkmcnt(0)
	s_add_u32 s50, s50, 0x6000
	s_addc_u32 s51, s51, 0
	s_add_u32 s56, s90, 0x38300000
	s_addc_u32 s57, s91, 0
	s_mov_b32 s19, s2
	s_cmp_lt_u32 s19, 0x200
	s_cbranch_scc0 .Lf8t_win8bcd1_end
	s_mul_hi_u32 s20, s19, 0x10000000
	s_mul_i32 s21, s20, 16
	s_sub_i32 s21, s19, s21
	s_lshl_b32 s60, s20, 7
	s_lshl_b32 s61, s21, 8
	s_add_i32 s24, s60, s16
	s_mul_i32 s24, s24, 0x16b80
	s_lshl_b32 s25, s61, 2
	s_add_u32 s24, s24, s25
	s_add_u32 s52, s50, s24
	s_addc_u32 s53, s51, 0
	global_load_dwordx4 v[80:83], v204, s[52:53]
	s_add_u32 s52, s52, 0x16b80
	s_addc_u32 s53, s53, 0
	global_load_dwordx4 v[84:87], v204, s[52:53]
	s_add_u32 s52, s52, 0x16b80
	s_addc_u32 s53, s53, 0
	global_load_dwordx4 v[88:91], v204, s[52:53]
	s_add_u32 s52, s52, 0x16b80
	s_addc_u32 s53, s53, 0
	global_load_dwordx4 v[92:95], v204, s[52:53]
	s_add_u32 s52, s52, 0x16b80
	s_addc_u32 s53, s53, 0
	global_load_dwordx4 v[96:99], v204, s[52:53]
	s_add_u32 s52, s52, 0x16b80
	s_addc_u32 s53, s53, 0
	global_load_dwordx4 v[100:103], v204, s[52:53]
	s_add_u32 s52, s52, 0x16b80
	s_addc_u32 s53, s53, 0
	global_load_dwordx4 v[104:107], v204, s[52:53]
	s_add_u32 s52, s52, 0x16b80
	s_addc_u32 s53, s53, 0
	global_load_dwordx4 v[108:111], v204, s[52:53]
	s_add_u32 s52, s52, 0x16b80
	s_addc_u32 s53, s53, 0
	global_load_dwordx4 v[112:115], v204, s[52:53]
	s_add_u32 s52, s52, 0x16b80
	s_addc_u32 s53, s53, 0
	global_load_dwordx4 v[116:119], v204, s[52:53]
	s_add_u32 s52, s52, 0x16b80
	s_addc_u32 s53, s53, 0
	global_load_dwordx4 v[120:123], v204, s[52:53]
	s_add_u32 s52, s52, 0x16b80
	s_addc_u32 s53, s53, 0
	global_load_dwordx4 v[124:127], v204, s[52:53]
	s_add_u32 s52, s52, 0x16b80
	s_addc_u32 s53, s53, 0
	global_load_dwordx4 v[128:131], v204, s[52:53]
	s_add_u32 s52, s52, 0x16b80
	s_addc_u32 s53, s53, 0
	global_load_dwordx4 v[132:135], v204, s[52:53]
	s_add_u32 s52, s52, 0x16b80
	s_addc_u32 s53, s53, 0
	global_load_dwordx4 v[136:139], v204, s[52:53]
	s_add_u32 s52, s52, 0x16b80
	s_addc_u32 s53, s53, 0
	global_load_dwordx4 v[140:143], v204, s[52:53]
	s_mov_b32 s58, 1
.Lf8t_win8bcd1_loop:
	s_add_i32 s64, s19, s96
	s_cmp_lt_u32 s64, 0x200
	s_cbranch_scc0 .Lf8t_win8bcd1_a_nonext
	s_mul_hi_u32 s20, s64, 0x10000000
	s_mul_i32 s21, s20, 16
	s_sub_i32 s21, s64, s21
	s_lshl_b32 s62, s20, 7
	s_lshl_b32 s63, s21, 8
	s_add_i32 s24, s62, s16
	s_mul_i32 s24, s24, 0x16b80
	s_lshl_b32 s25, s63, 2
	s_add_u32 s24, s24, s25
	s_add_u32 s52, s50, s24
	s_addc_u32 s53, s51, 0
	global_load_dwordx4 v[16:19], v204, s[52:53]
	s_add_u32 s52, s52, 0x16b80
	s_addc_u32 s53, s53, 0
	global_load_dwordx4 v[20:23], v204, s[52:53]
	s_add_u32 s52, s52, 0x16b80
	s_addc_u32 s53, s53, 0
	global_load_dwordx4 v[24:27], v204, s[52:53]
	s_add_u32 s52, s52, 0x16b80
	s_addc_u32 s53, s53, 0
	global_load_dwordx4 v[28:31], v204, s[52:53]
	s_add_u32 s52, s52, 0x16b80
	s_addc_u32 s53, s53, 0
	global_load_dwordx4 v[32:35], v204, s[52:53]
	s_add_u32 s52, s52, 0x16b80
	s_addc_u32 s53, s53, 0
	global_load_dwordx4 v[36:39], v204, s[52:53]
	s_add_u32 s52, s52, 0x16b80
	s_addc_u32 s53, s53, 0
	global_load_dwordx4 v[40:43], v204, s[52:53]
	s_add_u32 s52, s52, 0x16b80
	s_addc_u32 s53, s53, 0
	global_load_dwordx4 v[44:47], v204, s[52:53]
	s_add_u32 s52, s52, 0x16b80
	s_addc_u32 s53, s53, 0
	global_load_dwordx4 v[48:51], v204, s[52:53]
	s_add_u32 s52, s52, 0x16b80
	s_addc_u32 s53, s53, 0
	global_load_dwordx4 v[52:55], v204, s[52:53]
	s_add_u32 s52, s52, 0x16b80
	s_addc_u32 s53, s53, 0
	global_load_dwordx4 v[56:59], v204, s[52:53]
	s_add_u32 s52, s52, 0x16b80
	s_addc_u32 s53, s53, 0
	global_load_dwordx4 v[60:63], v204, s[52:53]
	s_add_u32 s52, s52, 0x16b80
	s_addc_u32 s53, s53, 0
	global_load_dwordx4 v[64:67], v204, s[52:53]
	s_add_u32 s52, s52, 0x16b80
	s_addc_u32 s53, s53, 0
	global_load_dwordx4 v[68:71], v204, s[52:53]
	s_add_u32 s52, s52, 0x16b80
	s_addc_u32 s53, s53, 0
	global_load_dwordx4 v[144:147], v204, s[52:53]
	s_add_u32 s52, s52, 0x16b80
	s_addc_u32 s53, s53, 0
	global_load_dwordx4 v[148:151], v204, s[52:53]
	s_cmp_eq_u32 s58, 1
	s_cbranch_scc1 .Lf8t_win8bcd1_a_first
	s_waitcnt vmcnt(20)
	s_branch .Lf8t_win8bcd1_a_go

; __device__ __forceinline__ unsigned pk4_i8(float a, float b, float c, float d, float s) {
;     const unsigned ua = __float_as_uint(__builtin_amdgcn_fmed3f(a * s, -127.f, 127.f) + 12582912.f), ub = __float_as_uint(__builtin_amdgcn_fmed3f(b * s, -127.f, 127.f) + 12582912.f);
;     const unsigned uc = __float_as_uint(__builtin_amdgcn_fmed3f(c * s, -127.f, 127.f) + 12582912.f), ud = __float_as_uint(__builtin_amdgcn_fmed3f(d * s, -127.f, 127.f) + 12582912.f);
.Lf8t_win8bcd1_a_go:
	s_mov_b32 s58, 0
	v_pk_mul_f32 v[80:81], v[80:81], s[36:37] op_sel_hi:[1,0]
	v_pk_mul_f32 v[82:83], v[82:83], s[36:37] op_sel_hi:[1,0]
	v_pk_mul_f32 v[84:85], v[84:85], s[36:37] op_sel_hi:[1,0]
	v_pk_mul_f32 v[86:87], v[86:87], s[36:37] op_sel_hi:[1,0]
	v_pk_mul_f32 v[88:89], v[88:89], s[36:37] op_sel_hi:[1,0]
	v_pk_mul_f32 v[90:91], v[90:91], s[36:37] op_sel_hi:[1,0]
	v_pk_mul_f32 v[92:93], v[92:93], s[36:37] op_sel_hi:[1,0]
	v_pk_mul_f32 v[94:95], v[94:95], s[36:37] op_sel_hi:[1,0]
	v_pk_mul_f32 v[96:97], v[96:97], s[36:37] op_sel_hi:[1,0]
	v_pk_mul_f32 v[98:99], v[98:99], s[36:37] op_sel_hi:[1,0]
	v_pk_mul_f32 v[100:101], v[100:101], s[36:37] op_sel_hi:[1,0]
	v_pk_mul_f32 v[102:103], v[102:103], s[36:37] op_sel_hi:[1,0]
	v_pk_mul_f32 v[104:105], v[104:105], s[36:37] op_sel_hi:[1,0]
	v_pk_mul_f32 v[106:107], v[106:107], s[36:37] op_sel_hi:[1,0]
	v_pk_mul_f32 v[108:109], v[108:109], s[36:37] op_sel_hi:[1,0]
	v_pk_mul_f32 v[110:111], v[110:111], s[36:37] op_sel_hi:[1,0]
	v_pk_mul_f32 v[112:113], v[112:113], s[36:37] op_sel_hi:[1,0]
	v_pk_mul_f32 v[114:115], v[114:115], s[36:37] op_sel_hi:[1,0]
	v_pk_mul_f32 v[116:117], v[116:117], s[36:37] op_sel_hi:[1,0]
	v_pk_mul_f32 v[118:119], v[118:119], s[36:37] op_sel_hi:[1,0]
	v_pk_mul_f32 v[120:121], v[120:121], s[36:37] op_sel_hi:[1,0]
	v_pk_mul_f32 v[122:123], v[122:123], s[36:37] op_sel_hi:[1,0]
	v_pk_mul_f32 v[124:125], v[124:125], s[36:37] op_sel_hi:[1,0]
	v_pk_mul_f32 v[126:127], v[126:127], s[36:37] op_sel_hi:[1,0]
	v_pk_mul_f32 v[128:129], v[128:129], s[36:37] op_sel_hi:[1,0]
	v_pk_mul_f32 v[130:131], v[130:131], s[36:37] op_sel_hi:[1,0]
	v_pk_mul_f32 v[132:133], v[132:133], s[36:37] op_sel_hi:[1,0]
	v_pk_mul_f32 v[134:135], v[134:135], s[36:37] op_sel_hi:[1,0]
	v_pk_mul_f32 v[136:137], v[136:137], s[36:37] op_sel_hi:[1,0]
	v_pk_mul_f32 v[138:139], v[138:139], s[36:37] op_sel_hi:[1,0]
	v_pk_mul_f32 v[140:141], v[140:141], s[36:37] op_sel_hi:[1,0]
	v_pk_mul_f32 v[142:143], v[142:143], s[36:37] op_sel_hi:[1,0]
	v_med3_f32 v80, v80, s40, v208
	v_med3_f32 v81, v81, s40, v208
	v_med3_f32 v82, v82, s40, v208
	v_med3_f32 v83, v83, s40, v208
	v_med3_f32 v84, v84, s40, v208
	v_med3_f32 v85, v85, s40, v208
	v_med3_f32 v86, v86, s40, v208
	v_med3_f32 v87, v87, s40, v208
	v_med3_f32 v88, v88, s40, v208
	v_med3_f32 v89, v89, s40, v208
	v_med3_f32 v90, v90, s40, v208
	v_med3_f32 v91, v91, s40, v208
	v_med3_f32 v92, v92, s40, v208
	v_med3_f32 v93, v93, s40, v208
	v_med3_f32 v94, v94, s40, v208
	v_med3_f32 v95, v95, s40, v208
	v_med3_f32 v96, v96, s40, v208
	v_med3_f32 v97, v97, s40, v208
	v_med3_f32 v98, v98, s40, v208
	v_med3_f32 v99, v99, s40, v208
	v_med3_f32 v100, v100, s40, v208
	v_med3_f32 v101, v101, s40, v208
	v_med3_f32 v102, v102, s40, v208
	v_med3_f32 v103, v103, s40, v208
	v_med3_f32 v104, v104, s40, v208
	v_med3_f32 v105, v105, s40, v208
	v_med3_f32 v106, v106, s40, v208
	v_med3_f32 v107, v107, s40, v208
	v_med3_f32 v108, v108, s40, v208
	v_med3_f32 v109, v109, s40, v208
	v_med3_f32 v110, v110, s40, v208
	v_med3_f32 v111, v111, s40, v208
	v_med3_f32 v112, v112, s40, v208
	v_med3_f32 v113, v113, s40, v208
	v_med3_f32 v114, v114, s40, v208
	v_med3_f32 v115, v115, s40, v208
	v_med3_f32 v116, v116, s40, v208
	v_med3_f32 v117, v117, s40, v208
	v_med3_f32 v118, v118, s40, v208
	v_med3_f32 v119, v119, s40, v208
	v_med3_f32 v120, v120, s40, v208
	v_med3_f32 v121, v121, s40, v208
	v_med3_f32 v122, v122, s40, v208
	v_med3_f32 v123, v123, s40, v208
	v_med3_f32 v124, v124, s40, v208
	v_med3_f32 v125, v125, s40, v208
	v_med3_f32 v126, v126, s40, v208
	v_med3_f32 v127, v127, s40, v208
	v_med3_f32 v128, v128, s40, v208
	v_med3_f32 v129, v129, s40, v208
	v_med3_f32 v130, v130, s40, v208
	v_med3_f32 v131, v131, s40, v208
	v_med3_f32 v132, v132, s40, v208
	v_med3_f32 v133, v133, s40, v208
	v_med3_f32 v134, v134, s40, v208
	v_med3_f32 v135, v135, s40, v208
	v_med3_f32 v136, v136, s40, v208
	v_med3_f32 v137, v137, s40, v208
	v_med3_f32 v138, v138, s40, v208
	v_med3_f32 v139, v139, s40, v208
	v_med3_f32 v140, v140, s40, v208
	v_med3_f32 v141, v141, s40, v208
	v_med3_f32 v142, v142, s40, v208
	v_med3_f32 v143, v143, s40, v208
	v_pk_add_f32 v[80:81], v[80:81], s[38:39] op_sel_hi:[1,0]
	v_pk_add_f32 v[82:83], v[82:83], s[38:39] op_sel_hi:[1,0]
	v_pk_add_f32 v[84:85], v[84:85], s[38:39] op_sel_hi:[1,0]
	v_pk_add_f32 v[86:87], v[86:87], s[38:39] op_sel_hi:[1,0]
	v_pk_add_f32 v[88:89], v[88:89], s[38:39] op_sel_hi:[1,0]
	v_pk_add_f32 v[90:91], v[90:91], s[38:39] op_sel_hi:[1,0]
	v_pk_add_f32 v[92:93], v[92:93], s[38:39] op_sel_hi:[1,0]
	v_pk_add_f32 v[94:95], v[94:95], s[38:39] op_sel_hi:[1,0]
	v_pk_add_f32 v[96:97], v[96:97], s[38:39] op_sel_hi:[1,0]
	v_pk_add_f32 v[98:99], v[98:99], s[38:39] op_sel_hi:[1,0]
	v_pk_add_f32 v[100:101], v[100:101], s[38:39] op_sel_hi:[1,0]
	v_pk_add_f32 v[102:103], v[102:103], s[38:39] op_sel_hi:[1,0]
	v_pk_add_f32 v[104:105], v[104:105], s[38:39] op_sel_hi:[1,0]
	v_pk_add_f32 v[106:107], v[106:107], s[38:39] op_sel_hi:[1,0]
	v_pk_add_f32 v[108:109], v[108:109], s[38:39] op_sel_hi:[1,0]
	v_pk_add_f32 v[110:111], v[110:111], s[38:39] op_sel_hi:[1,0]
	v_pk_add_f32 v[112:113], v[112:113], s[38:39] op_sel_hi:[1,0]
	v_pk_add_f32 v[114:115], v[114:115], s[38:39] op_sel_hi:[1,0]
	v_pk_add_f32 v[116:117], v[116:117], s[38:39] op_sel_hi:[1,0]
	v_pk_add_f32 v[118:119], v[118:119], s[38:39] op_sel_hi:[1,0]
; #define LAS __attribute__((address_space(3)))
; __device__ __forceinline__ unsigned pk4_f8(float a, float b, float c, float d) { int w = __builtin_amdgcn_cvt_pk_fp8_f32(a, b, 0, false); w = __builtin_amdgcn_cvt_pk_fp8_f32(c, d, w, true); return (unsigned)w; }
; #define LDS_WAIT() asm volatile("s_waitcnt lgkmcnt(0)" ::: "memory")
;     ...
;     for (int item = F.gw; item < nitems; item += F.NGW) { const int kb = item / nblk, nb = item % nblk, k0 = 64 * kb, n0 = 32 * nb;
;         int dr0 = n0; if (MAP == 1) { if (n0 < DFF) dr0 = (n0 >> 7) * 256 + (n0 & 127); else { const int uo = n0 - DFF; dr0 = (uo >> 7) * 256 + 128 + (uo & 127); } }
; #pragma unroll 8
;         for (int i = 0; i < 32; ++i) { const int kk = 2 * i + (lane >> 5); scr[kk * 33 + (lane & 31)] = W[(size_t)(k0 + kk) * ldw + n0 + (lane & 31)]; }
;         LDS_WAIT(); asm volatile("" ::: "memory");
;         const int c = lane & 3;
; #pragma unroll
;         for (int j = 0; j < 2; ++j) { const int n = (lane >> 2) + 16 * j; const LAS float* sp = scr + (16 * c) * 33 + n;
;             u32x4 o;
;             if (QI8) { o.x = pk4_i8(sp[0 * 33], sp[1 * 33], sp[2 * 33], sp[3 * 33], scl); o.y = pk4_i8(sp[4 * 33], sp[5 * 33], sp[6 * 33], sp[7 * 33], scl);
;                 o.z = pk4_i8(sp[8 * 33], sp[9 * 33], sp[10 * 33], sp[11 * 33], scl); o.w = pk4_i8(sp[12 * 33], sp[13 * 33], sp[14 * 33], sp[15 * 33], scl); }
;             else {
;             o.x = pk4_f8(sp[0 * 33] * scl, sp[1 * 33] * scl, sp[2 * 33] * scl, sp[3 * 33] * scl); o.y = pk4_f8(sp[4 * 33] * scl, sp[5 * 33] * scl, sp[6 * 33] * scl, sp[7 * 33] * scl);
;             o.z = pk4_f8(sp[8 * 33] * scl, sp[9 * 33] * scl, sp[10 * 33] * scl, sp[11 * 33] * scl); o.w = pk4_f8(sp[12 * 33] * scl, sp[13 * 33] * scl, sp[14 * 33] * scl, sp[15 * 33] * scl); }
;             *(u32x4*)(WT + (size_t)(dr0 + n) * K + k0 + 16 * c) = o; }
	v_pk_add_f32 v[120:121], v[120:121], s[38:39] op_sel_hi:[1,0]
	v_pk_add_f32 v[122:123], v[122:123], s[38:39] op_sel_hi:[1,0]
	v_pk_add_f32 v[124:125], v[124:125], s[38:39] op_sel_hi:[1,0]
	v_pk_add_f32 v[126:127], v[126:127], s[38:39] op_sel_hi:[1,0]
	v_pk_add_f32 v[128:129], v[128:129], s[38:39] op_sel_hi:[1,0]
	v_pk_add_f32 v[130:131], v[130:131], s[38:39] op_sel_hi:[1,0]
	v_pk_add_f32 v[132:133], v[132:133], s[38:39] op_sel_hi:[1,0]
	v_pk_add_f32 v[134:135], v[134:135], s[38:39] op_sel_hi:[1,0]
	v_pk_add_f32 v[136:137], v[136:137], s[38:39] op_sel_hi:[1,0]
	v_pk_add_f32 v[138:139], v[138:139], s[38:39] op_sel_hi:[1,0]
	v_pk_add_f32 v[140:141], v[140:141], s[38:39] op_sel_hi:[1,0]
	v_pk_add_f32 v[142:143], v[142:143], s[38:39] op_sel_hi:[1,0]
	v_perm_b32 v196, v84, v80, s41
	v_perm_b32 v197, v92, v88, s41
	v_perm_b32 v180, v197, v196, s42
	v_perm_b32 v196, v100, v96, s41
	v_perm_b32 v197, v108, v104, s41
	v_perm_b32 v181, v197, v196, s42
	v_perm_b32 v196, v116, v112, s41
	v_perm_b32 v197, v124, v120, s41
	v_perm_b32 v182, v197, v196, s42
	v_perm_b32 v196, v132, v128, s41
	v_perm_b32 v197, v140, v136, s41
	v_perm_b32 v183, v197, v196, s42
	v_perm_b32 v196, v85, v81, s41
	v_perm_b32 v197, v93, v89, s41
	v_perm_b32 v184, v197, v196, s42
	v_perm_b32 v196, v101, v97, s41
	v_perm_b32 v197, v109, v105, s41
	v_perm_b32 v185, v197, v196, s42
	v_perm_b32 v196, v117, v113, s41
	v_perm_b32 v197, v125, v121, s41
	v_perm_b32 v186, v197, v196, s42
	v_perm_b32 v196, v133, v129, s41
	v_perm_b32 v197, v141, v137, s41
	v_perm_b32 v187, v197, v196, s42
	v_perm_b32 v196, v86, v82, s41
	v_perm_b32 v197, v94, v90, s41
	v_perm_b32 v188, v197, v196, s42
	v_perm_b32 v196, v102, v98, s41
	v_perm_b32 v197, v110, v106, s41
	v_perm_b32 v189, v197, v196, s42
	v_perm_b32 v196, v118, v114, s41
	v_perm_b32 v197, v126, v122, s41
	v_perm_b32 v190, v197, v196, s42
	v_perm_b32 v196, v134, v130, s41
	v_perm_b32 v197, v142, v138, s41
	v_perm_b32 v191, v197, v196, s42
	v_perm_b32 v196, v87, v83, s41
	v_perm_b32 v197, v95, v91, s41
	v_perm_b32 v192, v197, v196, s42
	v_perm_b32 v196, v103, v99, s41
	v_perm_b32 v197, v111, v107, s41
	v_perm_b32 v193, v197, v196, s42
	v_perm_b32 v196, v119, v115, s41
	v_perm_b32 v197, v127, v123, s41
	v_perm_b32 v194, v197, v196, s42
	v_perm_b32 v196, v135, v131, s41
	v_perm_b32 v197, v143, v139, s41
	v_perm_b32 v195, v197, v196, s42
	ds_write_b128 v205, v[180:183] offset:0
	ds_write_b128 v205, v[184:187] offset:144
	ds_write_b128 v205, v[188:191] offset:288
	ds_write_b128 v205, v[192:195] offset:432
	s_mov_b32 s26, s61
	s_add_i32 s26, s26, s17
	s_mul_i32 s26, s26, 0x1000
	s_add_u32 s26, s26, s60
	s_add_u32 s54, s56, s26
	s_addc_u32 s55, s57, 0
	s_waitcnt lgkmcnt(0)
	s_barrier
	ds_read_b128 v[180:183], v206 offset:0
	ds_read_b128 v[184:187], v206 offset:1152
	ds_read_b128 v[188:191], v206 offset:2304
	ds_read_b128 v[192:195], v206 offset:3456
	s_waitcnt lgkmcnt(3)
	global_store_dwordx4 v207, v[180:183], s[54:55]
	s_add_u32 s54, s54, 0x8000
	s_addc_u32 s55, s55, 0
	s_waitcnt lgkmcnt(2)
	global_store_dwordx4 v207, v[184:187], s[54:55]
	s_add_u32 s54, s54, 0x8000
	s_addc_u32 s55, s55, 0
	s_waitcnt lgkmcnt(1)
	global_store_dwordx4 v207, v[188:191], s[54:55]
	s_add_u32 s54, s54, 0x8000
	s_addc_u32 s55, s55, 0
	s_waitcnt lgkmcnt(0)
	global_store_dwordx4 v207, v[192:195], s[54:55]
	s_mov_b32 s19, s64
	s_cmp_lt_u32 s19, 0x200
	s_cbranch_scc0 .Lf8t_win8bcd1_end
	s_add_i32 s64, s19, s96
	s_cmp_lt_u32 s64, 0x200
	s_cbranch_scc0 .Lf8t_win8bcd1_b_nonext
	s_mul_hi_u32 s20, s64, 0x10000000
	s_mul_i32 s21, s20, 16
	s_sub_i32 s21, s64, s21
	s_lshl_b32 s60, s20, 7
	s_lshl_b32 s61, s21, 8
	s_add_i32 s24, s60, s16
	s_mul_i32 s24, s24, 0x16b80
	s_lshl_b32 s25, s61, 2
	s_add_u32 s24, s24, s25
	s_add_u32 s52, s50, s24
	s_addc_u32 s53, s51, 0
	global_load_dwordx4 v[80:83], v204, s[52:53]
	s_add_u32 s52, s52, 0x16b80
	s_addc_u32 s53, s53, 0
	global_load_dwordx4 v[84:87], v204, s[52:53]
	s_add_u32 s52, s52, 0x16b80
	s_addc_u32 s53, s53, 0
	global_load_dwordx4 v[88:91], v204, s[52:53]
	s_add_u32 s52, s52, 0x16b80
	s_addc_u32 s53, s53, 0
	global_load_dwordx4 v[92:95], v204, s[52:53]
	s_add_u32 s52, s52, 0x16b80
	s_addc_u32 s53, s53, 0
	global_load_dwordx4 v[96:99], v204, s[52:53]
	s_add_u32 s52, s52, 0x16b80
	s_addc_u32 s53, s53, 0
	global_load_dwordx4 v[100:103], v204, s[52:53]
	s_add_u32 s52, s52, 0x16b80
	s_addc_u32 s53, s53, 0
	global_load_dwordx4 v[104:107], v204, s[52:53]
	s_add_u32 s52, s52, 0x16b80
	s_addc_u32 s53, s53, 0
	global_load_dwordx4 v[108:111], v204, s[52:53]
	s_add_u32 s52, s52, 0x16b80
	s_addc_u32 s53, s53, 0
	global_load_dwordx4 v[112:115], v204, s[52:53]
	s_add_u32 s52, s52, 0x16b80
	s_addc_u32 s53, s53, 0
	global_load_dwordx4 v[116:119], v204, s[52:53]
	s_add_u32 s52, s52, 0x16b80
	s_addc_u32 s53, s53, 0
	global_load_dwordx4 v[120:123], v204, s[52:53]
	s_add_u32 s52, s52, 0x16b80
	s_addc_u32 s53, s53, 0
	global_load_dwordx4 v[124:127], v204, s[52:53]
	s_add_u32 s52, s52, 0x16b80
	s_addc_u32 s53, s53, 0
	global_load_dwordx4 v[128:131], v204, s[52:53]
	s_add_u32 s52, s52, 0x16b80
	s_addc_u32 s53, s53, 0
	global_load_dwordx4 v[132:135], v204, s[52:53]
	s_add_u32 s52, s52, 0x16b80
	s_addc_u32 s53, s53, 0
	global_load_dwordx4 v[136:139], v204, s[52:53]
	s_add_u32 s52, s52, 0x16b80
	s_addc_u32 s53, s53, 0
	global_load_dwordx4 v[140:143], v204, s[52:53]
	s_waitcnt vmcnt(20)
	s_branch .Lf8t_win8bcd1_b_go

; __device__ __forceinline__ unsigned pk4_i8(float a, float b, float c, float d, float s) {
;     const unsigned ua = __float_as_uint(__builtin_amdgcn_fmed3f(a * s, -127.f, 127.f) + 12582912.f), ub = __float_as_uint(__builtin_amdgcn_fmed3f(b * s, -127.f, 127.f) + 12582912.f);
;     const unsigned uc = __float_as_uint(__builtin_amdgcn_fmed3f(c * s, -127.f, 127.f) + 12582912.f), ud = __float_as_uint(__builtin_amdgcn_fmed3f(d * s, -127.f, 127.f) + 12582912.f);
.Lf8t_win8bcd1_b_go:
	v_pk_mul_f32 v[16:17], v[16:17], s[36:37] op_sel_hi:[1,0]
	v_pk_mul_f32 v[18:19], v[18:19], s[36:37] op_sel_hi:[1,0]
	v_pk_mul_f32 v[20:21], v[20:21], s[36:37] op_sel_hi:[1,0]
	v_pk_mul_f32 v[22:23], v[22:23], s[36:37] op_sel_hi:[1,0]
	v_pk_mul_f32 v[24:25], v[24:25], s[36:37] op_sel_hi:[1,0]
	v_pk_mul_f32 v[26:27], v[26:27], s[36:37] op_sel_hi:[1,0]
	v_pk_mul_f32 v[28:29], v[28:29], s[36:37] op_sel_hi:[1,0]
	v_pk_mul_f32 v[30:31], v[30:31], s[36:37] op_sel_hi:[1,0]
	v_pk_mul_f32 v[32:33], v[32:33], s[36:37] op_sel_hi:[1,0]
	v_pk_mul_f32 v[34:35], v[34:35], s[36:37] op_sel_hi:[1,0]
	v_pk_mul_f32 v[36:37], v[36:37], s[36:37] op_sel_hi:[1,0]
	v_pk_mul_f32 v[38:39], v[38:39], s[36:37] op_sel_hi:[1,0]
	v_pk_mul_f32 v[40:41], v[40:41], s[36:37] op_sel_hi:[1,0]
	v_pk_mul_f32 v[42:43], v[42:43], s[36:37] op_sel_hi:[1,0]
	v_pk_mul_f32 v[44:45], v[44:45], s[36:37] op_sel_hi:[1,0]
	v_pk_mul_f32 v[46:47], v[46:47], s[36:37] op_sel_hi:[1,0]
	v_pk_mul_f32 v[48:49], v[48:49], s[36:37] op_sel_hi:[1,0]
	v_pk_mul_f32 v[50:51], v[50:51], s[36:37] op_sel_hi:[1,0]
	v_pk_mul_f32 v[52:53], v[52:53], s[36:37] op_sel_hi:[1,0]
	v_pk_mul_f32 v[54:55], v[54:55], s[36:37] op_sel_hi:[1,0]
	v_pk_mul_f32 v[56:57], v[56:57], s[36:37] op_sel_hi:[1,0]
	v_pk_mul_f32 v[58:59], v[58:59], s[36:37] op_sel_hi:[1,0]
	v_pk_mul_f32 v[60:61], v[60:61], s[36:37] op_sel_hi:[1,0]
	v_pk_mul_f32 v[62:63], v[62:63], s[36:37] op_sel_hi:[1,0]
	v_pk_mul_f32 v[64:65], v[64:65], s[36:37] op_sel_hi:[1,0]
	v_pk_mul_f32 v[66:67], v[66:67], s[36:37] op_sel_hi:[1,0]
	v_pk_mul_f32 v[68:69], v[68:69], s[36:37] op_sel_hi:[1,0]
	v_pk_mul_f32 v[70:71], v[70:71], s[36:37] op_sel_hi:[1,0]
	v_pk_mul_f32 v[144:145], v[144:145], s[36:37] op_sel_hi:[1,0]
	v_pk_mul_f32 v[146:147], v[146:147], s[36:37] op_sel_hi:[1,0]
	v_pk_mul_f32 v[148:149], v[148:149], s[36:37] op_sel_hi:[1,0]
	v_pk_mul_f32 v[150:151], v[150:151], s[36:37] op_sel_hi:[1,0]
	v_med3_f32 v16, v16, s40, v208
	v_med3_f32 v17, v17, s40, v208
	v_med3_f32 v18, v18, s40, v208
	v_med3_f32 v19, v19, s40, v208
	v_med3_f32 v20, v20, s40, v208
	v_med3_f32 v21, v21, s40, v208
	v_med3_f32 v22, v22, s40, v208
	v_med3_f32 v23, v23, s40, v208
	v_med3_f32 v24, v24, s40, v208
	v_med3_f32 v25, v25, s40, v208
	v_med3_f32 v26, v26, s40, v208
	v_med3_f32 v27, v27, s40, v208
	v_med3_f32 v28, v28, s40, v208
	v_med3_f32 v29, v29, s40, v208
	v_med3_f32 v30, v30, s40, v208
	v_med3_f32 v31, v31, s40, v208
	v_med3_f32 v32, v32, s40, v208
	v_med3_f32 v33, v33, s40, v208
	v_med3_f32 v34, v34, s40, v208
	v_med3_f32 v35, v35, s40, v208
	v_med3_f32 v36, v36, s40, v208
	v_med3_f32 v37, v37, s40, v208
	v_med3_f32 v38, v38, s40, v208
	v_med3_f32 v39, v39, s40, v208
	v_med3_f32 v40, v40, s40, v208
	v_med3_f32 v41, v41, s40, v208
	v_med3_f32 v42, v42, s40, v208
	v_med3_f32 v43, v43, s40, v208
	v_med3_f32 v44, v44, s40, v208
	v_med3_f32 v45, v45, s40, v208
	v_med3_f32 v46, v46, s40, v208
	v_med3_f32 v47, v47, s40, v208
	v_med3_f32 v48, v48, s40, v208
	v_med3_f32 v49, v49, s40, v208
	v_med3_f32 v50, v50, s40, v208
	v_med3_f32 v51, v51, s40, v208
	v_med3_f32 v52, v52, s40, v208
	v_med3_f32 v53, v53, s40, v208
	v_med3_f32 v54, v54, s40, v208
	v_med3_f32 v55, v55, s40, v208
	v_med3_f32 v56, v56, s40, v208
	v_med3_f32 v57, v57, s40, v208
	v_med3_f32 v58, v58, s40, v208
	v_med3_f32 v59, v59, s40, v208
	v_med3_f32 v60, v60, s40, v208
	v_med3_f32 v61, v61, s40, v208
	v_med3_f32 v62, v62, s40, v208
	v_med3_f32 v63, v63, s40, v208
	v_med3_f32 v64, v64, s40, v208
	v_med3_f32 v65, v65, s40, v208
	v_med3_f32 v66, v66, s40, v208
	v_med3_f32 v67, v67, s40, v208
	v_med3_f32 v68, v68, s40, v208
	v_med3_f32 v69, v69, s40, v208
	v_med3_f32 v70, v70, s40, v208
	v_med3_f32 v71, v71, s40, v208
	v_med3_f32 v144, v144, s40, v208
	v_med3_f32 v145, v145, s40, v208
	v_med3_f32 v146, v146, s40, v208
	v_med3_f32 v147, v147, s40, v208
	v_med3_f32 v148, v148, s40, v208
	v_med3_f32 v149, v149, s40, v208
	v_med3_f32 v150, v150, s40, v208
	v_med3_f32 v151, v151, s40, v208
	v_pk_add_f32 v[16:17], v[16:17], s[38:39] op_sel_hi:[1,0]
	v_pk_add_f32 v[18:19], v[18:19], s[38:39] op_sel_hi:[1,0]
	v_pk_add_f32 v[20:21], v[20:21], s[38:39] op_sel_hi:[1,0]
	v_pk_add_f32 v[22:23], v[22:23], s[38:39] op_sel_hi:[1,0]
	v_pk_add_f32 v[24:25], v[24:25], s[38:39] op_sel_hi:[1,0]
; #define LAS __attribute__((address_space(3)))
; __device__ __forceinline__ unsigned pk4_f8(float a, float b, float c, float d) { int w = __builtin_amdgcn_cvt_pk_fp8_f32(a, b, 0, false); w = __builtin_amdgcn_cvt_pk_fp8_f32(c, d, w, true); return (unsigned)w; }
; #define LDS_WAIT() asm volatile("s_waitcnt lgkmcnt(0)" ::: "memory")
; __device__ __forceinline__ unsigned pk4_i8(float a, float b, float c, float d, float s) {
;     ...
;     return (ua & 0xffu) | ((ub & 0xffu) << 8) | ((uc & 0xffu) << 16) | (ud << 24);
;     ...
;         for (int j = 0; j < 2; ++j) { const int n = (lane >> 2) + 16 * j; const LAS float* sp = scr + (16 * c) * 33 + n;
;             u32x4 o;
;             if (QI8) { o.x = pk4_i8(sp[0 * 33], sp[1 * 33], sp[2 * 33], sp[3 * 33], scl); o.y = pk4_i8(sp[4 * 33], sp[5 * 33], sp[6 * 33], sp[7 * 33], scl);
;                 o.z = pk4_i8(sp[8 * 33], sp[9 * 33], sp[10 * 33], sp[11 * 33], scl); o.w = pk4_i8(sp[12 * 33], sp[13 * 33], sp[14 * 33], sp[15 * 33], scl); }
;             else {
;             o.x = pk4_f8(sp[0 * 33] * scl, sp[1 * 33] * scl, sp[2 * 33] * scl, sp[3 * 33] * scl); o.y = pk4_f8(sp[4 * 33] * scl, sp[5 * 33] * scl, sp[6 * 33] * scl, sp[7 * 33] * scl);
;             o.z = pk4_f8(sp[8 * 33] * scl, sp[9 * 33] * scl, sp[10 * 33] * scl, sp[11 * 33] * scl); o.w = pk4_f8(sp[12 * 33] * scl, sp[13 * 33] * scl, sp[14 * 33] * scl, sp[15 * 33] * scl); }
;             *(u32x4*)(WT + (size_t)(dr0 + n) * K + k0 + 16 * c) = o; }
;         LDS_WAIT(); asm volatile("" ::: "memory"); }
	v_pk_add_f32 v[26:27], v[26:27], s[38:39] op_sel_hi:[1,0]
	v_pk_add_f32 v[28:29], v[28:29], s[38:39] op_sel_hi:[1,0]
	v_pk_add_f32 v[30:31], v[30:31], s[38:39] op_sel_hi:[1,0]
	v_pk_add_f32 v[32:33], v[32:33], s[38:39] op_sel_hi:[1,0]
	v_pk_add_f32 v[34:35], v[34:35], s[38:39] op_sel_hi:[1,0]
	v_pk_add_f32 v[36:37], v[36:37], s[38:39] op_sel_hi:[1,0]
	v_pk_add_f32 v[38:39], v[38:39], s[38:39] op_sel_hi:[1,0]
	v_pk_add_f32 v[40:41], v[40:41], s[38:39] op_sel_hi:[1,0]
	v_pk_add_f32 v[42:43], v[42:43], s[38:39] op_sel_hi:[1,0]
	v_pk_add_f32 v[44:45], v[44:45], s[38:39] op_sel_hi:[1,0]
	v_pk_add_f32 v[46:47], v[46:47], s[38:39] op_sel_hi:[1,0]
	v_pk_add_f32 v[48:49], v[48:49], s[38:39] op_sel_hi:[1,0]
	v_pk_add_f32 v[50:51], v[50:51], s[38:39] op_sel_hi:[1,0]
	v_pk_add_f32 v[52:53], v[52:53], s[38:39] op_sel_hi:[1,0]
	v_pk_add_f32 v[54:55], v[54:55], s[38:39] op_sel_hi:[1,0]
	v_pk_add_f32 v[56:57], v[56:57], s[38:39] op_sel_hi:[1,0]
	v_pk_add_f32 v[58:59], v[58:59], s[38:39] op_sel_hi:[1,0]
	v_pk_add_f32 v[60:61], v[60:61], s[38:39] op_sel_hi:[1,0]
	v_pk_add_f32 v[62:63], v[62:63], s[38:39] op_sel_hi:[1,0]
	v_pk_add_f32 v[64:65], v[64:65], s[38:39] op_sel_hi:[1,0]
	v_pk_add_f32 v[66:67], v[66:67], s[38:39] op_sel_hi:[1,0]
	v_pk_add_f32 v[68:69], v[68:69], s[38:39] op_sel_hi:[1,0]
	v_pk_add_f32 v[70:71], v[70:71], s[38:39] op_sel_hi:[1,0]
	v_pk_add_f32 v[144:145], v[144:145], s[38:39] op_sel_hi:[1,0]
	v_pk_add_f32 v[146:147], v[146:147], s[38:39] op_sel_hi:[1,0]
	v_pk_add_f32 v[148:149], v[148:149], s[38:39] op_sel_hi:[1,0]
	v_pk_add_f32 v[150:151], v[150:151], s[38:39] op_sel_hi:[1,0]
	v_perm_b32 v196, v20, v16, s41
	v_perm_b32 v197, v28, v24, s41
	v_perm_b32 v180, v197, v196, s42
	v_perm_b32 v196, v36, v32, s41
	v_perm_b32 v197, v44, v40, s41
	v_perm_b32 v181, v197, v196, s42
	v_perm_b32 v196, v52, v48, s41
	v_perm_b32 v197, v60, v56, s41
	v_perm_b32 v182, v197, v196, s42
	v_perm_b32 v196, v68, v64, s41
	v_perm_b32 v197, v148, v144, s41
	v_perm_b32 v183, v197, v196, s42
	v_perm_b32 v196, v21, v17, s41
	v_perm_b32 v197, v29, v25, s41
	v_perm_b32 v184, v197, v196, s42
	v_perm_b32 v196, v37, v33, s41
	v_perm_b32 v197, v45, v41, s41
	v_perm_b32 v185, v197, v196, s42
	v_perm_b32 v196, v53, v49, s41
	v_perm_b32 v197, v61, v57, s41
	v_perm_b32 v186, v197, v196, s42
	v_perm_b32 v196, v69, v65, s41
	v_perm_b32 v197, v149, v145, s41
	v_perm_b32 v187, v197, v196, s42
	v_perm_b32 v196, v22, v18, s41
	v_perm_b32 v197, v30, v26, s41
	v_perm_b32 v188, v197, v196, s42
	v_perm_b32 v196, v38, v34, s41
	v_perm_b32 v197, v46, v42, s41
	v_perm_b32 v189, v197, v196, s42
	v_perm_b32 v196, v54, v50, s41
	v_perm_b32 v197, v62, v58, s41
	v_perm_b32 v190, v197, v196, s42
	v_perm_b32 v196, v70, v66, s41
	v_perm_b32 v197, v150, v146, s41
	v_perm_b32 v191, v197, v196, s42
	v_perm_b32 v196, v23, v19, s41
	v_perm_b32 v197, v31, v27, s41
	v_perm_b32 v192, v197, v196, s42
	v_perm_b32 v196, v39, v35, s41
	v_perm_b32 v197, v47, v43, s41
	v_perm_b32 v193, v197, v196, s42
	v_perm_b32 v196, v55, v51, s41
	v_perm_b32 v197, v63, v59, s41
	v_perm_b32 v194, v197, v196, s42
	v_perm_b32 v196, v71, v67, s41
	v_perm_b32 v197, v151, v147, s41
	v_perm_b32 v195, v197, v196, s42
	ds_write_b128 v205, v[180:183] offset:36864
	ds_write_b128 v205, v[184:187] offset:37008
	ds_write_b128 v205, v[188:191] offset:37152
	ds_write_b128 v205, v[192:195] offset:37296
	s_mov_b32 s26, s63
	s_add_i32 s26, s26, s17
	s_mul_i32 s26, s26, 0x1000
	s_add_u32 s26, s26, s62
	s_add_u32 s54, s56, s26
	s_addc_u32 s55, s57, 0
	s_waitcnt lgkmcnt(0)
	s_barrier
	ds_read_b128 v[180:183], v206 offset:36864
	ds_read_b128 v[184:187], v206 offset:38016
	ds_read_b128 v[188:191], v206 offset:39168
	ds_read_b128 v[192:195], v206 offset:40320
	s_waitcnt lgkmcnt(3)
	global_store_dwordx4 v207, v[180:183], s[54:55]
	s_add_u32 s54, s54, 0x8000
	s_addc_u32 s55, s55, 0
	s_waitcnt lgkmcnt(2)
	global_store_dwordx4 v207, v[184:187], s[54:55]
	s_add_u32 s54, s54, 0x8000
	s_addc_u32 s55, s55, 0
	s_waitcnt lgkmcnt(1)
	global_store_dwordx4 v207, v[188:191], s[54:55]
	s_add_u32 s54, s54, 0x8000
	s_addc_u32 s55, s55, 0
	s_waitcnt lgkmcnt(0)
	global_store_dwordx4 v207, v[192:195], s[54:55]
	s_mov_b32 s19, s64
	s_cmp_lt_u32 s19, 0x200
	s_cbranch_scc1 .Lf8t_win8bcd1_loop

; #define LAS __attribute__((address_space(3)))
;     if (ldw == 0) ldw = N;
;     LAS float* scr = (LAS float*)(F.lds + F.wave * 16384); const int lane = F.lane;
;     const int nblk = N / 32, nitems = (K / 64) * nblk;
;     for (int item = F.gw; item < nitems; item += F.NGW) { const int kb = item / nblk, nb = item % nblk, k0 = 64 * kb, n0 = 32 * nb;
;         int dr0 = n0; if (MAP == 1) { if (n0 < DFF) dr0 = (n0 >> 7) * 256 + (n0 & 127); else { const int uo = n0 - DFF; dr0 = (uo >> 7) * 256 + 128 + (uo & 127); } }
; #pragma unroll 8
;         for (int i = 0; i < 32; ++i) { const int kk = 2 * i + (lane >> 5); scr[kk * 33 + (lane & 31)] = W[(size_t)(k0 + kk) * ldw + n0 + (lane & 31)]; }
; __device__ __forceinline__ void p0_prologue(Frame& F) {
;     ...
;     transpose_f8_matrix<0, true>(F, F.in[I_WOUT], D, D, F.ws + WS_WOUT, I8_WOUT);
.LBB0_67:
	s_andn2_b64 vcc, exec, s[6:7]
	s_cbranch_vccnz .LBB0_72
	s_barrier
	s_load_dwordx2 s[50:51], s[74:75], 0xd8
	v_readlane_b32 s16, v240, 2
	v_lshlrev_b32_e32 v204, 4, v178
	v_mov_b32_e32 v208, 0x42fe0000
	s_mov_b32 s36, 0x45559673
	s_mov_b32 s37, 0
	s_mov_b32 s38, 0x4b400000
	s_mov_b32 s39, 0
	s_mov_b32 s40, 0xc2fe0000
	s_mov_b32 s41, 0x0c0c0400
	s_mov_b32 s42, 0x05040100
	s_lshl_b32 s17, s16, 5
	v_mul_u32_u24_e32 v205, 0x240, v178
	s_lshl_b32 s18, s16, 4
	v_add_u32_e32 v205, s18, v205
	v_lshrrev_b32_e32 v196, 3, v178
	v_and_b32_e32 v197, 7, v178
	s_lshl_b32 s18, s16, 5
	v_add_u32_e32 v198, s18, v196
	v_mul_u32_u24_e32 v206, 0x90, v198
	v_lshl_add_u32 v206, v197, 4, v206
	v_mul_u32_u24_e32 v207, 0x1000, v196
	v_lshl_add_u32 v207, v197, 4, v207
	s_lshl_b32 s16, s16, 4
	s_waitcnt lgkmcnt(0)
	s_add_u32 s56, s90, 0x69d00000
	s_addc_u32 s57, s91, 0
	s_mov_b32 s19, s2
	s_cmp_lt_u32 s19, 0x200
	s_cbranch_scc0 .Lf8t_wout0_end
	s_mul_hi_u32 s20, s19, 0x10000000
	s_mul_i32 s21, s20, 16
	s_sub_i32 s21, s19, s21
	s_lshl_b32 s60, s20, 7
	s_lshl_b32 s61, s21, 8
	s_add_i32 s24, s60, s16
	s_mul_i32 s24, s24, 0x4000
	s_lshl_b32 s25, s61, 2
	s_add_u32 s24, s24, s25
	s_add_u32 s52, s50, s24
	s_addc_u32 s53, s51, 0
	global_load_dwordx4 v[80:83], v204, s[52:53]
	s_add_u32 s52, s52, 0x4000
	s_addc_u32 s53, s53, 0
	global_load_dwordx4 v[84:87], v204, s[52:53]
	s_add_u32 s52, s52, 0x4000
	s_addc_u32 s53, s53, 0
	global_load_dwordx4 v[88:91], v204, s[52:53]
	s_add_u32 s52, s52, 0x4000
	s_addc_u32 s53, s53, 0
	global_load_dwordx4 v[92:95], v204, s[52:53]
	s_add_u32 s52, s52, 0x4000
	s_addc_u32 s53, s53, 0
	global_load_dwordx4 v[96:99], v204, s[52:53]
	s_add_u32 s52, s52, 0x4000
	s_addc_u32 s53, s53, 0
	global_load_dwordx4 v[100:103], v204, s[52:53]
	s_add_u32 s52, s52, 0x4000
	s_addc_u32 s53, s53, 0
	global_load_dwordx4 v[104:107], v204, s[52:53]
	s_add_u32 s52, s52, 0x4000
	s_addc_u32 s53, s53, 0
	global_load_dwordx4 v[108:111], v204, s[52:53]
	s_add_u32 s52, s52, 0x4000
	s_addc_u32 s53, s53, 0
	global_load_dwordx4 v[112:115], v204, s[52:53]
	s_add_u32 s52, s52, 0x4000
	s_addc_u32 s53, s53, 0
	global_load_dwordx4 v[116:119], v204, s[52:53]
	s_add_u32 s52, s52, 0x4000
	s_addc_u32 s53, s53, 0
	global_load_dwordx4 v[120:123], v204, s[52:53]
	s_add_u32 s52, s52, 0x4000
	s_addc_u32 s53, s53, 0
	global_load_dwordx4 v[124:127], v204, s[52:53]
	s_add_u32 s52, s52, 0x4000
	s_addc_u32 s53, s53, 0
	global_load_dwordx4 v[128:131], v204, s[52:53]
	s_add_u32 s52, s52, 0x4000
	s_addc_u32 s53, s53, 0
	global_load_dwordx4 v[132:135], v204, s[52:53]
	s_add_u32 s52, s52, 0x4000
	s_addc_u32 s53, s53, 0
	global_load_dwordx4 v[136:139], v204, s[52:53]
	s_add_u32 s52, s52, 0x4000
	s_addc_u32 s53, s53, 0
	global_load_dwordx4 v[140:143], v204, s[52:53]
	s_mov_b32 s58, 1
.Lf8t_wout0_loop:
	s_add_i32 s64, s19, s96
	s_cmp_lt_u32 s64, 0x200
	s_cbranch_scc0 .Lf8t_wout0_a_nonext
	s_mul_hi_u32 s20, s64, 0x10000000
	s_mul_i32 s21, s20, 16
	s_sub_i32 s21, s64, s21
	s_lshl_b32 s62, s20, 7
	s_lshl_b32 s63, s21, 8
	s_add_i32 s24, s62, s16
	s_mul_i32 s24, s24, 0x4000
	s_lshl_b32 s25, s63, 2
	s_add_u32 s24, s24, s25
	s_add_u32 s52, s50, s24
	s_addc_u32 s53, s51, 0
	global_load_dwordx4 v[16:19], v204, s[52:53]
	s_add_u32 s52, s52, 0x4000
	s_addc_u32 s53, s53, 0
	global_load_dwordx4 v[20:23], v204, s[52:53]
	s_add_u32 s52, s52, 0x4000
	s_addc_u32 s53, s53, 0
	global_load_dwordx4 v[24:27], v204, s[52:53]
	s_add_u32 s52, s52, 0x4000
	s_addc_u32 s53, s53, 0
	global_load_dwordx4 v[28:31], v204, s[52:53]
	s_add_u32 s52, s52, 0x4000
	s_addc_u32 s53, s53, 0
	global_load_dwordx4 v[32:35], v204, s[52:53]
	s_add_u32 s52, s52, 0x4000
	s_addc_u32 s53, s53, 0
	global_load_dwordx4 v[36:39], v204, s[52:53]
	s_add_u32 s52, s52, 0x4000
	s_addc_u32 s53, s53, 0
	global_load_dwordx4 v[40:43], v204, s[52:53]
	s_add_u32 s52, s52, 0x4000
	s_addc_u32 s53, s53, 0
	global_load_dwordx4 v[44:47], v204, s[52:53]
	s_add_u32 s52, s52, 0x4000
	s_addc_u32 s53, s53, 0
	global_load_dwordx4 v[48:51], v204, s[52:53]
	s_add_u32 s52, s52, 0x4000
	s_addc_u32 s53, s53, 0
	global_load_dwordx4 v[52:55], v204, s[52:53]
	s_add_u32 s52, s52, 0x4000
	s_addc_u32 s53, s53, 0
	global_load_dwordx4 v[56:59], v204, s[52:53]
	s_add_u32 s52, s52, 0x4000
	s_addc_u32 s53, s53, 0
	global_load_dwordx4 v[60:63], v204, s[52:53]
	s_add_u32 s52, s52, 0x4000
	s_addc_u32 s53, s53, 0
	global_load_dwordx4 v[64:67], v204, s[52:53]
	s_add_u32 s52, s52, 0x4000
	s_addc_u32 s53, s53, 0
	global_load_dwordx4 v[68:71], v204, s[52:53]
	s_add_u32 s52, s52, 0x4000
	s_addc_u32 s53, s53, 0
	global_load_dwordx4 v[144:147], v204, s[52:53]
	s_add_u32 s52, s52, 0x4000
	s_addc_u32 s53, s53, 0
	global_load_dwordx4 v[148:151], v204, s[52:53]
	s_cmp_eq_u32 s58, 1
	s_cbranch_scc1 .Lf8t_wout0_a_first
	s_waitcnt vmcnt(20)
	s_branch .Lf8t_wout0_a_go

; __device__ __forceinline__ unsigned pk4_i8(float a, float b, float c, float d, float s) {
;     const unsigned ua = __float_as_uint(__builtin_amdgcn_fmed3f(a * s, -127.f, 127.f) + 12582912.f), ub = __float_as_uint(__builtin_amdgcn_fmed3f(b * s, -127.f, 127.f) + 12582912.f);
;     const unsigned uc = __float_as_uint(__builtin_amdgcn_fmed3f(c * s, -127.f, 127.f) + 12582912.f), ud = __float_as_uint(__builtin_amdgcn_fmed3f(d * s, -127.f, 127.f) + 12582912.f);
.Lf8t_wout0_a_go:
	s_mov_b32 s58, 0
	v_pk_mul_f32 v[80:81], v[80:81], s[36:37] op_sel_hi:[1,0]
	v_pk_mul_f32 v[82:83], v[82:83], s[36:37] op_sel_hi:[1,0]
	v_pk_mul_f32 v[84:85], v[84:85], s[36:37] op_sel_hi:[1,0]
	v_pk_mul_f32 v[86:87], v[86:87], s[36:37] op_sel_hi:[1,0]
	v_pk_mul_f32 v[88:89], v[88:89], s[36:37] op_sel_hi:[1,0]
	v_pk_mul_f32 v[90:91], v[90:91], s[36:37] op_sel_hi:[1,0]
	v_pk_mul_f32 v[92:93], v[92:93], s[36:37] op_sel_hi:[1,0]
	v_pk_mul_f32 v[94:95], v[94:95], s[36:37] op_sel_hi:[1,0]
	v_pk_mul_f32 v[96:97], v[96:97], s[36:37] op_sel_hi:[1,0]
	v_pk_mul_f32 v[98:99], v[98:99], s[36:37] op_sel_hi:[1,0]
	v_pk_mul_f32 v[100:101], v[100:101], s[36:37] op_sel_hi:[1,0]
	v_pk_mul_f32 v[102:103], v[102:103], s[36:37] op_sel_hi:[1,0]
	v_pk_mul_f32 v[104:105], v[104:105], s[36:37] op_sel_hi:[1,0]
	v_pk_mul_f32 v[106:107], v[106:107], s[36:37] op_sel_hi:[1,0]
	v_pk_mul_f32 v[108:109], v[108:109], s[36:37] op_sel_hi:[1,0]
	v_pk_mul_f32 v[110:111], v[110:111], s[36:37] op_sel_hi:[1,0]
	v_pk_mul_f32 v[112:113], v[112:113], s[36:37] op_sel_hi:[1,0]
	v_pk_mul_f32 v[114:115], v[114:115], s[36:37] op_sel_hi:[1,0]
	v_pk_mul_f32 v[116:117], v[116:117], s[36:37] op_sel_hi:[1,0]
	v_pk_mul_f32 v[118:119], v[118:119], s[36:37] op_sel_hi:[1,0]
	v_pk_mul_f32 v[120:121], v[120:121], s[36:37] op_sel_hi:[1,0]
	v_pk_mul_f32 v[122:123], v[122:123], s[36:37] op_sel_hi:[1,0]
	v_pk_mul_f32 v[124:125], v[124:125], s[36:37] op_sel_hi:[1,0]
	v_pk_mul_f32 v[126:127], v[126:127], s[36:37] op_sel_hi:[1,0]
	v_pk_mul_f32 v[128:129], v[128:129], s[36:37] op_sel_hi:[1,0]
	v_pk_mul_f32 v[130:131], v[130:131], s[36:37] op_sel_hi:[1,0]
	v_pk_mul_f32 v[132:133], v[132:133], s[36:37] op_sel_hi:[1,0]
	v_pk_mul_f32 v[134:135], v[134:135], s[36:37] op_sel_hi:[1,0]
	v_pk_mul_f32 v[136:137], v[136:137], s[36:37] op_sel_hi:[1,0]
	v_pk_mul_f32 v[138:139], v[138:139], s[36:37] op_sel_hi:[1,0]
	v_pk_mul_f32 v[140:141], v[140:141], s[36:37] op_sel_hi:[1,0]
	v_pk_mul_f32 v[142:143], v[142:143], s[36:37] op_sel_hi:[1,0]
	v_med3_f32 v80, v80, s40, v208
	v_med3_f32 v81, v81, s40, v208
	v_med3_f32 v82, v82, s40, v208
	v_med3_f32 v83, v83, s40, v208
	v_med3_f32 v84, v84, s40, v208
	v_med3_f32 v85, v85, s40, v208
	v_med3_f32 v86, v86, s40, v208
	v_med3_f32 v87, v87, s40, v208
	v_med3_f32 v88, v88, s40, v208
	v_med3_f32 v89, v89, s40, v208
	v_med3_f32 v90, v90, s40, v208
	v_med3_f32 v91, v91, s40, v208
	v_med3_f32 v92, v92, s40, v208
	v_med3_f32 v93, v93, s40, v208
	v_med3_f32 v94, v94, s40, v208
	v_med3_f32 v95, v95, s40, v208
	v_med3_f32 v96, v96, s40, v208
	v_med3_f32 v97, v97, s40, v208
	v_med3_f32 v98, v98, s40, v208
	v_med3_f32 v99, v99, s40, v208
	v_med3_f32 v100, v100, s40, v208
	v_med3_f32 v101, v101, s40, v208
	v_med3_f32 v102, v102, s40, v208
	v_med3_f32 v103, v103, s40, v208
	v_med3_f32 v104, v104, s40, v208
	v_med3_f32 v105, v105, s40, v208
	v_med3_f32 v106, v106, s40, v208
	v_med3_f32 v107, v107, s40, v208
	v_med3_f32 v108, v108, s40, v208
	v_med3_f32 v109, v109, s40, v208
	v_med3_f32 v110, v110, s40, v208
	v_med3_f32 v111, v111, s40, v208
	v_med3_f32 v112, v112, s40, v208
	v_med3_f32 v113, v113, s40, v208
	v_med3_f32 v114, v114, s40, v208
	v_med3_f32 v115, v115, s40, v208
	v_med3_f32 v116, v116, s40, v208
	v_med3_f32 v117, v117, s40, v208
	v_med3_f32 v118, v118, s40, v208
	v_med3_f32 v119, v119, s40, v208
	v_med3_f32 v120, v120, s40, v208
	v_med3_f32 v121, v121, s40, v208
	v_med3_f32 v122, v122, s40, v208
	v_med3_f32 v123, v123, s40, v208
	v_med3_f32 v124, v124, s40, v208
	v_med3_f32 v125, v125, s40, v208
	v_med3_f32 v126, v126, s40, v208
	v_med3_f32 v127, v127, s40, v208
	v_med3_f32 v128, v128, s40, v208
	v_med3_f32 v129, v129, s40, v208
	v_med3_f32 v130, v130, s40, v208
	v_med3_f32 v131, v131, s40, v208
	v_med3_f32 v132, v132, s40, v208
	v_med3_f32 v133, v133, s40, v208
	v_med3_f32 v134, v134, s40, v208
	v_med3_f32 v135, v135, s40, v208
	v_med3_f32 v136, v136, s40, v208
	v_med3_f32 v137, v137, s40, v208
	v_med3_f32 v138, v138, s40, v208
	v_med3_f32 v139, v139, s40, v208
	v_med3_f32 v140, v140, s40, v208
	v_med3_f32 v141, v141, s40, v208
	v_med3_f32 v142, v142, s40, v208
	v_med3_f32 v143, v143, s40, v208
	v_pk_add_f32 v[80:81], v[80:81], s[38:39] op_sel_hi:[1,0]
	v_pk_add_f32 v[82:83], v[82:83], s[38:39] op_sel_hi:[1,0]
	v_pk_add_f32 v[84:85], v[84:85], s[38:39] op_sel_hi:[1,0]
	v_pk_add_f32 v[86:87], v[86:87], s[38:39] op_sel_hi:[1,0]
	v_pk_add_f32 v[88:89], v[88:89], s[38:39] op_sel_hi:[1,0]
	v_pk_add_f32 v[90:91], v[90:91], s[38:39] op_sel_hi:[1,0]
	v_pk_add_f32 v[92:93], v[92:93], s[38:39] op_sel_hi:[1,0]
	v_pk_add_f32 v[94:95], v[94:95], s[38:39] op_sel_hi:[1,0]
	v_pk_add_f32 v[96:97], v[96:97], s[38:39] op_sel_hi:[1,0]
	v_pk_add_f32 v[98:99], v[98:99], s[38:39] op_sel_hi:[1,0]
	v_pk_add_f32 v[100:101], v[100:101], s[38:39] op_sel_hi:[1,0]
	v_pk_add_f32 v[102:103], v[102:103], s[38:39] op_sel_hi:[1,0]
	v_pk_add_f32 v[104:105], v[104:105], s[38:39] op_sel_hi:[1,0]
	v_pk_add_f32 v[106:107], v[106:107], s[38:39] op_sel_hi:[1,0]
	v_pk_add_f32 v[108:109], v[108:109], s[38:39] op_sel_hi:[1,0]
	v_pk_add_f32 v[110:111], v[110:111], s[38:39] op_sel_hi:[1,0]
	v_pk_add_f32 v[112:113], v[112:113], s[38:39] op_sel_hi:[1,0]
	v_pk_add_f32 v[114:115], v[114:115], s[38:39] op_sel_hi:[1,0]
	v_pk_add_f32 v[116:117], v[116:117], s[38:39] op_sel_hi:[1,0]
	v_pk_add_f32 v[118:119], v[118:119], s[38:39] op_sel_hi:[1,0]
; #define LAS __attribute__((address_space(3)))
; __device__ __forceinline__ unsigned pk4_f8(float a, float b, float c, float d) { int w = __builtin_amdgcn_cvt_pk_fp8_f32(a, b, 0, false); w = __builtin_amdgcn_cvt_pk_fp8_f32(c, d, w, true); return (unsigned)w; }
; #define LDS_WAIT() asm volatile("s_waitcnt lgkmcnt(0)" ::: "memory")
;     ...
;     for (int item = F.gw; item < nitems; item += F.NGW) { const int kb = item / nblk, nb = item % nblk, k0 = 64 * kb, n0 = 32 * nb;
;         int dr0 = n0; if (MAP == 1) { if (n0 < DFF) dr0 = (n0 >> 7) * 256 + (n0 & 127); else { const int uo = n0 - DFF; dr0 = (uo >> 7) * 256 + 128 + (uo & 127); } }
; #pragma unroll 8
;         for (int i = 0; i < 32; ++i) { const int kk = 2 * i + (lane >> 5); scr[kk * 33 + (lane & 31)] = W[(size_t)(k0 + kk) * ldw + n0 + (lane & 31)]; }
;         LDS_WAIT(); asm volatile("" ::: "memory");
;         const int c = lane & 3;
; #pragma unroll
;         for (int j = 0; j < 2; ++j) { const int n = (lane >> 2) + 16 * j; const LAS float* sp = scr + (16 * c) * 33 + n;
;             u32x4 o;
;             if (QI8) { o.x = pk4_i8(sp[0 * 33], sp[1 * 33], sp[2 * 33], sp[3 * 33], scl); o.y = pk4_i8(sp[4 * 33], sp[5 * 33], sp[6 * 33], sp[7 * 33], scl);
;                 o.z = pk4_i8(sp[8 * 33], sp[9 * 33], sp[10 * 33], sp[11 * 33], scl); o.w = pk4_i8(sp[12 * 33], sp[13 * 33], sp[14 * 33], sp[15 * 33], scl); }
;             else {
;             o.x = pk4_f8(sp[0 * 33] * scl, sp[1 * 33] * scl, sp[2 * 33] * scl, sp[3 * 33] * scl); o.y = pk4_f8(sp[4 * 33] * scl, sp[5 * 33] * scl, sp[6 * 33] * scl, sp[7 * 33] * scl);
;             o.z = pk4_f8(sp[8 * 33] * scl, sp[9 * 33] * scl, sp[10 * 33] * scl, sp[11 * 33] * scl); o.w = pk4_f8(sp[12 * 33] * scl, sp[13 * 33] * scl, sp[14 * 33] * scl, sp[15 * 33] * scl); }
;             *(u32x4*)(WT + (size_t)(dr0 + n) * K + k0 + 16 * c) = o; }
	v_pk_add_f32 v[120:121], v[120:121], s[38:39] op_sel_hi:[1,0]
	v_pk_add_f32 v[122:123], v[122:123], s[38:39] op_sel_hi:[1,0]
	v_pk_add_f32 v[124:125], v[124:125], s[38:39] op_sel_hi:[1,0]
	v_pk_add_f32 v[126:127], v[126:127], s[38:39] op_sel_hi:[1,0]
	v_pk_add_f32 v[128:129], v[128:129], s[38:39] op_sel_hi:[1,0]
	v_pk_add_f32 v[130:131], v[130:131], s[38:39] op_sel_hi:[1,0]
	v_pk_add_f32 v[132:133], v[132:133], s[38:39] op_sel_hi:[1,0]
	v_pk_add_f32 v[134:135], v[134:135], s[38:39] op_sel_hi:[1,0]
	v_pk_add_f32 v[136:137], v[136:137], s[38:39] op_sel_hi:[1,0]
	v_pk_add_f32 v[138:139], v[138:139], s[38:39] op_sel_hi:[1,0]
	v_pk_add_f32 v[140:141], v[140:141], s[38:39] op_sel_hi:[1,0]
	v_pk_add_f32 v[142:143], v[142:143], s[38:39] op_sel_hi:[1,0]
	v_perm_b32 v196, v84, v80, s41
	v_perm_b32 v197, v92, v88, s41
	v_perm_b32 v180, v197, v196, s42
	v_perm_b32 v196, v100, v96, s41
	v_perm_b32 v197, v108, v104, s41
	v_perm_b32 v181, v197, v196, s42
	v_perm_b32 v196, v116, v112, s41
	v_perm_b32 v197, v124, v120, s41
	v_perm_b32 v182, v197, v196, s42
	v_perm_b32 v196, v132, v128, s41
	v_perm_b32 v197, v140, v136, s41
	v_perm_b32 v183, v197, v196, s42
	v_perm_b32 v196, v85, v81, s41
	v_perm_b32 v197, v93, v89, s41
	v_perm_b32 v184, v197, v196, s42
	v_perm_b32 v196, v101, v97, s41
	v_perm_b32 v197, v109, v105, s41
	v_perm_b32 v185, v197, v196, s42
	v_perm_b32 v196, v117, v113, s41
	v_perm_b32 v197, v125, v121, s41
	v_perm_b32 v186, v197, v196, s42
	v_perm_b32 v196, v133, v129, s41
	v_perm_b32 v197, v141, v137, s41
	v_perm_b32 v187, v197, v196, s42
	v_perm_b32 v196, v86, v82, s41
	v_perm_b32 v197, v94, v90, s41
	v_perm_b32 v188, v197, v196, s42
	v_perm_b32 v196, v102, v98, s41
	v_perm_b32 v197, v110, v106, s41
	v_perm_b32 v189, v197, v196, s42
	v_perm_b32 v196, v118, v114, s41
	v_perm_b32 v197, v126, v122, s41
	v_perm_b32 v190, v197, v196, s42
	v_perm_b32 v196, v134, v130, s41
	v_perm_b32 v197, v142, v138, s41
	v_perm_b32 v191, v197, v196, s42
	v_perm_b32 v196, v87, v83, s41
	v_perm_b32 v197, v95, v91, s41
	v_perm_b32 v192, v197, v196, s42
	v_perm_b32 v196, v103, v99, s41
	v_perm_b32 v197, v111, v107, s41
	v_perm_b32 v193, v197, v196, s42
	v_perm_b32 v196, v119, v115, s41
	v_perm_b32 v197, v127, v123, s41
	v_perm_b32 v194, v197, v196, s42
	v_perm_b32 v196, v135, v131, s41
	v_perm_b32 v197, v143, v139, s41
	v_perm_b32 v195, v197, v196, s42
	ds_write_b128 v205, v[180:183] offset:0
	ds_write_b128 v205, v[184:187] offset:144
	ds_write_b128 v205, v[188:191] offset:288
	ds_write_b128 v205, v[192:195] offset:432
	s_mov_b32 s26, s61
	s_add_i32 s26, s26, s17
	s_mul_i32 s26, s26, 0x1000
	s_add_u32 s26, s26, s60
	s_add_u32 s54, s56, s26
	s_addc_u32 s55, s57, 0
	s_waitcnt lgkmcnt(0)
	s_barrier
	ds_read_b128 v[180:183], v206 offset:0
	ds_read_b128 v[184:187], v206 offset:1152
	ds_read_b128 v[188:191], v206 offset:2304
	ds_read_b128 v[192:195], v206 offset:3456
	s_waitcnt lgkmcnt(3)
	global_store_dwordx4 v207, v[180:183], s[54:55]
	s_add_u32 s54, s54, 0x8000
	s_addc_u32 s55, s55, 0
	s_waitcnt lgkmcnt(2)
	global_store_dwordx4 v207, v[184:187], s[54:55]
	s_add_u32 s54, s54, 0x8000
	s_addc_u32 s55, s55, 0
	s_waitcnt lgkmcnt(1)
	global_store_dwordx4 v207, v[188:191], s[54:55]
	s_add_u32 s54, s54, 0x8000
	s_addc_u32 s55, s55, 0
	s_waitcnt lgkmcnt(0)
	global_store_dwordx4 v207, v[192:195], s[54:55]
	s_mov_b32 s19, s64
	s_cmp_lt_u32 s19, 0x200
	s_cbranch_scc0 .Lf8t_wout0_end
	s_add_i32 s64, s19, s96
	s_cmp_lt_u32 s64, 0x200
	s_cbranch_scc0 .Lf8t_wout0_b_nonext
	s_mul_hi_u32 s20, s64, 0x10000000
	s_mul_i32 s21, s20, 16
	s_sub_i32 s21, s64, s21
	s_lshl_b32 s60, s20, 7
	s_lshl_b32 s61, s21, 8
	s_add_i32 s24, s60, s16
	s_mul_i32 s24, s24, 0x4000
	s_lshl_b32 s25, s61, 2
	s_add_u32 s24, s24, s25
	s_add_u32 s52, s50, s24
	s_addc_u32 s53, s51, 0
	global_load_dwordx4 v[80:83], v204, s[52:53]
	s_add_u32 s52, s52, 0x4000
	s_addc_u32 s53, s53, 0
	global_load_dwordx4 v[84:87], v204, s[52:53]
	s_add_u32 s52, s52, 0x4000
	s_addc_u32 s53, s53, 0
	global_load_dwordx4 v[88:91], v204, s[52:53]
	s_add_u32 s52, s52, 0x4000
	s_addc_u32 s53, s53, 0
	global_load_dwordx4 v[92:95], v204, s[52:53]
	s_add_u32 s52, s52, 0x4000
	s_addc_u32 s53, s53, 0
	global_load_dwordx4 v[96:99], v204, s[52:53]
	s_add_u32 s52, s52, 0x4000
	s_addc_u32 s53, s53, 0
	global_load_dwordx4 v[100:103], v204, s[52:53]
	s_add_u32 s52, s52, 0x4000
	s_addc_u32 s53, s53, 0
	global_load_dwordx4 v[104:107], v204, s[52:53]
	s_add_u32 s52, s52, 0x4000
	s_addc_u32 s53, s53, 0
	global_load_dwordx4 v[108:111], v204, s[52:53]
	s_add_u32 s52, s52, 0x4000
	s_addc_u32 s53, s53, 0
	global_load_dwordx4 v[112:115], v204, s[52:53]
	s_add_u32 s52, s52, 0x4000
	s_addc_u32 s53, s53, 0
	global_load_dwordx4 v[116:119], v204, s[52:53]
	s_add_u32 s52, s52, 0x4000
	s_addc_u32 s53, s53, 0
	global_load_dwordx4 v[120:123], v204, s[52:53]
	s_add_u32 s52, s52, 0x4000
	s_addc_u32 s53, s53, 0
	global_load_dwordx4 v[124:127], v204, s[52:53]
	s_add_u32 s52, s52, 0x4000
	s_addc_u32 s53, s53, 0
	global_load_dwordx4 v[128:131], v204, s[52:53]
	s_add_u32 s52, s52, 0x4000
	s_addc_u32 s53, s53, 0
	global_load_dwordx4 v[132:135], v204, s[52:53]
	s_add_u32 s52, s52, 0x4000
	s_addc_u32 s53, s53, 0
	global_load_dwordx4 v[136:139], v204, s[52:53]
	s_add_u32 s52, s52, 0x4000
	s_addc_u32 s53, s53, 0
	global_load_dwordx4 v[140:143], v204, s[52:53]
	s_waitcnt vmcnt(20)
	s_branch .Lf8t_wout0_b_go
